# adds: LN gain/bias loads hoisted, permlane-swap reductions in LN stats / mem attention / GLA-2, band next-tile loads issued before the step barrier
# speedup vs baseline: 1.0087x; 1.0087x over previous
.LBB0_182:
	s_nop 0
	v_and_b32_e32 v131, 64, v209
	v_xor_b32_e32 v130, 16, v209
	v_add_u32_e32 v131, 64, v131
	s_nop 0
	v_cmp_lt_i32_e32 vcc, v130, v131
	v_xor_b32_e32 v132, 32, v209
	s_nop 0
	v_cndmask_b32_e32 v130, v209, v130, vcc
	v_cmp_lt_i32_e32 vcc, v132, v131
	v_mov_b32_e32 v133, v92
	v_mov_b32_e32 v134, v90
	v_cndmask_b32_e32 v131, v209, v132, vcc
	v_mov_b32_e32 v132, v91
	v_mov_b32_e32 v135, v93
	s_nop 0
	v_pk_add_f32 v[132:133], v[132:133], v[134:135]
	v_mov_b32_e32 v134, v75
	v_mov_b32_e32 v135, v76
	v_mov_b32_e32 v136, v74
	v_mov_b32_e32 v137, v77
	v_pk_add_f32 v[134:135], v[134:135], v[136:137]
	v_add_f32_e32 v132, v132, v133
	v_pk_add_f32 v[134:135], v[134:135], v[134:135] op_sel_hi:[0,1]
	v_add_f32_e32 v133, 0, v132
	v_add_f32_e32 v137, v6, v7
	s_waitcnt vmcnt(0) lgkmcnt(0)
	v_add_f32_e32 v139, v8, v9
	v_mov_b32_e32 v136, v2
	v_mov_b32_e32 v138, v3
	v_mov_b32_e32 v134, v4
	v_mov_b32_e32 v132, v5
	v_pk_add_f32 v[136:137], v[136:137], v[138:139]
	v_pk_add_f32 v[132:133], v[134:135], v[132:133]
	v_lshlrev_b32_e32 v130, 2, v130
	v_pk_add_f32 v[132:133], v[136:137], v[132:133]
	v_lshlrev_b32_e32 v131, 2, v131
	v_add_f32_e32 v132, v132, v133
	v_mov_b32_e32 v133, v132
	s_nop 1
	v_permlane16_swap_b32_e32 v133, v132
	s_nop 0
	s_nop 0
	s_nop 0
	s_nop 0
	s_waitcnt lgkmcnt(0)
	v_add_f32_e32 v132, v132, v133
	v_mov_b32_e32 v133, v132
	s_nop 1
	v_permlane32_swap_b32_e32 v133, v132
	v_and_b32_e32 v0, 63, v160
	s_lshl_b32 s14, s29, 3
	s_waitcnt lgkmcnt(0)
	v_add_f32_e32 v132, v132, v133
	v_fmamk_f32 v134, v132, 0xbc800000, v93
	v_fmamk_f32 v136, v132, 0xbc800000, v91
	v_fmamk_f32 v133, v132, 0xbc800000, v92
	v_fmamk_f32 v135, v132, 0xbc800000, v90
	v_mul_f32_e32 v136, v136, v136
	v_mul_f32_e32 v134, v134, v134
	v_fmac_f32_e32 v136, v135, v135
	v_fmac_f32_e32 v134, v133, v133
	v_fmamk_f32 v135, v132, 0xbc800000, v77
	v_fmamk_f32 v137, v132, 0xbc800000, v75
	v_add_f32_e32 v133, v136, v134
	v_fmamk_f32 v134, v132, 0xbc800000, v76
	v_fmamk_f32 v136, v132, 0xbc800000, v74
	v_mul_f32_e32 v137, v137, v137
	v_mul_f32_e32 v135, v135, v135
	v_fmac_f32_e32 v137, v136, v136
	v_fmac_f32_e32 v135, v134, v134
	v_add_f32_e32 v134, v137, v135
	v_fmamk_f32 v135, v132, 0xbc800000, v9
	v_fmamk_f32 v137, v132, 0xbc800000, v7
	v_add_f32_e32 v133, v133, v134
	v_fmamk_f32 v134, v132, 0xbc800000, v8
	v_fmamk_f32 v136, v132, 0xbc800000, v6
	v_mul_f32_e32 v137, v137, v137
	v_mul_f32_e32 v135, v135, v135
	v_fmac_f32_e32 v137, v136, v136
	v_fmac_f32_e32 v135, v134, v134
	v_add_f32_e32 v134, v137, v135
	v_fmamk_f32 v135, v132, 0xbc800000, v5
	v_fmamk_f32 v137, v132, 0xbc800000, v3
	v_add_f32_e32 v133, v134, v133
	v_fmamk_f32 v134, v132, 0xbc800000, v4
	v_fmamk_f32 v136, v132, 0xbc800000, v2
	v_mul_f32_e32 v137, v137, v137
	v_mul_f32_e32 v135, v135, v135
	v_fmac_f32_e32 v137, v136, v136
	v_fmac_f32_e32 v135, v134, v134
	v_add_f32_e32 v134, v137, v135
	v_add_f32_e32 v133, v134, v133
	v_mov_b32_e32 v134, v133
	s_nop 1
	v_permlane16_swap_b32_e32 v134, v133
	v_cmp_gt_u32_e32 vcc, 16, v0
	s_add_i32 s14, s14, 0
	s_waitcnt lgkmcnt(0)
	v_add_f32_e32 v133, v133, v134
	v_mov_b32_e32 v134, v133
	s_nop 1
	v_permlane32_swap_b32_e32 v134, v133
	s_and_saveexec_b64 s[18:19], vcc
	s_cbranch_execz .LBB0_184
	s_lshl_b32 s15, s54, 11
	s_add_i32 s15, s14, s15
	v_mul_f32_e32 v132, 0x3c800000, v132
	s_waitcnt lgkmcnt(0)
	v_add_f32_e32 v133, v133, v134
	v_lshl_add_u32 v134, v161, 5, s15
	ds_write_b64 v134, v[132:133]
.LBB0_184:
	s_or_b64 exec, exec, s[18:19]
	v_mov_b32_e32 v132, v95
	v_mov_b32_e32 v133, v96
	s_waitcnt lgkmcnt(0)
	v_mov_b32_e32 v134, v94
	v_mov_b32_e32 v135, v97
	v_pk_add_f32 v[132:133], v[132:133], v[134:135]
	v_mov_b32_e32 v134, v79
	v_mov_b32_e32 v135, v80
	v_mov_b32_e32 v136, v78
	v_mov_b32_e32 v137, v81
	v_pk_add_f32 v[134:135], v[134:135], v[136:137]
	v_add_f32_e32 v132, v132, v133
	v_pk_add_f32 v[134:135], v[134:135], v[134:135] op_sel_hi:[0,1]
	v_add_f32_e32 v133, 0, v132
	v_add_f32_e32 v137, v14, v15
	v_add_f32_e32 v139, v16, v17
	v_mov_b32_e32 v136, v10
	v_mov_b32_e32 v138, v11
	v_mov_b32_e32 v134, v12
	v_mov_b32_e32 v132, v13
	v_pk_add_f32 v[136:137], v[136:137], v[138:139]
	v_pk_add_f32 v[132:133], v[134:135], v[132:133]
	s_nop 0
	v_pk_add_f32 v[132:133], v[136:137], v[132:133]
	s_nop 0
	v_add_f32_e32 v132, v132, v133
	v_mov_b32_e32 v133, v132
	s_nop 1
	v_permlane16_swap_b32_e32 v133, v132
	s_waitcnt lgkmcnt(0)
	v_add_f32_e32 v132, v132, v133
	v_mov_b32_e32 v133, v132
	s_nop 1
	v_permlane32_swap_b32_e32 v133, v132
	s_waitcnt lgkmcnt(0)
	v_add_f32_e32 v132, v132, v133
	v_fmamk_f32 v134, v132, 0xbc800000, v97
	v_fmamk_f32 v136, v132, 0xbc800000, v95
	v_fmamk_f32 v133, v132, 0xbc800000, v96
	v_fmamk_f32 v135, v132, 0xbc800000, v94
	v_mul_f32_e32 v136, v136, v136
	v_mul_f32_e32 v134, v134, v134
	v_fmac_f32_e32 v136, v135, v135
	v_fmac_f32_e32 v134, v133, v133
	v_fmamk_f32 v135, v132, 0xbc800000, v81
	v_fmamk_f32 v137, v132, 0xbc800000, v79
	v_add_f32_e32 v133, v136, v134
	v_fmamk_f32 v134, v132, 0xbc800000, v80
	v_fmamk_f32 v136, v132, 0xbc800000, v78
	v_mul_f32_e32 v137, v137, v137
	v_mul_f32_e32 v135, v135, v135
	v_fmac_f32_e32 v137, v136, v136
	v_fmac_f32_e32 v135, v134, v134
	v_add_f32_e32 v134, v137, v135
	v_fmamk_f32 v135, v132, 0xbc800000, v17
	v_fmamk_f32 v137, v132, 0xbc800000, v15
	v_add_f32_e32 v133, v133, v134
	v_fmamk_f32 v134, v132, 0xbc800000, v16
	v_fmamk_f32 v136, v132, 0xbc800000, v14
	v_mul_f32_e32 v137, v137, v137
	v_mul_f32_e32 v135, v135, v135
	v_fmac_f32_e32 v137, v136, v136
	v_fmac_f32_e32 v135, v134, v134
	v_add_f32_e32 v134, v137, v135
	v_fmamk_f32 v135, v132, 0xbc800000, v13
	v_fmamk_f32 v137, v132, 0xbc800000, v11
	v_add_f32_e32 v133, v134, v133
	v_fmamk_f32 v134, v132, 0xbc800000, v12
	v_fmamk_f32 v136, v132, 0xbc800000, v10
	v_mul_f32_e32 v137, v137, v137
	v_mul_f32_e32 v135, v135, v135
	v_fmac_f32_e32 v137, v136, v136
	v_fmac_f32_e32 v135, v134, v134
	v_add_f32_e32 v134, v137, v135
	v_add_f32_e32 v133, v134, v133
	v_mov_b32_e32 v134, v133
	s_nop 1
	v_permlane16_swap_b32_e32 v134, v133
	s_waitcnt lgkmcnt(0)
	v_add_f32_e32 v133, v133, v134
	v_mov_b32_e32 v134, v133
	s_nop 1
	v_permlane32_swap_b32_e32 v134, v133
	s_and_saveexec_b64 s[18:19], vcc
	s_mov_b32 s29, s31
	s_cbranch_execz .LBB0_186
	s_lshl_b32 s15, s54, 11
	s_add_i32 s15, s14, s15
	v_mul_f32_e32 v132, 0x3c800000, v132
	s_waitcnt lgkmcnt(0)
	v_add_f32_e32 v133, v133, v134
	v_lshl_add_u32 v134, v161, 5, s15
	ds_write_b64 v134, v[132:133] offset:512
.LBB0_186:
	s_or_b64 exec, exec, s[18:19]
	v_mov_b32_e32 v132, v103
	v_mov_b32_e32 v133, v104
	s_waitcnt lgkmcnt(0)
	v_mov_b32_e32 v134, v102
	v_mov_b32_e32 v135, v105
	v_pk_add_f32 v[132:133], v[132:133], v[134:135]
	v_mov_b32_e32 v134, v99
	v_mov_b32_e32 v135, v100
	v_mov_b32_e32 v136, v98
	v_mov_b32_e32 v137, v101
	v_pk_add_f32 v[134:135], v[134:135], v[136:137]
	v_add_f32_e32 v132, v132, v133
	v_pk_add_f32 v[134:135], v[134:135], v[134:135] op_sel_hi:[0,1]
	v_add_f32_e32 v133, 0, v132
	v_add_f32_e32 v137, v22, v23
	v_add_f32_e32 v139, v24, v25
	v_mov_b32_e32 v136, v18
	v_mov_b32_e32 v138, v19
	v_mov_b32_e32 v134, v20
	v_mov_b32_e32 v132, v21
	v_pk_add_f32 v[136:137], v[136:137], v[138:139]
	v_pk_add_f32 v[132:133], v[134:135], v[132:133]
	s_nop 0
	v_pk_add_f32 v[132:133], v[136:137], v[132:133]
	s_nop 0
	v_add_f32_e32 v132, v132, v133
	v_mov_b32_e32 v133, v132
	s_nop 1
	v_permlane16_swap_b32_e32 v133, v132
	s_waitcnt lgkmcnt(0)
	v_add_f32_e32 v132, v132, v133
	v_mov_b32_e32 v133, v132
	s_nop 1
	v_permlane32_swap_b32_e32 v133, v132
	s_waitcnt lgkmcnt(0)
	v_add_f32_e32 v132, v132, v133
	v_fmamk_f32 v134, v132, 0xbc800000, v105
	v_fmamk_f32 v136, v132, 0xbc800000, v103
	v_fmamk_f32 v133, v132, 0xbc800000, v104
	v_fmamk_f32 v135, v132, 0xbc800000, v102
	v_mul_f32_e32 v136, v136, v136
	v_mul_f32_e32 v134, v134, v134
	v_fmac_f32_e32 v136, v135, v135
	v_fmac_f32_e32 v134, v133, v133
	v_fmamk_f32 v135, v132, 0xbc800000, v101
	v_fmamk_f32 v137, v132, 0xbc800000, v99
	v_add_f32_e32 v133, v136, v134
	v_fmamk_f32 v134, v132, 0xbc800000, v100
	v_fmamk_f32 v136, v132, 0xbc800000, v98
	v_mul_f32_e32 v137, v137, v137
	v_mul_f32_e32 v135, v135, v135
	v_fmac_f32_e32 v137, v136, v136
	v_fmac_f32_e32 v135, v134, v134
	v_add_f32_e32 v134, v137, v135
	v_fmamk_f32 v135, v132, 0xbc800000, v25
	v_fmamk_f32 v137, v132, 0xbc800000, v23
	v_add_f32_e32 v133, v133, v134
	v_fmamk_f32 v134, v132, 0xbc800000, v24
	v_fmamk_f32 v136, v132, 0xbc800000, v22
	v_mul_f32_e32 v137, v137, v137
	v_mul_f32_e32 v135, v135, v135
	v_fmac_f32_e32 v137, v136, v136
	v_fmac_f32_e32 v135, v134, v134
	v_add_f32_e32 v134, v137, v135
	v_fmamk_f32 v135, v132, 0xbc800000, v21
	v_fmamk_f32 v137, v132, 0xbc800000, v19
	v_add_f32_e32 v133, v134, v133
	v_fmamk_f32 v134, v132, 0xbc800000, v20
	v_fmamk_f32 v136, v132, 0xbc800000, v18
	v_mul_f32_e32 v137, v137, v137
	v_mul_f32_e32 v135, v135, v135
	v_fmac_f32_e32 v137, v136, v136
	v_fmac_f32_e32 v135, v134, v134
	v_add_f32_e32 v134, v137, v135
	v_add_f32_e32 v133, v134, v133
	v_mov_b32_e32 v134, v133
	s_nop 1
	v_permlane16_swap_b32_e32 v134, v133
	s_waitcnt lgkmcnt(0)
	v_add_f32_e32 v133, v133, v134
	v_mov_b32_e32 v134, v133
	s_nop 1
	v_permlane32_swap_b32_e32 v134, v133
	s_and_saveexec_b64 s[18:19], vcc
	s_cbranch_execz .LBB0_188
	s_lshl_b32 s15, s54, 11
	s_add_i32 s15, s14, s15
	v_mul_f32_e32 v132, 0x3c800000, v132
	s_waitcnt lgkmcnt(0)
	v_add_f32_e32 v133, v133, v134
	v_lshl_add_u32 v134, v161, 5, s15
	ds_write_b64 v134, v[132:133] offset:1024
.LBB0_188:
	s_or_b64 exec, exec, s[18:19]
	v_mov_b32_e32 v132, v119
	v_mov_b32_e32 v133, v120
	s_waitcnt lgkmcnt(0)
	v_mov_b32_e32 v134, v118
	v_mov_b32_e32 v135, v121
	v_pk_add_f32 v[132:133], v[132:133], v[134:135]
	v_mov_b32_e32 v134, v107
	v_mov_b32_e32 v135, v108
	v_mov_b32_e32 v136, v106
	v_mov_b32_e32 v137, v109
	v_pk_add_f32 v[134:135], v[134:135], v[136:137]
	v_add_f32_e32 v132, v132, v133
	v_pk_add_f32 v[134:135], v[134:135], v[134:135] op_sel_hi:[0,1]
	v_add_f32_e32 v133, 0, v132
	v_add_f32_e32 v137, v30, v31
	v_add_f32_e32 v139, v32, v33
	v_mov_b32_e32 v136, v26
	v_mov_b32_e32 v138, v27
	v_mov_b32_e32 v134, v28
	v_mov_b32_e32 v132, v29
	v_pk_add_f32 v[136:137], v[136:137], v[138:139]
	v_pk_add_f32 v[132:133], v[134:135], v[132:133]
	s_nop 0
	v_pk_add_f32 v[132:133], v[136:137], v[132:133]
	s_nop 0
	v_add_f32_e32 v132, v132, v133
	v_mov_b32_e32 v133, v132
	s_nop 1
	v_permlane16_swap_b32_e32 v133, v132
	s_waitcnt lgkmcnt(0)
	v_add_f32_e32 v132, v132, v133
	v_mov_b32_e32 v133, v132
	s_nop 1
	v_permlane32_swap_b32_e32 v133, v132
	s_waitcnt lgkmcnt(0)
	v_add_f32_e32 v132, v132, v133
	v_fmamk_f32 v134, v132, 0xbc800000, v121
	v_fmamk_f32 v136, v132, 0xbc800000, v119
	v_fmamk_f32 v133, v132, 0xbc800000, v120
	v_fmamk_f32 v135, v132, 0xbc800000, v118
	v_mul_f32_e32 v136, v136, v136
	v_mul_f32_e32 v134, v134, v134
	v_fmac_f32_e32 v136, v135, v135
	v_fmac_f32_e32 v134, v133, v133
	v_fmamk_f32 v135, v132, 0xbc800000, v109
	v_fmamk_f32 v137, v132, 0xbc800000, v107
	v_add_f32_e32 v133, v136, v134
	v_fmamk_f32 v134, v132, 0xbc800000, v108
	v_fmamk_f32 v136, v132, 0xbc800000, v106
	v_mul_f32_e32 v137, v137, v137
	v_mul_f32_e32 v135, v135, v135
	v_fmac_f32_e32 v137, v136, v136
	v_fmac_f32_e32 v135, v134, v134
	v_add_f32_e32 v134, v137, v135
	v_fmamk_f32 v135, v132, 0xbc800000, v33
	v_fmamk_f32 v137, v132, 0xbc800000, v31
	v_add_f32_e32 v133, v133, v134
	v_fmamk_f32 v134, v132, 0xbc800000, v32
	v_fmamk_f32 v136, v132, 0xbc800000, v30
	v_mul_f32_e32 v137, v137, v137
	v_mul_f32_e32 v135, v135, v135
	v_fmac_f32_e32 v137, v136, v136
	v_fmac_f32_e32 v135, v134, v134
	v_add_f32_e32 v134, v137, v135
	v_fmamk_f32 v135, v132, 0xbc800000, v29
	v_fmamk_f32 v137, v132, 0xbc800000, v27
	v_add_f32_e32 v133, v134, v133
	v_fmamk_f32 v134, v132, 0xbc800000, v28
	v_fmamk_f32 v136, v132, 0xbc800000, v26
	v_mul_f32_e32 v137, v137, v137
	v_mul_f32_e32 v135, v135, v135
	v_fmac_f32_e32 v137, v136, v136
	v_fmac_f32_e32 v135, v134, v134
	v_add_f32_e32 v134, v137, v135
	v_add_f32_e32 v133, v134, v133
	v_mov_b32_e32 v134, v133
	s_nop 1
	v_permlane16_swap_b32_e32 v134, v133
	s_waitcnt lgkmcnt(0)
	v_add_f32_e32 v133, v133, v134
	v_mov_b32_e32 v134, v133
	s_nop 1
	v_permlane32_swap_b32_e32 v134, v133
	s_and_saveexec_b64 s[18:19], vcc
	s_cbranch_execz .LBB0_190
	s_lshl_b32 s15, s54, 11
	s_add_i32 s15, s14, s15
	v_mul_f32_e32 v132, 0x3c800000, v132
	s_waitcnt lgkmcnt(0)
	v_add_f32_e32 v133, v133, v134
	v_lshl_add_u32 v134, v161, 5, s15
	ds_write_b64 v134, v[132:133] offset:1536
.LBB0_190:
	s_or_b64 exec, exec, s[18:19]
	v_mov_b32_e32 v132, v127
	v_mov_b32_e32 v133, v128
	s_waitcnt lgkmcnt(0)
	v_mov_b32_e32 v134, v126
	v_mov_b32_e32 v135, v129
	v_pk_add_f32 v[132:133], v[132:133], v[134:135]
	v_mov_b32_e32 v134, v123
	v_mov_b32_e32 v135, v124
	v_mov_b32_e32 v136, v122
	v_mov_b32_e32 v137, v125
	v_pk_add_f32 v[134:135], v[134:135], v[136:137]
	v_add_f32_e32 v132, v132, v133
	v_pk_add_f32 v[134:135], v[134:135], v[134:135] op_sel_hi:[0,1]
	v_add_f32_e32 v133, 0, v132
	v_add_f32_e32 v137, v38, v39
	v_add_f32_e32 v139, v40, v41
	v_mov_b32_e32 v136, v34
	v_mov_b32_e32 v138, v35
	v_mov_b32_e32 v134, v36
	v_mov_b32_e32 v132, v37
	v_pk_add_f32 v[136:137], v[136:137], v[138:139]
	v_pk_add_f32 v[132:133], v[134:135], v[132:133]
	s_nop 0
	v_pk_add_f32 v[132:133], v[136:137], v[132:133]
	s_nop 0
	v_add_f32_e32 v132, v132, v133
	v_mov_b32_e32 v133, v132
	s_nop 1
	v_permlane16_swap_b32_e32 v133, v132
	s_waitcnt lgkmcnt(0)
	v_add_f32_e32 v132, v132, v133
	v_mov_b32_e32 v133, v132
	s_nop 1
	v_permlane32_swap_b32_e32 v133, v132
	s_waitcnt lgkmcnt(0)
	v_add_f32_e32 v132, v132, v133
	v_fmamk_f32 v134, v132, 0xbc800000, v129
	v_fmamk_f32 v136, v132, 0xbc800000, v127
	v_fmamk_f32 v133, v132, 0xbc800000, v128
	v_fmamk_f32 v135, v132, 0xbc800000, v126
	v_mul_f32_e32 v136, v136, v136
	v_mul_f32_e32 v134, v134, v134
	v_fmac_f32_e32 v136, v135, v135
	v_fmac_f32_e32 v134, v133, v133
	v_fmamk_f32 v135, v132, 0xbc800000, v125
	v_fmamk_f32 v137, v132, 0xbc800000, v123
	v_add_f32_e32 v133, v136, v134
	v_fmamk_f32 v134, v132, 0xbc800000, v124
	v_fmamk_f32 v136, v132, 0xbc800000, v122
	v_mul_f32_e32 v137, v137, v137
	v_mul_f32_e32 v135, v135, v135
	v_fmac_f32_e32 v137, v136, v136
	v_fmac_f32_e32 v135, v134, v134
	v_add_f32_e32 v134, v137, v135
	v_fmamk_f32 v135, v132, 0xbc800000, v41
	v_fmamk_f32 v137, v132, 0xbc800000, v39
	v_add_f32_e32 v133, v133, v134
	v_fmamk_f32 v134, v132, 0xbc800000, v40
	v_fmamk_f32 v136, v132, 0xbc800000, v38
	v_mul_f32_e32 v137, v137, v137
	v_mul_f32_e32 v135, v135, v135
	v_fmac_f32_e32 v137, v136, v136
	v_fmac_f32_e32 v135, v134, v134
	v_add_f32_e32 v134, v137, v135
	v_fmamk_f32 v135, v132, 0xbc800000, v37
	v_fmamk_f32 v137, v132, 0xbc800000, v35
	v_add_f32_e32 v133, v134, v133
	v_fmamk_f32 v134, v132, 0xbc800000, v36
	v_fmamk_f32 v136, v132, 0xbc800000, v34
	v_mul_f32_e32 v137, v137, v137
	v_mul_f32_e32 v135, v135, v135
	v_fmac_f32_e32 v137, v136, v136
	v_fmac_f32_e32 v135, v134, v134
	v_add_f32_e32 v134, v137, v135
	v_add_f32_e32 v133, v134, v133
	v_mov_b32_e32 v134, v133
	s_nop 1
	v_permlane16_swap_b32_e32 v134, v133
	s_waitcnt lgkmcnt(0)
	v_add_f32_e32 v133, v133, v134
	v_mov_b32_e32 v134, v133
	s_nop 1
	v_permlane32_swap_b32_e32 v134, v133
	s_and_saveexec_b64 s[18:19], vcc
	s_cbranch_execz .LBB0_192
	s_lshl_b32 s15, s54, 11
	s_add_i32 s15, s14, s15
	v_mul_f32_e32 v132, 0x3c800000, v132
	s_waitcnt lgkmcnt(0)
	v_add_f32_e32 v133, v133, v134
	v_lshl_add_u32 v134, v161, 5, s15
	ds_write_b64 v134, v[132:133] offset:4096
.LBB0_192:
	s_or_b64 exec, exec, s[18:19]
	v_mov_b32_e32 v132, v115
	v_mov_b32_e32 v133, v116
	s_waitcnt lgkmcnt(0)
	v_mov_b32_e32 v134, v114
	v_mov_b32_e32 v135, v117
	v_pk_add_f32 v[132:133], v[132:133], v[134:135]
	v_mov_b32_e32 v134, v111
	v_mov_b32_e32 v135, v112
	v_mov_b32_e32 v136, v110
	v_mov_b32_e32 v137, v113
	v_pk_add_f32 v[134:135], v[134:135], v[136:137]
	v_add_f32_e32 v132, v132, v133
	v_pk_add_f32 v[134:135], v[134:135], v[134:135] op_sel_hi:[0,1]
	v_add_f32_e32 v133, 0, v132
	v_add_f32_e32 v137, v46, v47
	v_add_f32_e32 v139, v48, v49
	v_mov_b32_e32 v136, v42
	v_mov_b32_e32 v138, v43
	v_mov_b32_e32 v134, v44
	v_mov_b32_e32 v132, v45
	v_pk_add_f32 v[136:137], v[136:137], v[138:139]
	v_pk_add_f32 v[132:133], v[134:135], v[132:133]
	s_nop 0
	v_pk_add_f32 v[132:133], v[136:137], v[132:133]
	s_nop 0
	v_add_f32_e32 v132, v132, v133
	v_mov_b32_e32 v133, v132
	s_nop 1
	v_permlane16_swap_b32_e32 v133, v132
	s_waitcnt lgkmcnt(0)
	v_add_f32_e32 v132, v132, v133
	v_mov_b32_e32 v133, v132
	s_nop 1
	v_permlane32_swap_b32_e32 v133, v132
	s_waitcnt lgkmcnt(0)
	v_add_f32_e32 v132, v132, v133
	v_fmamk_f32 v134, v132, 0xbc800000, v117
	v_fmamk_f32 v136, v132, 0xbc800000, v115
	v_fmamk_f32 v133, v132, 0xbc800000, v116
	v_fmamk_f32 v135, v132, 0xbc800000, v114
	v_mul_f32_e32 v136, v136, v136
	v_mul_f32_e32 v134, v134, v134
	v_fmac_f32_e32 v136, v135, v135
	v_fmac_f32_e32 v134, v133, v133
	v_fmamk_f32 v135, v132, 0xbc800000, v113
	v_fmamk_f32 v137, v132, 0xbc800000, v111
	v_add_f32_e32 v133, v136, v134
	v_fmamk_f32 v134, v132, 0xbc800000, v112
	v_fmamk_f32 v136, v132, 0xbc800000, v110
	v_mul_f32_e32 v137, v137, v137
	v_mul_f32_e32 v135, v135, v135
	v_fmac_f32_e32 v137, v136, v136
	v_fmac_f32_e32 v135, v134, v134
	v_add_f32_e32 v134, v137, v135
	v_fmamk_f32 v135, v132, 0xbc800000, v49
	v_fmamk_f32 v137, v132, 0xbc800000, v47
	v_add_f32_e32 v133, v133, v134
	v_fmamk_f32 v134, v132, 0xbc800000, v48
	v_fmamk_f32 v136, v132, 0xbc800000, v46
	v_mul_f32_e32 v137, v137, v137
	v_mul_f32_e32 v135, v135, v135
	v_fmac_f32_e32 v137, v136, v136
	v_fmac_f32_e32 v135, v134, v134
	v_add_f32_e32 v134, v137, v135
	v_fmamk_f32 v135, v132, 0xbc800000, v45
	v_fmamk_f32 v137, v132, 0xbc800000, v43
	v_add_f32_e32 v133, v134, v133
	v_fmamk_f32 v134, v132, 0xbc800000, v44
	v_fmamk_f32 v136, v132, 0xbc800000, v42
	v_mul_f32_e32 v137, v137, v137
	v_mul_f32_e32 v135, v135, v135
	v_fmac_f32_e32 v137, v136, v136
	v_fmac_f32_e32 v135, v134, v134
	v_add_f32_e32 v134, v137, v135
	v_add_f32_e32 v133, v134, v133
	v_mov_b32_e32 v134, v133
	s_nop 1
	v_permlane16_swap_b32_e32 v134, v133
	s_waitcnt lgkmcnt(0)
	v_add_f32_e32 v133, v133, v134
	v_mov_b32_e32 v134, v133
	s_nop 1
	v_permlane32_swap_b32_e32 v134, v133
	s_and_saveexec_b64 s[18:19], vcc
	s_cbranch_execz .LBB0_194
	s_lshl_b32 s15, s54, 11
	s_add_i32 s15, s14, s15
	v_mul_f32_e32 v132, 0x3c800000, v132
	s_waitcnt lgkmcnt(0)
	v_add_f32_e32 v133, v133, v134
	v_lshl_add_u32 v134, v161, 5, s15
	ds_write_b64 v134, v[132:133] offset:4608
.LBB0_194:
	s_or_b64 exec, exec, s[18:19]
	v_mov_b32_e32 v132, v87
	v_mov_b32_e32 v133, v88
	s_waitcnt lgkmcnt(0)
	v_mov_b32_e32 v134, v86
	v_mov_b32_e32 v135, v89
	v_pk_add_f32 v[132:133], v[132:133], v[134:135]
	v_mov_b32_e32 v134, v83
	v_mov_b32_e32 v135, v84
	v_mov_b32_e32 v136, v82
	v_mov_b32_e32 v137, v85
	v_pk_add_f32 v[134:135], v[134:135], v[136:137]
	v_add_f32_e32 v132, v132, v133
	v_pk_add_f32 v[134:135], v[134:135], v[134:135] op_sel_hi:[0,1]
	v_add_f32_e32 v133, 0, v132
	v_add_f32_e32 v137, v62, v63
	v_add_f32_e32 v139, v64, v65
	v_mov_b32_e32 v136, v54
	v_mov_b32_e32 v138, v55
	v_mov_b32_e32 v134, v56
	v_mov_b32_e32 v132, v57
	v_pk_add_f32 v[136:137], v[136:137], v[138:139]
	v_pk_add_f32 v[132:133], v[134:135], v[132:133]
	s_nop 0
	v_pk_add_f32 v[132:133], v[136:137], v[132:133]
	s_nop 0
	v_add_f32_e32 v132, v132, v133
	v_mov_b32_e32 v133, v132
	s_nop 1
	v_permlane16_swap_b32_e32 v133, v132
	s_waitcnt lgkmcnt(0)
	v_add_f32_e32 v132, v132, v133
	v_mov_b32_e32 v133, v132
	s_nop 1
	v_permlane32_swap_b32_e32 v133, v132
	s_waitcnt lgkmcnt(0)
	v_add_f32_e32 v132, v132, v133
	v_fmamk_f32 v134, v132, 0xbc800000, v89
	v_fmamk_f32 v136, v132, 0xbc800000, v87
	v_fmamk_f32 v133, v132, 0xbc800000, v88
	v_fmamk_f32 v135, v132, 0xbc800000, v86
	v_mul_f32_e32 v136, v136, v136
	v_mul_f32_e32 v134, v134, v134
	v_fmac_f32_e32 v136, v135, v135
	v_fmac_f32_e32 v134, v133, v133
	v_fmamk_f32 v135, v132, 0xbc800000, v85
	v_fmamk_f32 v137, v132, 0xbc800000, v83
	v_add_f32_e32 v133, v136, v134
	v_fmamk_f32 v134, v132, 0xbc800000, v84
	v_fmamk_f32 v136, v132, 0xbc800000, v82
	v_mul_f32_e32 v137, v137, v137
	v_mul_f32_e32 v135, v135, v135
	v_fmac_f32_e32 v137, v136, v136
	v_fmac_f32_e32 v135, v134, v134
	v_add_f32_e32 v134, v137, v135
	v_fmamk_f32 v135, v132, 0xbc800000, v65
	v_fmamk_f32 v137, v132, 0xbc800000, v63
	v_add_f32_e32 v133, v133, v134
	v_fmamk_f32 v134, v132, 0xbc800000, v64
	v_fmamk_f32 v136, v132, 0xbc800000, v62
	v_mul_f32_e32 v137, v137, v137
	v_mul_f32_e32 v135, v135, v135
	v_fmac_f32_e32 v137, v136, v136
	v_fmac_f32_e32 v135, v134, v134
	v_add_f32_e32 v134, v137, v135
	v_fmamk_f32 v135, v132, 0xbc800000, v57
	v_fmamk_f32 v137, v132, 0xbc800000, v55
	v_add_f32_e32 v133, v134, v133
	v_fmamk_f32 v134, v132, 0xbc800000, v56
	v_fmamk_f32 v136, v132, 0xbc800000, v54
	v_mul_f32_e32 v137, v137, v137
	v_mul_f32_e32 v135, v135, v135
	v_fmac_f32_e32 v137, v136, v136
	v_fmac_f32_e32 v135, v134, v134
	v_add_f32_e32 v134, v137, v135
	v_add_f32_e32 v133, v134, v133
	v_mov_b32_e32 v134, v133
	s_nop 1
	v_permlane16_swap_b32_e32 v134, v133
	s_waitcnt lgkmcnt(0)
	v_add_f32_e32 v133, v133, v134
	v_mov_b32_e32 v134, v133
	s_nop 1
	v_permlane32_swap_b32_e32 v134, v133
	s_and_saveexec_b64 s[18:19], vcc
	s_cbranch_execz .LBB0_196
	s_lshl_b32 s15, s54, 11
	s_add_i32 s15, s14, s15
	v_mul_f32_e32 v132, 0x3c800000, v132
	s_waitcnt lgkmcnt(0)
	v_add_f32_e32 v133, v133, v134
	v_lshl_add_u32 v134, v161, 5, s15
	ds_write_b64 v134, v[132:133] offset:5120
.LBB0_196:
	s_or_b64 exec, exec, s[18:19]
	v_mov_b32_e32 v132, v71
	v_mov_b32_e32 v133, v72
	s_waitcnt lgkmcnt(0)
	v_mov_b32_e32 v134, v70
	v_mov_b32_e32 v135, v73
	v_pk_add_f32 v[132:133], v[132:133], v[134:135]
	v_mov_b32_e32 v134, v67
	v_mov_b32_e32 v135, v68
	v_mov_b32_e32 v136, v66
	v_mov_b32_e32 v137, v69
	v_pk_add_f32 v[134:135], v[134:135], v[136:137]
	v_add_f32_e32 v132, v132, v133
	v_pk_add_f32 v[134:135], v[134:135], v[134:135] op_sel_hi:[0,1]
	v_add_f32_e32 v133, 0, v132
	v_add_f32_e32 v137, v58, v59
	v_add_f32_e32 v139, v60, v61
	v_mov_b32_e32 v136, v50
	v_mov_b32_e32 v138, v51
	v_mov_b32_e32 v134, v52
	v_mov_b32_e32 v132, v53
	v_pk_add_f32 v[136:137], v[136:137], v[138:139]
	v_pk_add_f32 v[132:133], v[134:135], v[132:133]
	s_nop 0
	v_pk_add_f32 v[132:133], v[136:137], v[132:133]
	s_nop 0
	v_add_f32_e32 v132, v132, v133
	v_mov_b32_e32 v133, v132
	s_nop 1
	v_permlane16_swap_b32_e32 v133, v132
	s_waitcnt lgkmcnt(0)
	v_add_f32_e32 v132, v132, v133
	v_mov_b32_e32 v133, v132
	s_nop 1
	v_permlane32_swap_b32_e32 v133, v132
	s_waitcnt lgkmcnt(0)
	v_add_f32_e32 v132, v132, v133
	v_fmamk_f32 v134, v132, 0xbc800000, v73
	v_fmamk_f32 v136, v132, 0xbc800000, v71
	v_fmamk_f32 v133, v132, 0xbc800000, v72
	v_fmamk_f32 v135, v132, 0xbc800000, v70
	v_mul_f32_e32 v136, v136, v136
	v_mul_f32_e32 v134, v134, v134
	v_fmac_f32_e32 v136, v135, v135
	v_fmac_f32_e32 v134, v133, v133
	v_fmamk_f32 v135, v132, 0xbc800000, v69
	v_fmamk_f32 v137, v132, 0xbc800000, v67
	v_add_f32_e32 v133, v136, v134
	v_fmamk_f32 v134, v132, 0xbc800000, v68
	v_fmamk_f32 v136, v132, 0xbc800000, v66
	v_mul_f32_e32 v137, v137, v137
	v_mul_f32_e32 v135, v135, v135
	v_fmac_f32_e32 v137, v136, v136
	v_fmac_f32_e32 v135, v134, v134
	v_add_f32_e32 v134, v137, v135
	v_fmamk_f32 v135, v132, 0xbc800000, v61
	v_fmamk_f32 v137, v132, 0xbc800000, v59
	v_add_f32_e32 v133, v133, v134
	v_fmamk_f32 v134, v132, 0xbc800000, v60
	v_fmamk_f32 v136, v132, 0xbc800000, v58
	v_mul_f32_e32 v137, v137, v137
	v_mul_f32_e32 v135, v135, v135
	v_fmac_f32_e32 v137, v136, v136
	v_fmac_f32_e32 v135, v134, v134
	v_add_f32_e32 v134, v137, v135
	v_fmamk_f32 v135, v132, 0xbc800000, v53
	v_fmamk_f32 v137, v132, 0xbc800000, v51
	v_add_f32_e32 v133, v134, v133
	v_fmamk_f32 v134, v132, 0xbc800000, v52
	v_fmamk_f32 v136, v132, 0xbc800000, v50
	v_mul_f32_e32 v137, v137, v137
	v_mul_f32_e32 v135, v135, v135
	v_fmac_f32_e32 v137, v136, v136
	v_fmac_f32_e32 v135, v134, v134
	v_add_f32_e32 v134, v137, v135
	v_add_f32_e32 v133, v134, v133
	v_mov_b32_e32 v130, v133
	s_nop 1
	v_permlane16_swap_b32_e32 v130, v133
	s_waitcnt lgkmcnt(0)
	v_add_f32_e32 v130, v133, v130
	v_mov_b32_e32 v131, v130
	s_nop 1
	v_permlane32_swap_b32_e32 v131, v130
	s_and_saveexec_b64 s[18:19], vcc
	s_cbranch_execz .LBB0_198
	s_lshl_b32 s15, s54, 11
	s_add_i32 s14, s14, s15
	v_mul_f32_e32 v132, 0x3c800000, v132
	s_waitcnt lgkmcnt(0)
	v_add_f32_e32 v133, v130, v131
	v_lshl_add_u32 v130, v161, 5, s14
	ds_write_b64 v130, v[132:133] offset:5632

.LBB0_211:
	s_waitcnt vmcnt(0) lgkmcnt(0)
	s_barrier
	v_readlane_b32 s50, v238, 10
	v_readlane_b32 s51, v238, 11
	v_readlane_b32 s52, v238, 12
	v_readlane_b32 s53, v238, 13
	v_lshlrev_b32_e32 v239, 2, v152
	s_add_u32 s14, s50, s18
	s_addc_u32 s15, s51, s19
	s_add_u32 s6, s52, s18
	s_addc_u32 s7, s53, s19
	global_load_dwordx4 v[240:243], v239, s[14:15]
	global_load_dwordx4 v[244:247], v239, s[6:7]
	global_load_dwordx4 v[248:251], v239, s[14:15] offset:64
	global_load_dwordx4 v[252:255], v239, s[6:7] offset:64
	s_and_saveexec_b64 s[40:41], s[38:39]
	s_cbranch_execz .LBB0_213
	v_lshlrev_b64 v[130:131], 6, v[130:131]
	v_lshl_add_u64 v[130:131], s[36:37], 0, v[130:131]
	flat_load_dwordx2 v[134:135], v[130:131] sc1
	flat_load_dwordx2 v[136:137], v[130:131] offset:8 sc1
	flat_load_dwordx2 v[138:139], v[130:131] offset:16 sc1
	flat_load_dwordx2 v[140:141], v[130:131] offset:24 sc1
	flat_load_dwordx2 v[142:143], v[130:131] offset:32 sc1
	flat_load_dwordx2 v[144:145], v[130:131] offset:40 sc1
	flat_load_dwordx2 v[146:147], v[130:131] offset:48 sc1
	flat_load_dwordx2 v[148:149], v[130:131] offset:56 sc1
	s_mov_b32 s0, 0xf800000
	s_waitcnt vmcnt(0) lgkmcnt(0)
	v_add_f32_e32 v0, 0, v134
	v_add_f32_e32 v0, v0, v136
	v_add_f32_e32 v0, v0, v138
	v_add_f32_e32 v0, v0, v140
	v_add_f32_e32 v0, v0, v142
	v_add_f32_e32 v0, v0, v144
	v_add_f32_e32 v0, v0, v146
	v_add_f32_e32 v0, v0, v148
	v_fmamk_f32 v131, v0, 0xbe000000, v134
	v_mul_f32_e32 v133, 0x43800000, v131
	v_fmac_f32_e32 v135, v131, v133
	v_fmamk_f32 v133, v0, 0xbe000000, v136
	v_mul_f32_e32 v134, 0x43800000, v133
	v_fmac_f32_e32 v137, v133, v134
	v_fmamk_f32 v133, v0, 0xbe000000, v138
	v_mul_f32_e32 v134, 0x43800000, v133
	v_fmac_f32_e32 v139, v133, v134
	v_fmamk_f32 v133, v0, 0xbe000000, v140
	v_mul_f32_e32 v134, 0x43800000, v133
	v_fmac_f32_e32 v141, v133, v134
	v_fmamk_f32 v133, v0, 0xbe000000, v142
	v_add_f32_e32 v131, 0, v135
	v_mul_f32_e32 v134, 0x43800000, v133
	v_add_f32_e32 v131, v137, v131
	v_fmac_f32_e32 v143, v133, v134
	v_fmamk_f32 v133, v0, 0xbe000000, v144
	v_add_f32_e32 v131, v139, v131
	v_mul_f32_e32 v134, 0x43800000, v133
	v_add_f32_e32 v131, v141, v131
	v_fmac_f32_e32 v145, v133, v134
	v_fmamk_f32 v133, v0, 0xbe000000, v146
	v_mul_f32_e32 v130, 0x3e000000, v0
	v_add_f32_e32 v131, v143, v131
	v_mul_f32_e32 v134, 0x43800000, v133
	v_fmamk_f32 v0, v0, 0xbe000000, v148
	v_add_f32_e32 v131, v145, v131
	v_fmac_f32_e32 v147, v133, v134
	v_mul_f32_e32 v133, 0x43800000, v0
	v_add_f32_e32 v131, v147, v131
	v_fmac_f32_e32 v149, v0, v133
	v_add_f32_e32 v0, v149, v131
	v_fmamk_f32 v0, v0, 0x3a000000, v206
	v_cmp_gt_f32_e32 vcc, s0, v0
	v_mul_f32_e32 v131, 0x4f800000, v0
	s_nop 0
	v_cndmask_b32_e32 v0, v0, v131, vcc
	v_sqrt_f32_e32 v131, v0
	s_nop 0
	v_add_u32_e32 v133, -1, v131
	v_fma_f32 v134, -v133, v131, v0
	v_cmp_ge_f32_e64 s[0:1], 0, v134
	v_add_u32_e32 v134, 1, v131
	s_nop 0
	v_cndmask_b32_e64 v133, v131, v133, s[0:1]
	v_fma_f32 v131, -v134, v131, v0
	v_cmp_lt_f32_e64 s[0:1], 0, v131
	s_nop 1
	v_cndmask_b32_e64 v131, v133, v134, s[0:1]
	v_mul_f32_e32 v133, 0x37800000, v131
	v_cndmask_b32_e32 v131, v131, v133, vcc
	v_cmp_class_f32_e32 vcc, v0, v207
	s_nop 1
	v_cndmask_b32_e32 v0, v131, v0, vcc
	v_div_scale_f32 v131, s[0:1], v0, v0, 1.0
	v_rcp_f32_e32 v133, v131
	s_nop 0
	v_fma_f32 v134, -v131, v133, 1.0
	v_fmac_f32_e32 v133, v134, v133
	v_div_scale_f32 v134, vcc, 1.0, v0, 1.0
	v_mul_f32_e32 v135, v134, v133
	v_fma_f32 v136, -v131, v135, v134
	v_fmac_f32_e32 v135, v136, v133
	v_fma_f32 v131, -v131, v135, v134
	v_div_fmas_f32 v131, v131, v133, v135
	v_div_fixup_f32 v131, v131, v0, 1.0
	v_lshl_add_u32 v0, v132, 3, 0
	ds_write_b64 v0, v[130:131] offset:8192
.LBB0_213:
	s_or_b64 exec, exec, s[40:41]
	s_sub_i32 s0, s94, 25
	v_readlane_b32 s48, v238, 8
	s_cmp_lt_u32 s0, -6
	v_readlane_b32 s50, v238, 10
	s_cselect_b64 s[0:1], -1, 0
	v_readlane_b32 s51, v238, 11
	s_add_u32 s14, s50, s18
	v_readlane_b32 s52, v238, 12
	s_addc_u32 s15, s51, s19
	v_readlane_b32 s53, v238, 13
	s_add_u32 s18, s52, s18
	v_lshlrev_b64 v[130:131], 2, v[152:153]
	s_addc_u32 s19, s53, s19
	s_waitcnt lgkmcnt(0)
	s_barrier
	v_lshl_add_u64 v[156:157], s[14:15], 0, v[130:131]
	v_lshl_add_u64 v[158:159], s[18:19], 0, v[130:131]
	s_waitcnt vmcnt(0)
	v_mov_b32_e32 v138, v240
	v_mov_b32_e32 v139, v241
	v_mov_b32_e32 v140, v242
	v_mov_b32_e32 v141, v243
	v_mov_b32_e32 v142, v244
	v_mov_b32_e32 v143, v245
	v_mov_b32_e32 v144, v246
	v_mov_b32_e32 v145, v247
	v_mov_b32_e32 v130, v248
	v_mov_b32_e32 v131, v249
	v_mov_b32_e32 v132, v250
	v_mov_b32_e32 v133, v251
	v_mov_b32_e32 v134, v252
	v_mov_b32_e32 v135, v253
	v_mov_b32_e32 v136, v254
	v_mov_b32_e32 v137, v255
	global_load_dwordx4 v[240:243], v239, s[18:19] offset:512
	global_load_dwordx4 v[244:247], v239, s[14:15] offset:512
	global_load_dwordx4 v[248:251], v239, s[14:15] offset:576
	global_load_dwordx4 v[252:255], v239, s[18:19] offset:576
	v_lshl_add_u32 v0, v168, 3, 0
	ds_read_b64 v[166:167], v0 offset:8192
	v_add_u32_e32 v162, s44, v168
	v_ashrrev_i32_e32 v163, 31, v162
	v_readlane_b32 s14, v238, 16
	v_lshlrev_b64 v[154:155], 11, v[162:163]
	s_waitcnt lgkmcnt(0)
	v_sub_f32_e32 v93, v93, v166
	v_sub_f32_e32 v92, v92, v166
	v_sub_f32_e32 v91, v91, v166
	v_sub_f32_e32 v90, v90, v166
	v_readlane_b32 s15, v238, 17
	v_readlane_b32 s54, v238, 14
	v_readlane_b32 s55, v238, 15
	v_lshl_add_u64 v[164:165], v[154:155], 0, v[152:153]
	v_pk_mul_f32 v[90:91], v[166:167], v[90:91] op_sel:[1,0]
	v_pk_mul_f32 v[92:93], v[166:167], v[92:93] op_sel:[1,0]
	s_or_b64 s[0:1], s[0:1], s[14:15]
	s_mov_b64 s[18:19], -1
	s_and_b64 vcc, exec, s[0:1]
	v_lshl_add_u64 v[160:161], v[164:165], 2, s[54:55]
	v_readlane_b32 s49, v238, 9
	s_nop 0
	v_pk_fma_f32 v[148:149], v[140:141], v[92:93], v[144:145]
	v_pk_fma_f32 v[146:147], v[138:139], v[90:91], v[142:143]
	s_cbranch_vccnz .LBB0_215
	s_mov_b64 s[18:19], 0
	global_store_dwordx4 v[160:161], v[146:149], off

.LBB0_277:
	s_waitcnt vmcnt(16)
	v_mov_b32_e32 v74, v240
	v_mov_b32_e32 v75, v241
	v_mov_b32_e32 v76, v242
	v_mov_b32_e32 v77, v243
	v_mov_b32_e32 v78, v244
	v_mov_b32_e32 v79, v245
	v_mov_b32_e32 v80, v246
	v_mov_b32_e32 v81, v247
	v_mov_b32_e32 v66, v248
	v_mov_b32_e32 v67, v249
	v_mov_b32_e32 v68, v250
	v_mov_b32_e32 v69, v251
	v_mov_b32_e32 v70, v252
	v_mov_b32_e32 v71, v253
	v_mov_b32_e32 v72, v254
	v_mov_b32_e32 v73, v255
	ds_read_b64 v[88:89], v0 offset:8192
	s_and_b64 vcc, exec, s[38:39]
	s_mov_b64 s[0:1], -1
	s_waitcnt lgkmcnt(0)
	v_sub_f32_e32 v9, v9, v88
	v_sub_f32_e32 v8, v8, v88
	v_sub_f32_e32 v7, v7, v88
	v_sub_f32_e32 v6, v6, v88
	v_pk_mul_f32 v[6:7], v[88:89], v[6:7] op_sel:[1,0]
	v_pk_mul_f32 v[8:9], v[88:89], v[8:9] op_sel:[1,0]
	s_nop 0
	v_pk_fma_f32 v[6:7], v[78:79], v[6:7], v[74:75]
	v_pk_fma_f32 v[8:9], v[80:81], v[8:9], v[76:77]
	s_cbranch_vccnz .LBB0_279
	s_mov_b64 s[0:1], 0
	global_store_dwordx4 v[160:161], v[6:9], off offset:512

.LBB0_348:
	s_and_b32 s18, s14, 0xffffffc0
	s_and_b32 s22, s15, 3
	s_ashr_i32 s19, s18, 31
	s_mul_i32 s23, s18, 0x2a00
	s_mul_hi_i32 s2, s18, 0x2a00
	s_add_u32 s36, s4, s23
	s_addc_u32 s37, s5, s2
	v_lshl_add_u64 v[2:3], s[36:37], 0, v[50:51]
	s_lshl_b32 s2, s22, 7
	v_lshlrev_b32_e32 v0, 1, v52
	v_lshl_add_u64 v[2:3], v[2:3], 0, s[2:3]
	v_lshl_add_u64 v[2:3], v[2:3], 0, v[0:1]
	v_add_co_u32_e32 v2, vcc, s61, v2
	s_lshl_b32 s22, s22, 8
	s_nop 0
	v_addc_co_u32_e32 v3, vcc, 0, v3, vcc
	global_load_dwordx4 v[26:29], v[2:3], off offset:2048 nt
	global_load_dwordx4 v[14:17], v[2:3], off offset:2560 nt
	v_add_u32_e32 v2, s18, v53
	v_ashrrev_i32_e32 v3, 31, v2
	v_lshlrev_b64 v[2:3], 10, v[2:3]
	v_lshl_add_u64 v[2:3], s[0:1], 0, v[2:3]
	s_mov_b32 s23, s3
	v_lshl_add_u64 v[2:3], v[2:3], 0, s[22:23]
	v_lshlrev_b32_e32 v0, 2, v52
	v_lshl_add_u64 v[2:3], v[2:3], 0, v[0:1]
	global_load_dwordx4 v[38:41], v[2:3], off offset:16 nt
	global_load_dwordx4 v[46:49], v[2:3], off nt
	s_or_b32 s60, s2, 0x400
	v_lshl_add_u64 v[2:3], s[18:19], 1, v[54:55]
	v_add_u32_e32 v0, s60, v53
	s_movk_i32 s6, 0x4080
	v_mad_i64_i32 v[4:5], s[24:25], v0, s6, v[2:3]
	v_add_u32_e32 v0, s60, v84
	v_mad_i64_i32 v[2:3], s[24:25], v0, s6, v[2:3]
	global_load_dwordx4 v[22:25], v[4:5], off nt
	global_load_dwordx4 v[34:37], v[2:3], off nt
	v_lshl_add_u64 v[4:5], v[70:71], 0, v[68:69]
	global_load_dwordx4 v[30:33], v[4:5], off nt
	v_lshl_add_u64 v[2:3], v[70:71], 0, v[72:73]
	global_load_dwordx4 v[42:45], v[2:3], off nt
	v_mov_b32_e32 v75, v1
	v_lshl_add_u64 v[2:3], s[36:37], 0, v[74:75]
	v_lshl_add_u64 v[2:3], v[2:3], 0, s[22:23]
	s_mov_b64 s[6:7], 0x1c00
	v_lshl_add_u64 v[2:3], v[2:3], 0, s[6:7]
	s_mov_b32 s6, 0x3e000000
	v_lshl_add_u64 v[4:5], v[56:57], 1, v[2:3]
	v_lshl_add_u64 v[2:3], v[60:61], 1, v[2:3]
	global_load_dwordx2 v[82:83], v[4:5], off nt
	global_load_dwordx4 v[18:21], v[58:59], off
	global_load_dwordx2 v[80:81], v[4:5], off offset:32 nt
	global_load_dwordx4 v[10:13], v[58:59], off offset:64
	global_load_dwordx2 v[78:79], v[4:5], off offset:64 nt
	global_load_dwordx4 v[6:9], v[58:59], off offset:128
	global_load_dwordx2 v[76:77], v[2:3], off nt
	s_nop 0
	global_load_dwordx4 v[2:5], v[62:63], off
	v_add_u32_e32 v75, v95, v98
	s_waitcnt vmcnt(0)
	v_lshlrev_b32_e32 v116, 16, v26
	v_and_b32_e32 v117, 0xffff0000, v26
	v_pk_mul_f32 v[116:117], v[116:117], s[6:7] op_sel_hi:[1,0]
	v_lshlrev_b32_e32 v120, 16, v14
	v_and_b32_e32 v121, 0xffff0000, v14
	v_lshlrev_b32_e32 v26, 16, v27
	v_and_b32_e32 v27, 0xffff0000, v27
	v_pk_mul_f32 v[26:27], v[26:27], s[6:7] op_sel_hi:[1,0]
	v_lshlrev_b32_e32 v14, 16, v15
	v_and_b32_e32 v15, 0xffff0000, v15
	v_mul_f32_e32 v0, 0x3fb8aa3b, v46
	v_exp_f32_e32 v114, v0
	v_mul_f32_e32 v0, 0xbfb8aa3b, v46
	v_exp_f32_e32 v46, v0
	v_mul_f32_e32 v0, 0x3fb8aa3b, v47
	v_exp_f32_e32 v115, v0
	v_mul_f32_e32 v0, 0xbfb8aa3b, v47
	v_exp_f32_e32 v47, v0
	v_mul_f32_e32 v0, 0x3fb8aa3b, v48
	v_pk_mul_f32 v[118:119], v[116:117], v[114:115]
	v_pk_mul_f32 v[114:115], v[114:115], v[120:121]
	v_pk_mul_f32 v[116:117], v[116:117], v[46:47]
	v_pk_mul_f32 v[46:47], v[46:47], v[120:121]
	v_exp_f32_e32 v120, v0
	v_mul_f32_e32 v0, 0xbfb8aa3b, v48
	v_exp_f32_e32 v48, v0
	v_mul_f32_e32 v0, 0x3fb8aa3b, v49
	v_exp_f32_e32 v121, v0
	v_mul_f32_e32 v0, 0xbfb8aa3b, v49
	v_exp_f32_e32 v49, v0
	v_mul_f32_e32 v0, 0x3fb8aa3b, v38
	v_pk_mul_f32 v[122:123], v[26:27], v[120:121]
	v_pk_mul_f32 v[120:121], v[120:121], v[14:15]
	v_pk_mul_f32 v[26:27], v[26:27], v[48:49]
	v_pk_mul_f32 v[48:49], v[48:49], v[14:15]
	v_exp_f32_e32 v14, v0
	v_mul_f32_e32 v0, 0xbfb8aa3b, v38
	v_exp_f32_e32 v38, v0
	v_mul_f32_e32 v0, 0x3fb8aa3b, v39
	v_exp_f32_e32 v15, v0
	v_mul_f32_e32 v0, 0xbfb8aa3b, v39
	v_lshlrev_b32_e32 v124, 16, v28
	v_and_b32_e32 v125, 0xffff0000, v28
	v_exp_f32_e32 v39, v0
	v_pk_mul_f32 v[124:125], v[124:125], s[6:7] op_sel_hi:[1,0]
	v_lshlrev_b32_e32 v128, 16, v16
	v_and_b32_e32 v129, 0xffff0000, v16
	v_mul_f32_e32 v0, 0x3fb8aa3b, v40
	v_pk_mul_f32 v[126:127], v[124:125], v[14:15]
	v_pk_mul_f32 v[130:131], v[14:15], v[128:129]
	v_exp_f32_e32 v14, v0
	v_mul_f32_e32 v0, 0xbfb8aa3b, v40
	v_exp_f32_e32 v40, v0
	v_mul_f32_e32 v0, 0x3fb8aa3b, v41
	v_exp_f32_e32 v15, v0
	v_mul_f32_e32 v0, 0xbfb8aa3b, v41
	v_exp_f32_e32 v41, v0
	v_lshlrev_b32_e32 v28, 16, v29
	v_and_b32_e32 v29, 0xffff0000, v29
	v_pk_mul_f32 v[28:29], v[28:29], s[6:7] op_sel_hi:[1,0]
	v_pk_mul_f32 v[124:125], v[124:125], v[38:39]
	v_pk_mul_f32 v[38:39], v[38:39], v[128:129]
	v_pk_mul_f32 v[128:129], v[28:29], v[14:15]
	v_lshlrev_b32_e32 v16, 16, v17
	v_and_b32_e32 v17, 0xffff0000, v17
	v_pk_mul_f32 v[28:29], v[28:29], v[40:41]
	v_pk_mul_f32 v[132:133], v[14:15], v[16:17]
	v_pk_mul_f32 v[40:41], v[40:41], v[16:17]
	v_cvt_pk_bf16_f32 v14, v118, v119
	v_cvt_pk_bf16_f32 v15, v122, v123
	v_cvt_pk_bf16_f32 v16, v126, v127
	v_cvt_pk_bf16_f32 v17, v128, v129
	ds_write_b128 v107, v[14:17] offset:27648
	v_cvt_pk_bf16_f32 v14, v116, v117
	v_cvt_pk_bf16_f32 v15, v26, v27
	v_cvt_pk_bf16_f32 v16, v124, v125
	v_cvt_pk_bf16_f32 v17, v28, v29
	ds_write_b128 v107, v[14:17] offset:36864
	v_cvt_pk_bf16_f32 v14, v114, v115
	v_cvt_pk_bf16_f32 v15, v120, v121
	v_cvt_pk_bf16_f32 v16, v130, v131
	v_cvt_pk_bf16_f32 v17, v132, v133
	ds_write_b128 v107, v[14:17] offset:46080
	v_cvt_pk_bf16_f32 v14, v46, v47
	v_cvt_pk_bf16_f32 v15, v48, v49
	v_cvt_pk_bf16_f32 v16, v38, v39
	v_cvt_pk_bf16_f32 v17, v40, v41
	v_add_u32_e32 v0, v87, v86
	ds_write_b128 v107, v[14:17] offset:55296
	ds_write_b128 v0, v[22:25]
	v_add_u32_e32 v0, v88, v86
	ds_write_b128 v0, v[30:33]
	v_add_u32_e32 v0, v87, v89
	ds_write_b128 v0, v[34:37]
	v_add_u32_e32 v0, v88, v89
	ds_write_b128 v0, v[42:45]
	s_waitcnt lgkmcnt(0)
	s_barrier
	ds_read_b128 v[14:17], v108 offset:27648
	ds_read_b128 v[22:25], v109 offset:55296
	s_waitcnt lgkmcnt(0)
	v_mfma_f32_16x16x32_bf16 v[14:17], v[14:17], v[22:25], 0
	ds_read_b128 v[22:25], v108 offset:36864
	ds_read_b128 v[26:29], v109 offset:46080
	s_waitcnt lgkmcnt(0)
	v_mfma_f32_16x16x32_bf16 v[22:25], v[22:25], v[26:29], 0
	ds_read_b128 v[26:29], v108 offset:27712
	ds_read_b128 v[30:33], v109 offset:55360
	s_waitcnt lgkmcnt(0)
	v_mfma_f32_16x16x32_bf16 v[14:17], v[26:29], v[30:33], v[14:17]
	ds_read_b128 v[26:29], v108 offset:36928
	ds_read_b128 v[30:33], v109 offset:46144
	s_waitcnt lgkmcnt(0)
	v_mfma_f32_16x16x32_bf16 v[22:25], v[26:29], v[30:33], v[22:25]
	s_nop 7
	v_cndmask_b32_e64 v0, v14, v22, s[38:39]
	v_cvt_pk_bf16_f32 v0, v0, s0
	ds_write_b16 v110, v0
	v_cndmask_b32_e64 v0, v15, v23, s[40:41]
	v_cvt_pk_bf16_f32 v0, v0, s0
	ds_write_b16 v110, v0 offset:144
	v_cndmask_b32_e64 v0, v16, v24, s[42:43]
	v_cvt_pk_bf16_f32 v0, v0, s0
	ds_write_b16 v110, v0 offset:288
	v_cndmask_b32_e64 v0, v17, v25, s[44:45]
	v_cvt_pk_bf16_f32 v0, v0, s0
	ds_write_b16 v110, v0 offset:432
	ds_read_b128 v[14:17], v108 offset:27648
	ds_read_b128 v[22:25], v109 offset:57600
	s_waitcnt lgkmcnt(0)
	v_mfma_f32_16x16x32_bf16 v[14:17], v[14:17], v[22:25], 0
	ds_read_b128 v[22:25], v108 offset:36864
	ds_read_b128 v[26:29], v109 offset:48384
	s_waitcnt lgkmcnt(0)
	v_mfma_f32_16x16x32_bf16 v[22:25], v[22:25], v[26:29], 0
	ds_read_b128 v[26:29], v108 offset:27712
	ds_read_b128 v[30:33], v109 offset:57664
	s_waitcnt lgkmcnt(0)
	v_mfma_f32_16x16x32_bf16 v[14:17], v[26:29], v[30:33], v[14:17]
	ds_read_b128 v[26:29], v108 offset:36928
	ds_read_b128 v[30:33], v109 offset:48448
	s_waitcnt lgkmcnt(0)
	v_mfma_f32_16x16x32_bf16 v[22:25], v[26:29], v[30:33], v[22:25]
	v_add_u32_e32 v26, v95, v96
	s_nop 6
	v_cndmask_b32_e64 v0, v14, v22, s[46:47]
	v_cvt_pk_bf16_f32 v0, v0, s0
	ds_write_b16 v90, v0
	v_cndmask_b32_e64 v0, v15, v23, s[48:49]
	v_cvt_pk_bf16_f32 v0, v0, s0
	ds_write_b16 v91, v0
	v_cndmask_b32_e64 v0, v16, v24, s[50:51]
	v_cvt_pk_bf16_f32 v0, v0, s0
	ds_write_b16 v92, v0
	v_cndmask_b32_e64 v0, v17, v25, s[52:53]
	v_cvt_pk_bf16_f32 v0, v0, s0
	ds_write_b16 v93, v0
	v_add_u32_e32 v0, v94, v96
	s_waitcnt lgkmcnt(0)
	s_barrier
	ds_read_b128 v[14:17], v0
	ds_read_b128 v[34:37], v111
	ds_read_b128 v[22:25], v26
	ds_read_b128 v[38:41], v112 offset:27648
	s_waitcnt lgkmcnt(2)
	v_mfma_f32_16x16x32_bf16 v[14:17], v[14:17], v[34:37], 0
	s_waitcnt lgkmcnt(0)
	v_mfma_f32_16x16x32_bf16 v[14:17], v[22:25], v[38:41], v[14:17]
	ds_read_b128 v[22:25], v0 offset:64
	ds_read_b128 v[42:45], v111 offset:64
	v_add_u32_e32 v0, v94, v97
	s_waitcnt lgkmcnt(0)
	v_mfma_f32_16x16x32_bf16 v[14:17], v[22:25], v[42:45], v[14:17]
	ds_read_b128 v[22:25], v26 offset:64
	ds_read_b128 v[46:49], v112 offset:27712
	v_add_u32_e32 v26, v95, v97
	s_waitcnt lgkmcnt(0)
	v_mfma_f32_16x16x32_bf16 v[30:33], v[22:25], v[46:49], v[14:17]
	ds_read_b128 v[22:25], v26
	s_nop 1
	ds_read_b128 v[14:17], v0
	s_waitcnt lgkmcnt(0)
	v_mfma_f32_16x16x32_bf16 v[14:17], v[14:17], v[34:37], 0
	v_mfma_f32_16x16x32_bf16 v[14:17], v[22:25], v[38:41], v[14:17]
	ds_read_b128 v[22:25], v0 offset:64
	v_add_u32_e32 v0, v94, v98
	s_waitcnt lgkmcnt(0)
	v_mfma_f32_16x16x32_bf16 v[14:17], v[22:25], v[42:45], v[14:17]
	ds_read_b128 v[22:25], v26 offset:64
	s_waitcnt lgkmcnt(0)
	v_mfma_f32_16x16x32_bf16 v[26:29], v[22:25], v[46:49], v[14:17]
	s_nop 4
	ds_read_b128 v[14:17], v0
	ds_read_b128 v[22:25], v75
	s_waitcnt lgkmcnt(1)
	v_mfma_f32_16x16x32_bf16 v[14:17], v[14:17], v[34:37], 0
	s_waitcnt lgkmcnt(0)
	v_mfma_f32_16x16x32_bf16 v[14:17], v[22:25], v[38:41], v[14:17]
	ds_read_b128 v[22:25], v0 offset:64
	v_add_u32_e32 v0, v94, v99
	s_waitcnt lgkmcnt(0)
	v_mfma_f32_16x16x32_bf16 v[14:17], v[22:25], v[42:45], v[14:17]
	ds_read_b128 v[22:25], v75 offset:64
	v_add_u32_e32 v75, v95, v99
	s_waitcnt lgkmcnt(0)
	v_mfma_f32_16x16x32_bf16 v[22:25], v[22:25], v[46:49], v[14:17]
	s_nop 3
	ds_read_b128 v[14:17], v0
	s_waitcnt lgkmcnt(0)
	v_mfma_f32_16x16x32_bf16 v[14:17], v[14:17], v[34:37], 0
	ds_read_b128 v[34:37], v75
	s_waitcnt lgkmcnt(0)
	v_mfma_f32_16x16x32_bf16 v[14:17], v[34:37], v[38:41], v[14:17]
	ds_read_b128 v[34:37], v0 offset:64
	v_mul_f32_e32 v0, v31, v31
	v_fmac_f32_e32 v0, v30, v30
	s_waitcnt lgkmcnt(0)
	v_mfma_f32_16x16x32_bf16 v[14:17], v[34:37], v[42:45], v[14:17]
	ds_read_b128 v[34:37], v75 offset:64
	s_waitcnt lgkmcnt(0)
	v_mfma_f32_16x16x32_bf16 v[14:17], v[34:37], v[46:49], v[14:17]
	v_mul_f32_e32 v34, v33, v33
	v_fmac_f32_e32 v34, v32, v32
	v_add_f32_e32 v0, v0, v34
	v_mul_f32_e32 v34, v27, v27
	v_mul_f32_e32 v35, v29, v29
	v_fmac_f32_e32 v34, v26, v26
	v_fmac_f32_e32 v35, v28, v28
	v_add_f32_e32 v34, v34, v35
	v_add_f32_e32 v0, v0, v34
	v_mul_f32_e32 v34, v23, v23
	v_mul_f32_e32 v35, v25, v25
	v_fmac_f32_e32 v34, v22, v22
	v_fmac_f32_e32 v35, v24, v24
	v_add_f32_e32 v34, v34, v35
	v_add_f32_e32 v0, v0, v34
	v_mul_f32_e32 v34, v15, v15
	v_mul_f32_e32 v35, v17, v17
	v_fmac_f32_e32 v34, v14, v14
	v_fmac_f32_e32 v35, v16, v16
	v_add_f32_e32 v34, v34, v35
	v_add_f32_e32 v0, v0, v34
	v_mov_b32_e32 v34, v0
	s_nop 1
	v_permlane16_swap_b32_e32 v34, v0
	s_waitcnt lgkmcnt(0)
	v_add_f32_e32 v0, v0, v34
	v_mov_b32_e32 v34, v0
	s_nop 1
	v_permlane32_swap_b32_e32 v34, v0
	s_and_saveexec_b64 s[36:37], s[54:55]
	s_cbranch_execz .LBB0_347
	s_waitcnt lgkmcnt(0)
	v_add_f32_e32 v0, v0, v34
	ds_write_b32 v105, v0 offset:27136
	s_branch .LBB0_347

.LBB0_351:
	s_andn2_b64 vcc, exec, s[0:1]
	s_cbranch_vccnz .LBB0_357
	v_readlane_b32 s22, v238, 21
	s_mul_i32 s0, s22, 0x2a00
	s_add_u32 s0, s4, s0
	s_mul_hi_i32 s1, s22, 0x2a00
	s_addc_u32 s1, s5, s1
	v_ashrrev_i32_e32 v128, 3, v104
	v_mov_b64_e32 v[2:3], s[0:1]
	v_readlane_b32 s2, v238, 23
	v_lshlrev_b32_e32 v0, 3, v104
	v_mad_i64_i32 v[2:3], s[14:15], v128, s59, v[2:3]
	s_lshl_b32 s18, s2, 1
	s_mov_b32 s19, s3
	v_and_b32_e32 v0, 56, v0
	v_lshlrev_b32_e32 v18, 1, v0
	v_mov_b32_e32 v19, v1
	v_lshl_add_u64 v[2:3], v[2:3], 0, s[18:19]
	v_lshl_add_u64 v[2:3], v[2:3], 0, v[18:19]
	v_add_co_u32_e32 v2, vcc, s61, v2
	s_add_u32 s36, s10, 0x1c600000
	s_nop 0
	v_addc_co_u32_e32 v3, vcc, 0, v3, vcc
	global_load_dwordx4 v[66:69], v[2:3], off offset:2048 nt
	global_load_dwordx4 v[54:57], v[2:3], off offset:2560 nt
	v_add_u32_e32 v2, s22, v128
	v_ashrrev_i32_e32 v3, 31, v2
	s_addc_u32 s37, s11, 0
	v_lshlrev_b64 v[2:3], 10, v[2:3]
	v_lshl_add_u64 v[2:3], s[36:37], 0, v[2:3]
	s_lshl_b32 s38, s2, 2
	s_mov_b32 s39, s3
	v_lshl_add_u64 v[2:3], v[2:3], 0, s[38:39]
	v_lshlrev_b32_e32 v20, 2, v0
	v_mov_b32_e32 v21, v1
	v_lshl_add_u64 v[2:3], v[2:3], 0, v[20:21]
	global_load_dwordx4 v[74:77], v[2:3], off offset:16 nt
	global_load_dwordx4 v[78:81], v[2:3], off nt
	s_add_u32 s24, s10, 0x1a000000
	s_addc_u32 s25, s11, 0
	v_readlane_b32 s14, v238, 24
	v_readlane_b32 s23, v238, 22
	v_readlane_b32 s15, v238, 25
	s_add_u32 s14, s24, s14
	s_addc_u32 s15, s25, s15
	s_lshl_b64 s[22:23], s[22:23], 1
	s_add_u32 s22, s8, s22
	v_add_u32_e32 v0, 0x200, v104
	s_addc_u32 s23, s9, s23
	v_readlane_b32 s2, v238, 27
	v_ashrrev_i32_e32 v129, 3, v0
	v_lshl_add_u64 v[2:3], s[22:23], 0, v[18:19]
	v_add_u32_e32 v28, s2, v128
	s_movk_i32 s6, 0x4080
	v_add_u32_e32 v29, s2, v129
	v_lshl_add_u64 v[4:5], s[14:15], 0, v[18:19]
	v_mad_i64_i32 v[6:7], s[14:15], v28, s6, v[2:3]
	v_mad_i64_i32 v[2:3], s[14:15], v29, s6, v[2:3]
	global_load_dwordx4 v[50:53], v[6:7], off nt
	global_load_dwordx4 v[62:65], v[2:3], off nt
	v_lshlrev_b32_e32 v6, 6, v128
	v_lshlrev_b32_e32 v2, 6, v129
	v_ashrrev_i32_e32 v7, 31, v6
	v_ashrrev_i32_e32 v3, 31, v2
	v_lshlrev_b64 v[22:23], 1, v[6:7]
	v_lshlrev_b64 v[34:35], 1, v[2:3]
	v_lshl_add_u64 v[6:7], v[4:5], 0, v[22:23]
	v_lshl_add_u64 v[2:3], v[4:5], 0, v[34:35]
	global_load_dwordx4 v[58:61], v[6:7], off nt
	global_load_dwordx4 v[70:73], v[2:3], off nt
	s_lshl_b32 s22, s78, 4
	s_and_b32 s79, s22, 48
	v_or_b32_e32 v105, s79, v102
	v_mul_u32_u24_e32 v2, 0x1500, v105
	v_lshlrev_b32_e32 v84, 1, v2
	v_mov_b32_e32 v85, v1
	v_lshl_add_u64 v[2:3], s[0:1], 0, v[84:85]
	v_readlane_b32 s0, v238, 26
	s_lshl_b32 s2, s0, 1
	v_readlane_b32 s0, v236, 46
	s_lshl_b32 s14, s0, 7
	s_ashr_i32 s15, s14, 31
	v_readlane_b32 s40, v236, 11
	s_and_b32 s0, s22, 0xffffffc0
	s_lshl_b64 s[14:15], s[14:15], 2
	v_readlane_b32 s52, v236, 23
	v_readlane_b32 s1, v236, 47
	v_readlane_b32 s53, v236, 24
	s_add_u32 s14, s52, s14
	v_lshlrev_b32_e32 v0, 2, v103
	s_addc_u32 s15, s53, s15
	s_or_b32 s1, s22, 48
	v_or_b32_e32 v90, s0, v0
	v_or_b32_e32 v82, s1, v0
	v_lshl_add_u64 v[2:3], v[2:3], 0, s[2:3]
	s_mov_b64 s[64:65], 0x1c00
	v_ashrrev_i32_e32 v91, 31, v90
	v_ashrrev_i32_e32 v83, 31, v82
	v_lshl_add_u64 v[2:3], v[2:3], 0, s[64:65]
	v_lshlrev_b64 v[86:87], 1, v[90:91]
	v_readlane_b32 s41, v236, 12
	v_lshlrev_b64 v[106:107], 1, v[82:83]
	v_lshl_add_u64 v[4:5], v[2:3], 0, v[86:87]
	v_lshl_add_u64 v[6:7], v[90:91], 2, s[14:15]
	v_lshl_add_u64 v[2:3], v[2:3], 0, v[106:107]
	v_readlane_b32 s40, v238, 28
	global_load_dwordx2 v[100:101], v[4:5], off nt
	global_load_dwordx4 v[14:17], v[6:7], off
	global_load_dwordx2 v[98:99], v[4:5], off offset:32 nt
	global_load_dwordx4 v[10:13], v[6:7], off offset:64
	global_load_dwordx2 v[96:97], v[4:5], off offset:64 nt
	s_nop 0
	global_load_dwordx4 v[6:9], v[6:7], off offset:128
	v_readlane_b32 s41, v238, 29
	global_load_dwordx2 v[94:95], v[2:3], off nt
	v_lshl_add_u64 v[2:3], v[82:83], 2, s[14:15]
	s_mul_i32 s14, s40, 0x2a00
	s_add_u32 s14, s4, s14
	s_mul_hi_i32 s15, s40, 0x2a00
	s_addc_u32 s15, s5, s15
	v_mov_b64_e32 v[24:25], s[14:15]
	v_mad_i64_i32 v[24:25], s[22:23], v128, s59, v[24:25]
	v_lshl_add_u64 v[24:25], v[24:25], 0, s[18:19]
	v_readlane_b32 s18, v238, 30
	v_lshl_add_u64 v[84:85], s[14:15], 0, v[84:85]
	v_readlane_b32 s19, v238, 31
	s_add_u32 s18, s24, s18
	v_lshl_add_u64 v[84:85], v[84:85], 0, s[2:3]
	s_addc_u32 s19, s25, s19
	s_lshl_b64 s[22:23], s[40:41], 1
	v_lshl_add_u64 v[84:85], v[84:85], 0, s[64:65]
	s_add_u32 s22, s8, s22
	v_lshl_add_u64 v[86:87], v[84:85], 0, v[86:87]
	v_lshl_add_u64 v[84:85], v[84:85], 0, v[106:107]
	s_waitcnt vmcnt(0)
	v_mul_f32_e32 v106, 0x3fb8aa3b, v78
	v_mul_f32_e32 v78, 0xbfb8aa3b, v78
	v_mul_f32_e32 v107, 0x3fb8aa3b, v79
	v_mul_f32_e32 v79, 0xbfb8aa3b, v79
	s_addc_u32 s23, s9, s23
	v_exp_f32_e32 v106, v106
	v_exp_f32_e32 v78, v78
	v_exp_f32_e32 v107, v107
	v_exp_f32_e32 v79, v79
	v_lshl_add_u64 v[26:27], s[22:23], 0, v[18:19]
	v_lshl_add_u64 v[24:25], v[24:25], 0, v[18:19]
	v_lshl_add_u64 v[36:37], s[18:19], 0, v[18:19]
	v_mad_i64_i32 v[18:19], s[18:19], v28, s6, v[26:27]
	v_mad_i64_i32 v[26:27], s[18:19], v29, s6, v[26:27]
	v_lshlrev_b32_e32 v108, 16, v66
	v_and_b32_e32 v109, 0xffff0000, v66
	s_mov_b32 s6, 0x3e000000
	v_pk_mul_f32 v[108:109], v[108:109], s[6:7] op_sel_hi:[1,0]
	v_lshlrev_b32_e32 v112, 16, v54
	v_and_b32_e32 v113, 0xffff0000, v54
	v_mul_f32_e32 v54, 0x3fb8aa3b, v80
	v_pk_mul_f32 v[110:111], v[108:109], v[106:107]
	v_pk_mul_f32 v[108:109], v[108:109], v[78:79]
	v_pk_mul_f32 v[106:107], v[106:107], v[112:113]
	v_pk_mul_f32 v[78:79], v[78:79], v[112:113]
	v_exp_f32_e32 v112, v54
	v_mul_f32_e32 v54, 0xbfb8aa3b, v80
	v_exp_f32_e32 v80, v54
	v_mul_f32_e32 v54, 0x3fb8aa3b, v81
	v_exp_f32_e32 v113, v54
	v_mul_f32_e32 v54, 0xbfb8aa3b, v81
	v_exp_f32_e32 v81, v54
	v_lshlrev_b32_e32 v66, 16, v67
	v_and_b32_e32 v67, 0xffff0000, v67
	v_pk_mul_f32 v[66:67], v[66:67], s[6:7] op_sel_hi:[1,0]
	v_lshlrev_b32_e32 v54, 16, v55
	v_and_b32_e32 v55, 0xffff0000, v55
	v_pk_mul_f32 v[114:115], v[66:67], v[112:113]
	v_pk_mul_f32 v[66:67], v[66:67], v[80:81]
	v_pk_mul_f32 v[112:113], v[112:113], v[54:55]
	v_pk_mul_f32 v[80:81], v[80:81], v[54:55]
	v_mul_f32_e32 v55, 0xbfb8aa3b, v74
	v_mul_f32_e32 v54, 0x3fb8aa3b, v74
	v_exp_f32_e32 v74, v55
	v_mul_f32_e32 v55, 0x3fb8aa3b, v75
	v_exp_f32_e32 v54, v54
	v_exp_f32_e32 v55, v55
	v_mul_f32_e32 v75, 0xbfb8aa3b, v75
	v_exp_f32_e32 v75, v75
	v_lshlrev_b32_e32 v116, 16, v68
	v_and_b32_e32 v117, 0xffff0000, v68
	v_pk_mul_f32 v[116:117], v[116:117], s[6:7] op_sel_hi:[1,0]
	v_lshlrev_b32_e32 v120, 16, v56
	v_and_b32_e32 v121, 0xffff0000, v56
	v_pk_mul_f32 v[118:119], v[116:117], v[54:55]
	v_pk_mul_f32 v[122:123], v[54:55], v[120:121]
	v_mul_f32_e32 v55, 0xbfb8aa3b, v76
	v_pk_mul_f32 v[116:117], v[116:117], v[74:75]
	v_pk_mul_f32 v[120:121], v[74:75], v[120:121]
	v_mul_f32_e32 v54, 0x3fb8aa3b, v76
	v_exp_f32_e32 v74, v55
	v_mul_f32_e32 v55, 0x3fb8aa3b, v77
	v_add_co_u32_e32 v24, vcc, s61, v24
	v_exp_f32_e32 v54, v54
	v_exp_f32_e32 v55, v55
	v_mul_f32_e32 v56, 0xbfb8aa3b, v77
	v_addc_co_u32_e32 v25, vcc, 0, v25, vcc
	v_exp_f32_e32 v75, v56
	global_load_dwordx4 v[2:5], v[2:3], off
	s_nop 0
	global_load_dwordx4 v[38:41], v[24:25], off offset:2048 nt
	global_load_dwordx4 v[30:33], v[24:25], off offset:2560 nt
	v_add_u32_e32 v24, s40, v128
	v_lshlrev_b32_e32 v68, 16, v69
	v_and_b32_e32 v69, 0xffff0000, v69
	v_ashrrev_i32_e32 v25, 31, v24
	v_pk_mul_f32 v[68:69], v[68:69], s[6:7] op_sel_hi:[1,0]
	v_lshlrev_b32_e32 v56, 16, v57
	v_and_b32_e32 v57, 0xffff0000, v57
	v_lshlrev_b64 v[24:25], 10, v[24:25]
	v_pk_mul_f32 v[76:77], v[68:69], v[54:55]
	v_pk_mul_f32 v[124:125], v[54:55], v[56:57]
	s_movk_i32 s6, 0x90
	v_lshlrev_b32_e32 v54, 4, v104
	v_lshl_add_u64 v[24:25], s[36:37], 0, v[24:25]
	v_pk_mul_f32 v[68:69], v[68:69], v[74:75]
	v_pk_mul_f32 v[126:127], v[74:75], v[56:57]
	v_mul_lo_u32 v128, v128, s6
	v_and_b32_e32 v75, 0x70, v54
	v_lshl_add_u64 v[24:25], v[24:25], 0, s[38:39]
	v_add_u32_e32 v74, v128, v75
	v_lshl_add_u64 v[20:21], v[24:25], 0, v[20:21]
	v_lshl_add_u64 v[22:23], v[36:37], 0, v[22:23]
	v_lshl_add_u64 v[34:35], v[36:37], 0, v[34:35]
	v_cvt_pk_bf16_f32 v54, v110, v111
	v_cvt_pk_bf16_f32 v55, v114, v115
	v_cvt_pk_bf16_f32 v56, v118, v119
	v_cvt_pk_bf16_f32 v57, v76, v77
	v_add_u32_e32 v74, 0, v74
	global_load_dwordx4 v[42:45], v[20:21], off offset:16 nt
	global_load_dwordx4 v[46:49], v[20:21], off nt
	v_readlane_b32 s7, v236, 32
	global_load_dwordx4 v[18:21], v[18:19], off nt
	v_readlane_b32 s18, v236, 33
	global_load_dwordx4 v[22:25], v[22:23], off nt
	s_lshl_b32 s14, s78, 3
	global_load_dwordx4 v[26:29], v[26:27], off nt
	s_and_b32 s14, s14, -16
	global_load_dwordx4 v[34:37], v[34:35], off nt
	s_nop 0
	global_load_dwordx2 v[92:93], v[86:87], off nt
	global_load_dwordx2 v[88:89], v[86:87], off offset:32 nt
	s_nop 0
	global_load_dwordx2 v[86:87], v[86:87], off offset:64 nt
	ds_write_b128 v74, v[54:57] offset:27648
	v_cvt_pk_bf16_f32 v54, v108, v109
	v_cvt_pk_bf16_f32 v55, v66, v67
	v_cvt_pk_bf16_f32 v56, v116, v117
	v_cvt_pk_bf16_f32 v57, v68, v69
	ds_write_b128 v74, v[54:57] offset:36864
	v_cvt_pk_bf16_f32 v54, v106, v107
	v_cvt_pk_bf16_f32 v55, v112, v113
	v_cvt_pk_bf16_f32 v56, v122, v123
	v_cvt_pk_bf16_f32 v57, v124, v125
	ds_write_b128 v74, v[54:57] offset:46080
	v_cvt_pk_bf16_f32 v54, v78, v79
	v_cvt_pk_bf16_f32 v55, v80, v81
	v_cvt_pk_bf16_f32 v56, v120, v121
	v_cvt_pk_bf16_f32 v57, v126, v127
	ds_write_b128 v74, v[54:57] offset:55296
	v_add_u32_e32 v54, s7, v75
	v_add_u32_e32 v55, s18, v75
	v_add_u32_e32 v75, v54, v128
	ds_write_b128 v75, v[50:53]
	v_mul_lo_u32 v50, v129, s6
	v_add_u32_e32 v77, v54, v50
	v_add_u32_e32 v78, v55, v50
	v_or_b32_e32 v50, s14, v102
	v_mul_lo_u32 v50, v50, s6
	v_add_u32_e32 v76, v55, v128
	v_add_u32_e32 v50, 0, v50
	v_lshlrev_b32_e32 v67, 4, v103
	s_lshl_b32 s15, s78, 5
	ds_write_b128 v76, v[58:61]
	ds_write_b128 v78, v[70:73]
	v_add_u32_e32 v69, v50, v67
	v_add_u32_e32 v70, 0, v67
	v_and_or_b32 v66, s15, 32, v102
	global_load_dwordx2 v[84:85], v[84:85], off nt
	ds_write_b128 v77, v[62:65]
	s_waitcnt lgkmcnt(0)
	s_barrier
	v_mad_u32_u24 v72, v66, s6, v70
	ds_read_b128 v[50:53], v69 offset:27648
	ds_read_b128 v[54:57], v72 offset:55296
	s_waitcnt lgkmcnt(0)
	v_mfma_f32_16x16x32_bf16 v[50:53], v[50:53], v[54:57], 0
	ds_read_b128 v[54:57], v69 offset:36864
	ds_read_b128 v[58:61], v72 offset:46080
	v_or_b32_e32 v68, s14, v0
	s_add_i32 s14, 0, 0x12000
	s_waitcnt lgkmcnt(0)
	v_mfma_f32_16x16x32_bf16 v[54:57], v[54:57], v[58:61], 0
	ds_read_b128 v[58:61], v69 offset:27712
	ds_read_b128 v[62:65], v72 offset:55360
	v_cmp_gt_i32_e64 s[38:39], v66, v68
	v_mul_lo_u32 v79, v68, s6
	s_waitcnt lgkmcnt(0)
	v_mfma_f32_16x16x32_bf16 v[50:53], v[58:61], v[62:65], v[50:53]
	ds_read_b128 v[58:61], v69 offset:36928
	ds_read_b128 v[62:65], v72 offset:46144
	v_or_b32_e32 v80, 1, v68
	v_cmp_gt_i32_e64 s[40:41], v66, v80
	s_waitcnt lgkmcnt(0)
	v_mfma_f32_16x16x32_bf16 v[54:57], v[58:61], v[62:65], v[54:57]
	v_lshl_add_u32 v58, v66, 1, s14
	v_add_u32_e32 v71, v58, v79
	v_readlane_b32 s42, v236, 13
	s_nop 4
	v_cndmask_b32_e64 v50, v50, v54, s[38:39]
	v_cvt_pk_bf16_f32 v50, v50, s0
	v_readlane_b32 s43, v236, 14
	ds_write_b16 v71, v50
	v_cndmask_b32_e64 v50, v51, v55, s[40:41]
	v_add_u32_e32 v81, 0x90, v79
	v_or_b32_e32 v104, 2, v68
	v_cvt_pk_bf16_f32 v50, v50, s0
	v_add_u32_e32 v51, v58, v81
	v_cmp_gt_i32_e64 s[42:43], v66, v104
	v_readlane_b32 s44, v236, 15
	v_readlane_b32 s45, v236, 16
	ds_write_b16 v51, v50
	v_cndmask_b32_e64 v50, v52, v56, s[42:43]
	v_add_u32_e32 v106, 0x120, v79
	v_or_b32_e32 v107, 3, v68
	v_cvt_pk_bf16_f32 v50, v50, s0
	v_add_u32_e32 v51, v58, v106
	v_cmp_gt_i32_e64 s[44:45], v66, v107
	ds_write_b16 v51, v50
	v_add_u32_e32 v108, 0x1b0, v79
	v_cndmask_b32_e64 v50, v53, v57, s[44:45]
	v_cvt_pk_bf16_f32 v50, v50, s0
	v_add_u32_e32 v51, v58, v108
	ds_write_b16 v51, v50
	ds_read_b128 v[50:53], v69 offset:27648
	ds_read_b128 v[54:57], v72 offset:57600
	s_waitcnt lgkmcnt(0)
	v_mfma_f32_16x16x32_bf16 v[50:53], v[50:53], v[54:57], 0
	ds_read_b128 v[54:57], v69 offset:36864
	ds_read_b128 v[58:61], v72 offset:48384
	v_readlane_b32 s46, v236, 17
	v_readlane_b32 s47, v236, 18
	s_waitcnt lgkmcnt(0)
	v_mfma_f32_16x16x32_bf16 v[54:57], v[54:57], v[58:61], 0
	ds_read_b128 v[58:61], v69 offset:27712
	ds_read_b128 v[62:65], v72 offset:57664
	v_or_b32_e32 v109, 16, v66
	v_cmp_gt_i32_e64 s[46:47], v109, v68
	s_waitcnt lgkmcnt(0)
	v_mfma_f32_16x16x32_bf16 v[50:53], v[58:61], v[62:65], v[50:53]
	ds_read_b128 v[58:61], v69 offset:36928
	ds_read_b128 v[62:65], v72 offset:48448
	v_readlane_b32 s48, v236, 19
	v_readlane_b32 s49, v236, 20
	s_waitcnt lgkmcnt(0)
	v_mfma_f32_16x16x32_bf16 v[54:57], v[58:61], v[62:65], v[54:57]
	v_cmp_gt_i32_e64 s[48:49], v109, v80
	v_readlane_b32 s50, v236, 21
	v_readlane_b32 s51, v236, 22
	s_nop 4
	v_cndmask_b32_e64 v50, v50, v54, s[46:47]
	v_lshlrev_b32_e32 v54, 1, v109
	v_cvt_pk_bf16_f32 v50, v50, s0
	v_add3_u32 v79, s14, v79, v54
	ds_write_b16 v79, v50
	v_cndmask_b32_e64 v50, v51, v55, s[48:49]
	v_cvt_pk_bf16_f32 v50, v50, s0
	v_add3_u32 v81, s14, v81, v54
	v_cmp_gt_i32_e64 s[50:51], v109, v104
	ds_write_b16 v81, v50
	v_add3_u32 v104, s14, v106, v54
	v_cndmask_b32_e64 v50, v52, v56, s[50:51]
	v_cvt_pk_bf16_f32 v50, v50, s0
	v_cmp_gt_i32_e64 s[52:53], v109, v107
	ds_write_b16 v104, v50
	v_mov_b32_e32 v73, s14
	v_cndmask_b32_e64 v50, v53, v57, s[52:53]
	v_cvt_pk_bf16_f32 v50, v50, s0
	v_add3_u32 v106, s14, v108, v54
	ds_write_b16 v106, v50
	v_mad_u32_u24 v50, v105, s6, v73
	v_add_u32_e32 v73, v50, v67
	v_mad_u32_u24 v50, v105, s6, 0
	v_or_b32_e32 v110, s0, v102
	v_add_u32_e32 v72, v50, v67
	v_add_u32_e32 v68, s7, v67
	v_mul_lo_u32 v50, v110, s6
	v_add_u32_e32 v67, s18, v67
	v_add_u32_e32 v107, v68, v50
	s_waitcnt lgkmcnt(0)
	s_barrier
	v_add_u32_e32 v80, v67, v50
	ds_read_b128 v[50:53], v107
	ds_read_b128 v[114:117], v73
	ds_read_b128 v[54:57], v80
	ds_read_b128 v[118:121], v72 offset:27648
	s_waitcnt lgkmcnt(2)
	v_mfma_f32_16x16x32_bf16 v[50:53], v[50:53], v[114:117], 0
	v_readlane_b32 s54, v236, 25
	v_readlane_b32 s55, v236, 26
	v_cmp_eq_u32_e64 s[54:55], 0, v103
	s_waitcnt lgkmcnt(0)
	v_mfma_f32_16x16x32_bf16 v[50:53], v[54:57], v[118:121], v[50:53]
	ds_read_b128 v[54:57], v107 offset:64
	ds_read_b128 v[122:125], v73 offset:64
	s_waitcnt lgkmcnt(0)
	v_mfma_f32_16x16x32_bf16 v[50:53], v[54:57], v[122:125], v[50:53]
	ds_read_b128 v[54:57], v80 offset:64
	ds_read_b128 v[126:129], v72 offset:27712
	s_waitcnt lgkmcnt(0)
	v_mfma_f32_16x16x32_bf16 v[62:65], v[54:57], v[126:129], v[50:53]
	s_nop 3
	v_or_b32_e32 v50, 16, v110
	v_mul_lo_u32 v50, v50, s6
	v_add_u32_e32 v109, v68, v50
	v_add_u32_e32 v108, v67, v50
	ds_read_b128 v[50:53], v109
	ds_read_b128 v[54:57], v108
	s_waitcnt lgkmcnt(1)
	v_mfma_f32_16x16x32_bf16 v[50:53], v[50:53], v[114:117], 0
	s_waitcnt lgkmcnt(0)
	v_mfma_f32_16x16x32_bf16 v[50:53], v[54:57], v[118:121], v[50:53]
	ds_read_b128 v[54:57], v109 offset:64
	s_waitcnt lgkmcnt(0)
	v_mfma_f32_16x16x32_bf16 v[50:53], v[54:57], v[122:125], v[50:53]
	ds_read_b128 v[54:57], v108 offset:64
	s_waitcnt lgkmcnt(0)
	v_mfma_f32_16x16x32_bf16 v[58:61], v[54:57], v[126:129], v[50:53]
	s_nop 4
	v_or_b32_e32 v50, 32, v110
	v_mul_lo_u32 v50, v50, s6
	v_add_u32_e32 v111, v68, v50
	v_add_u32_e32 v110, v67, v50
	ds_read_b128 v[50:53], v111
	ds_read_b128 v[54:57], v110
	s_waitcnt lgkmcnt(1)
	v_mfma_f32_16x16x32_bf16 v[50:53], v[50:53], v[114:117], 0
	s_waitcnt lgkmcnt(0)
	v_mfma_f32_16x16x32_bf16 v[50:53], v[54:57], v[118:121], v[50:53]
	ds_read_b128 v[54:57], v111 offset:64
	s_waitcnt lgkmcnt(0)
	v_mfma_f32_16x16x32_bf16 v[50:53], v[54:57], v[122:125], v[50:53]
	ds_read_b128 v[54:57], v110 offset:64
	s_waitcnt lgkmcnt(0)
	v_mfma_f32_16x16x32_bf16 v[54:57], v[54:57], v[126:129], v[50:53]
	s_nop 4
	v_or_b32_e32 v50, s1, v102
	v_mul_lo_u32 v50, v50, s6
	v_add_u32_e32 v113, v68, v50
	v_add_u32_e32 v112, v67, v50
	ds_read_b128 v[50:53], v113
	s_waitcnt lgkmcnt(0)
	v_mfma_f32_16x16x32_bf16 v[50:53], v[50:53], v[114:117], 0
	ds_read_b128 v[114:117], v112
	v_mul_f32_e32 v67, v63, v63
	v_mul_f32_e32 v68, v65, v65
	s_waitcnt lgkmcnt(0)
	v_mfma_f32_16x16x32_bf16 v[50:53], v[114:117], v[118:121], v[50:53]
	ds_read_b128 v[114:117], v113 offset:64
	v_fmac_f32_e32 v67, v62, v62
	v_fmac_f32_e32 v68, v64, v64
	s_waitcnt lgkmcnt(0)
	v_mfma_f32_16x16x32_bf16 v[50:53], v[114:117], v[122:125], v[50:53]
	ds_read_b128 v[114:117], v112 offset:64
	v_add_f32_e32 v67, v67, v68
	v_mul_f32_e32 v68, v59, v59
	s_waitcnt lgkmcnt(0)
	v_mfma_f32_16x16x32_bf16 v[50:53], v[114:117], v[126:129], v[50:53]
	v_mul_f32_e32 v114, v61, v61
	v_fmac_f32_e32 v68, v58, v58
	v_fmac_f32_e32 v114, v60, v60
	v_add_f32_e32 v68, v68, v114
	v_add_f32_e32 v67, v67, v68
	v_mul_f32_e32 v68, v55, v55
	v_mul_f32_e32 v114, v57, v57
	v_fmac_f32_e32 v68, v54, v54
	v_fmac_f32_e32 v114, v56, v56
	v_add_f32_e32 v68, v68, v114
	v_add_f32_e32 v67, v67, v68
	v_mul_f32_e32 v68, v51, v51
	v_mul_f32_e32 v114, v53, v53
	v_fmac_f32_e32 v68, v50, v50
	v_fmac_f32_e32 v114, v52, v52
	v_add_f32_e32 v68, v68, v114
	v_and_b32_e32 v114, 64, v209
	v_add_f32_e32 v67, v67, v68
	v_xor_b32_e32 v68, 16, v209
	v_add_u32_e32 v115, 64, v114
	v_cmp_lt_i32_e32 vcc, v68, v115
	s_nop 1
	v_cndmask_b32_e32 v68, v209, v68, vcc
	v_lshlrev_b32_e32 v114, 2, v68
	v_mov_b32_e32 v68, v67
	s_nop 1
	v_permlane16_swap_b32_e32 v68, v67
	s_waitcnt lgkmcnt(0)
	v_add_f32_e32 v67, v67, v68
	v_xor_b32_e32 v68, 32, v209
	v_cmp_lt_i32_e32 vcc, v68, v115
	s_nop 1
	v_cndmask_b32_e32 v68, v209, v68, vcc
	v_lshlrev_b32_e32 v115, 2, v68
	v_mov_b32_e32 v68, v67
	s_nop 1
	v_permlane32_swap_b32_e32 v68, v67
	s_and_saveexec_b64 s[18:19], s[54:55]
	s_cbranch_execz .LBB0_354
	s_and_b32 s1, s77, 0xffffff00
	s_add_i32 s1, s1, 0
	s_lshl_b32 s14, s79, 2
	s_add_i32 s1, s1, s14
	s_waitcnt lgkmcnt(0)
	v_add_f32_e32 v67, v67, v68
	v_lshl_add_u32 v68, v102, 2, s1
	ds_write_b32 v68, v67 offset:27136
.LBB0_354:
	s_or_b64 exec, exec, s[18:19]
	v_lshl_add_u32 v103, v105, 2, 0
	v_mul_u32_u24_e32 v116, 0x90, v66
	s_waitcnt lgkmcnt(0)
	s_barrier
	ds_read2st64_b32 v[66:67], v103 offset0:106 offset1:107
	v_lshlrev_b32_e32 v117, 16, v100
	v_and_b32_e32 v100, 0xffff0000, v100
	v_mul_f32_e32 v118, 0xbfb8aa3b, v117
	v_mul_f32_e32 v119, 0xbfb8aa3b, v100
	s_waitcnt lgkmcnt(0)
	v_add_f32_e32 v66, v66, v67
	v_fmamk_f32 v66, v66, 0x3c000000, v208
	v_cmp_gt_f32_e32 vcc, s89, v66
	v_mul_f32_e32 v67, 0x4b800000, v66
	v_exp_f32_e32 v118, v118
	v_cndmask_b32_e32 v66, v66, v67, vcc
	v_rsq_f32_e32 v66, v66
	v_exp_f32_e32 v119, v119
	v_readlane_b32 s14, v238, 21
	v_readlane_b32 s15, v238, 22
	v_mul_f32_e32 v67, 0x45800000, v66
	v_pk_add_f32 v[118:119], v[118:119], 1.0 op_sel_hi:[1,0]
	v_cndmask_b32_e32 v68, v66, v67, vcc
	v_or_b32_e32 v66, s14, v105
	v_pk_mul_f32 v[62:63], v[62:63], v[68:69] op_sel_hi:[1,0]
	v_ashrrev_i32_e32 v67, 31, v66
	v_pk_mul_f32 v[62:63], v[14:15], v[62:63]
	v_rcp_f32_e32 v120, v119
	s_nop 0
	v_mul_f32_e32 v119, v100, v120
	v_lshlrev_b64 v[66:67], 12, v[66:67]
	v_pk_mul_f32 v[64:65], v[64:65], v[68:69] op_sel_hi:[1,0]
	v_lshl_add_u64 v[66:67], s[56:57], 0, v[66:67]
	v_rcp_f32_e32 v100, v118
	s_nop 0
	v_mul_f32_e32 v118, v117, v100
	v_pk_mul_f32 v[62:63], v[118:119], v[62:63]
	v_lshlrev_b32_e32 v117, 16, v101
	v_and_b32_e32 v118, 0xffff0000, v101
	v_mul_f32_e32 v100, 0xbfb8aa3b, v117
	v_mul_f32_e32 v101, 0xbfb8aa3b, v118
	v_exp_f32_e32 v100, v100
	v_exp_f32_e32 v101, v101
	v_pk_mul_f32 v[64:65], v[16:17], v[64:65]
	v_lshl_add_u64 v[66:67], v[66:67], 0, s[2:3]
	v_cvt_pk_bf16_f32 v62, v62, v63
	v_pk_add_f32 v[100:101], v[100:101], 1.0 op_sel_hi:[1,0]
	v_pk_mul_f32 v[58:59], v[58:59], v[68:69] op_sel_hi:[1,0]
	v_pk_mul_f32 v[58:59], v[10:11], v[58:59]
	v_pk_mul_f32 v[60:61], v[60:61], v[68:69] op_sel_hi:[1,0]
	s_ashr_i32 s1, s0, 31
	v_rcp_f32_e32 v119, v101
	s_nop 0
	v_mul_f32_e32 v101, v118, v119
	v_pk_mul_f32 v[60:61], v[12:13], v[60:61]
	v_pk_mul_f32 v[54:55], v[54:55], v[68:69] op_sel_hi:[1,0]
	v_pk_mul_f32 v[56:57], v[56:57], v[68:69] op_sel_hi:[1,0]
	v_rcp_f32_e32 v118, v100
	s_nop 0
	v_mul_f32_e32 v100, v117, v118
	v_pk_mul_f32 v[64:65], v[100:101], v[64:65]
	v_pk_mul_f32 v[54:55], v[6:7], v[54:55]
	v_cvt_pk_bf16_f32 v63, v64, v65
	v_lshl_add_u64 v[64:65], v[90:91], 1, v[66:67]
	global_store_dwordx2 v[64:65], v[62:63], off offset:2048
	v_lshlrev_b32_e32 v64, 16, v98
	v_and_b32_e32 v65, 0xffff0000, v98
	v_mul_f32_e32 v62, 0xbfb8aa3b, v64
	v_mul_f32_e32 v63, 0xbfb8aa3b, v65
	v_exp_f32_e32 v62, v62
	v_exp_f32_e32 v63, v63
	v_pk_mul_f32 v[56:57], v[8:9], v[56:57]
	v_pk_mul_f32 v[50:51], v[50:51], v[68:69] op_sel_hi:[1,0]
	v_pk_mul_f32 v[52:53], v[52:53], v[68:69] op_sel_hi:[1,0]
	v_pk_add_f32 v[62:63], v[62:63], 1.0 op_sel_hi:[1,0]
	s_waitcnt vmcnt(13)
	v_pk_mul_f32 v[50:51], v[2:3], v[50:51]
	v_pk_mul_f32 v[52:53], v[4:5], v[52:53]
	v_rcp_f32_e32 v98, v63
	s_nop 0
	v_mul_f32_e32 v63, v65, v98
	s_nop 0
	v_rcp_f32_e32 v65, v62
	s_nop 0
	v_mul_f32_e32 v62, v64, v65
	v_lshlrev_b32_e32 v64, 16, v99
	v_and_b32_e32 v65, 0xffff0000, v99
	v_pk_mul_f32 v[58:59], v[62:63], v[58:59]
	v_mul_f32_e32 v62, 0xbfb8aa3b, v64
	v_mul_f32_e32 v63, 0xbfb8aa3b, v65
	v_exp_f32_e32 v62, v62
	v_exp_f32_e32 v63, v63
	s_nop 0
	v_pk_add_f32 v[62:63], v[62:63], 1.0 op_sel_hi:[1,0]
	s_nop 0
	s_nop 0
	v_rcp_f32_e32 v98, v63
	s_nop 0
	v_mul_f32_e32 v63, v65, v98
	s_nop 0
	v_rcp_f32_e32 v65, v62
	s_nop 0
	v_mul_f32_e32 v62, v64, v65
	v_pk_mul_f32 v[60:61], v[62:63], v[60:61]
	v_cvt_pk_bf16_f32 v62, v58, v59
	v_lshl_add_u64 v[58:59], s[0:1], 0, v[0:1]
	v_cvt_pk_bf16_f32 v63, v60, v61
	v_lshl_add_u64 v[60:61], v[58:59], 1, v[66:67]
	v_lshlrev_b32_e32 v0, 16, v96
	v_and_b32_e32 v64, 0xffff0000, v96
	global_store_dwordx2 v[60:61], v[62:63], off offset:2080
	v_mul_f32_e32 v62, 0xbfb8aa3b, v0
	v_mul_f32_e32 v63, 0xbfb8aa3b, v64
	v_exp_f32_e32 v62, v62
	v_exp_f32_e32 v63, v63
	s_nop 0
	v_pk_add_f32 v[62:63], v[62:63], 1.0 op_sel_hi:[1,0]
	s_nop 0
	s_nop 0
	v_rcp_f32_e32 v65, v63
	s_nop 0
	v_mul_f32_e32 v63, v64, v65
	s_nop 0
	v_rcp_f32_e32 v64, v62
	s_nop 0
	v_mul_f32_e32 v62, v0, v64
	v_lshlrev_b32_e32 v0, 16, v97
	v_and_b32_e32 v64, 0xffff0000, v97
	v_pk_mul_f32 v[54:55], v[62:63], v[54:55]
	v_mul_f32_e32 v62, 0xbfb8aa3b, v0
	v_mul_f32_e32 v63, 0xbfb8aa3b, v64
	v_exp_f32_e32 v62, v62
	v_exp_f32_e32 v63, v63
	v_cvt_pk_bf16_f32 v54, v54, v55
	v_pk_add_f32 v[62:63], v[62:63], 1.0 op_sel_hi:[1,0]
	s_nop 0
	s_nop 0
	v_rcp_f32_e32 v65, v63
	s_nop 0
	v_mul_f32_e32 v63, v64, v65
	s_nop 0
	v_rcp_f32_e32 v64, v62
	s_nop 0
	v_mul_f32_e32 v62, v0, v64
	v_pk_mul_f32 v[56:57], v[62:63], v[56:57]
	v_lshlrev_b32_e32 v0, 16, v94
	v_cvt_pk_bf16_f32 v55, v56, v57
	v_and_b32_e32 v56, 0xffff0000, v94
	global_store_dwordx2 v[60:61], v[54:55], off offset:2112
	v_mul_f32_e32 v54, 0xbfb8aa3b, v0
	v_mul_f32_e32 v55, 0xbfb8aa3b, v56
	v_exp_f32_e32 v54, v54
	v_exp_f32_e32 v55, v55
	s_nop 0
	v_pk_add_f32 v[54:55], v[54:55], 1.0 op_sel_hi:[1,0]
	s_nop 0
	s_nop 0
	v_rcp_f32_e32 v57, v55
	s_nop 0
	v_mul_f32_e32 v55, v56, v57
	s_nop 0
	v_rcp_f32_e32 v56, v54
	s_nop 0
	v_mul_f32_e32 v54, v0, v56
	v_lshlrev_b32_e32 v0, 16, v95
	v_and_b32_e32 v56, 0xffff0000, v95
	v_pk_mul_f32 v[50:51], v[54:55], v[50:51]
	v_mul_f32_e32 v54, 0xbfb8aa3b, v0
	v_mul_f32_e32 v55, 0xbfb8aa3b, v56
	v_exp_f32_e32 v54, v54
	v_exp_f32_e32 v55, v55
	v_cvt_pk_bf16_f32 v50, v50, v51
	v_pk_add_f32 v[54:55], v[54:55], 1.0 op_sel_hi:[1,0]
	s_nop 0
	s_nop 0
	v_rcp_f32_e32 v57, v55
	s_nop 0
	v_mul_f32_e32 v55, v56, v57
	v_div_scale_f32 v56, s[0:1], v54, v54, v0
	v_rcp_f32_e32 v57, v56
	s_mov_b32 s0, 0x3e000000
	s_waitcnt vmcnt(14)
	v_and_b32_e32 v63, 0xffff0000, v40
	v_fma_f32 v60, -v56, v57, 1.0
	v_fmac_f32_e32 v57, v60, v57
	v_div_scale_f32 v60, vcc, v0, v54, v0
	v_mul_f32_e32 v61, v60, v57
	v_fma_f32 v62, -v56, v61, v60
	v_fmac_f32_e32 v61, v62, v57
	v_fma_f32 v56, -v56, v61, v60
	v_div_fmas_f32 v56, v56, v57, v61
	v_div_fixup_f32 v54, v56, v54, v0
	v_pk_mul_f32 v[52:53], v[54:55], v[52:53]
	s_waitcnt vmcnt(11)
	v_mul_f32_e32 v0, 0x3fb8aa3b, v46
	v_cvt_pk_bf16_f32 v51, v52, v53
	v_lshl_add_u64 v[52:53], v[82:83], 1, v[66:67]
	global_store_dwordx2 v[52:53], v[50:51], off offset:2048
	v_exp_f32_e32 v50, v0
	v_mul_f32_e32 v0, 0xbfb8aa3b, v46
	v_exp_f32_e32 v46, v0
	v_mul_f32_e32 v0, 0x3fb8aa3b, v47
	v_exp_f32_e32 v51, v0
	v_mul_f32_e32 v0, 0xbfb8aa3b, v47
	v_exp_f32_e32 v47, v0
	v_lshlrev_b32_e32 v52, 16, v38
	v_and_b32_e32 v53, 0xffff0000, v38
	v_pk_mul_f32 v[52:53], v[52:53], s[0:1] op_sel_hi:[1,0]
	v_lshlrev_b32_e32 v56, 16, v30
	v_and_b32_e32 v57, 0xffff0000, v30
	v_mul_f32_e32 v0, 0x3fb8aa3b, v48
	v_pk_mul_f32 v[54:55], v[52:53], v[50:51]
	v_pk_mul_f32 v[52:53], v[52:53], v[46:47]
	v_pk_mul_f32 v[50:51], v[50:51], v[56:57]
	v_pk_mul_f32 v[46:47], v[46:47], v[56:57]
	v_exp_f32_e32 v56, v0
	v_mul_f32_e32 v0, 0xbfb8aa3b, v48
	v_exp_f32_e32 v48, v0
	v_mul_f32_e32 v0, 0x3fb8aa3b, v49
	v_exp_f32_e32 v57, v0
	v_mul_f32_e32 v0, 0xbfb8aa3b, v49
	v_exp_f32_e32 v49, v0
	v_lshlrev_b32_e32 v38, 16, v39
	v_and_b32_e32 v39, 0xffff0000, v39
	v_pk_mul_f32 v[38:39], v[38:39], s[0:1] op_sel_hi:[1,0]
	v_lshlrev_b32_e32 v30, 16, v31
	v_and_b32_e32 v31, 0xffff0000, v31
	v_mul_f32_e32 v0, 0x3fb8aa3b, v42
	v_pk_mul_f32 v[60:61], v[38:39], v[56:57]
	v_pk_mul_f32 v[38:39], v[38:39], v[48:49]
	v_pk_mul_f32 v[56:57], v[56:57], v[30:31]
	v_pk_mul_f32 v[48:49], v[48:49], v[30:31]
	v_exp_f32_e32 v30, v0
	v_mul_f32_e32 v0, 0xbfb8aa3b, v42
	v_exp_f32_e32 v42, v0
	v_mul_f32_e32 v0, 0x3fb8aa3b, v43
	v_exp_f32_e32 v31, v0
	v_mul_f32_e32 v0, 0xbfb8aa3b, v43
	v_lshlrev_b32_e32 v62, 16, v40
	v_exp_f32_e32 v43, v0
	v_pk_mul_f32 v[62:63], v[62:63], s[0:1] op_sel_hi:[1,0]
	v_lshlrev_b32_e32 v66, 16, v32
	v_and_b32_e32 v67, 0xffff0000, v32
	v_mul_f32_e32 v0, 0x3fb8aa3b, v44
	v_pk_mul_f32 v[64:65], v[62:63], v[30:31]
	v_pk_mul_f32 v[94:95], v[30:31], v[66:67]
	v_exp_f32_e32 v30, v0
	v_mul_f32_e32 v0, 0xbfb8aa3b, v44
	v_exp_f32_e32 v44, v0
	v_mul_f32_e32 v0, 0x3fb8aa3b, v45
	v_exp_f32_e32 v31, v0
	v_mul_f32_e32 v0, 0xbfb8aa3b, v45
	v_exp_f32_e32 v45, v0
	v_lshlrev_b32_e32 v40, 16, v41
	v_and_b32_e32 v41, 0xffff0000, v41
	v_pk_mul_f32 v[40:41], v[40:41], s[0:1] op_sel_hi:[1,0]
	v_pk_mul_f32 v[62:63], v[62:63], v[42:43]
	v_pk_mul_f32 v[42:43], v[42:43], v[66:67]
	v_pk_mul_f32 v[66:67], v[40:41], v[30:31]
	v_lshlrev_b32_e32 v32, 16, v33
	v_and_b32_e32 v33, 0xffff0000, v33
	v_pk_mul_f32 v[40:41], v[40:41], v[44:45]
	v_pk_mul_f32 v[96:97], v[30:31], v[32:33]
	v_pk_mul_f32 v[44:45], v[44:45], v[32:33]
	v_cvt_pk_bf16_f32 v30, v54, v55
	v_cvt_pk_bf16_f32 v31, v60, v61
	v_cvt_pk_bf16_f32 v32, v64, v65
	v_cvt_pk_bf16_f32 v33, v66, v67
	s_barrier
	ds_write_b128 v74, v[30:33] offset:27648
	v_cvt_pk_bf16_f32 v30, v52, v53
	v_cvt_pk_bf16_f32 v31, v38, v39
	v_cvt_pk_bf16_f32 v32, v62, v63
	v_cvt_pk_bf16_f32 v33, v40, v41
	ds_write_b128 v74, v[30:33] offset:36864
	v_cvt_pk_bf16_f32 v30, v50, v51
	v_cvt_pk_bf16_f32 v31, v56, v57
	v_cvt_pk_bf16_f32 v32, v94, v95
	v_cvt_pk_bf16_f32 v33, v96, v97
	ds_write_b128 v74, v[30:33] offset:46080
	v_cvt_pk_bf16_f32 v30, v46, v47
	v_cvt_pk_bf16_f32 v31, v48, v49
	v_cvt_pk_bf16_f32 v32, v42, v43
	v_cvt_pk_bf16_f32 v33, v44, v45
	ds_write_b128 v74, v[30:33] offset:55296
	s_waitcnt vmcnt(11)
	ds_write_b128 v75, v[18:21]
	s_waitcnt vmcnt(10)
	ds_write_b128 v76, v[22:25]
	s_waitcnt vmcnt(9)
	ds_write_b128 v77, v[26:29]
	s_waitcnt vmcnt(8)
	ds_write_b128 v78, v[34:37]
	s_waitcnt lgkmcnt(0)
	s_barrier
	ds_read_b128 v[18:21], v69 offset:27648
	v_add_u32_e32 v0, v70, v116
	ds_read_b128 v[22:25], v0 offset:55296
	s_waitcnt lgkmcnt(0)
	v_mfma_f32_16x16x32_bf16 v[18:21], v[18:21], v[22:25], 0
	ds_read_b128 v[22:25], v69 offset:36864
	ds_read_b128 v[26:29], v0 offset:46080
	s_waitcnt lgkmcnt(0)
	v_mfma_f32_16x16x32_bf16 v[22:25], v[22:25], v[26:29], 0
	ds_read_b128 v[26:29], v69 offset:27712
	ds_read_b128 v[30:33], v0 offset:55360
	s_waitcnt lgkmcnt(0)
	v_mfma_f32_16x16x32_bf16 v[18:21], v[26:29], v[30:33], v[18:21]
	ds_read_b128 v[26:29], v69 offset:36928
	ds_read_b128 v[30:33], v0 offset:46144
	s_waitcnt lgkmcnt(0)
	v_mfma_f32_16x16x32_bf16 v[22:25], v[26:29], v[30:33], v[22:25]
	s_nop 7
	v_cndmask_b32_e64 v18, v18, v22, s[38:39]
	v_cvt_pk_bf16_f32 v18, v18, s0
	ds_write_b16 v71, v18
	v_cndmask_b32_e64 v18, v19, v23, s[40:41]
	v_cvt_pk_bf16_f32 v18, v18, s0
	ds_write_b16 v71, v18 offset:144
	v_cndmask_b32_e64 v18, v20, v24, s[42:43]
	v_cvt_pk_bf16_f32 v18, v18, s0
	ds_write_b16 v71, v18 offset:288
	v_cndmask_b32_e64 v18, v21, v25, s[44:45]
	v_cvt_pk_bf16_f32 v18, v18, s0
	ds_write_b16 v71, v18 offset:432
	ds_read_b128 v[18:21], v69 offset:27648
	ds_read_b128 v[22:25], v0 offset:57600
	s_waitcnt lgkmcnt(0)
	v_mfma_f32_16x16x32_bf16 v[18:21], v[18:21], v[22:25], 0
	ds_read_b128 v[22:25], v69 offset:36864
	ds_read_b128 v[26:29], v0 offset:48384
	s_waitcnt lgkmcnt(0)
	v_mfma_f32_16x16x32_bf16 v[22:25], v[22:25], v[26:29], 0
	ds_read_b128 v[26:29], v69 offset:27712
	ds_read_b128 v[30:33], v0 offset:57664
	s_waitcnt lgkmcnt(0)
	v_mfma_f32_16x16x32_bf16 v[18:21], v[26:29], v[30:33], v[18:21]
	ds_read_b128 v[26:29], v69 offset:36928
	ds_read_b128 v[30:33], v0 offset:48448
	s_waitcnt lgkmcnt(0)
	v_mfma_f32_16x16x32_bf16 v[22:25], v[26:29], v[30:33], v[22:25]
	s_nop 7
	v_cndmask_b32_e64 v0, v18, v22, s[46:47]
	v_cvt_pk_bf16_f32 v0, v0, s0
	ds_write_b16 v79, v0
	v_cndmask_b32_e64 v0, v19, v23, s[48:49]
	v_cvt_pk_bf16_f32 v0, v0, s0
	ds_write_b16 v81, v0
	v_cndmask_b32_e64 v0, v20, v24, s[50:51]
	v_cvt_pk_bf16_f32 v0, v0, s0
	ds_write_b16 v104, v0
	v_cndmask_b32_e64 v0, v21, v25, s[52:53]
	v_cvt_pk_bf16_f32 v0, v0, s0
	ds_write_b16 v106, v0
	s_waitcnt lgkmcnt(0)
	s_barrier
	ds_read_b128 v[18:21], v107
	ds_read_b128 v[34:37], v73
	ds_read_b128 v[22:25], v80
	ds_read_b128 v[38:41], v72 offset:27648
	s_waitcnt lgkmcnt(2)
	v_mfma_f32_16x16x32_bf16 v[18:21], v[18:21], v[34:37], 0
	s_waitcnt lgkmcnt(0)
	v_mfma_f32_16x16x32_bf16 v[18:21], v[22:25], v[38:41], v[18:21]
	ds_read_b128 v[22:25], v107 offset:64
	ds_read_b128 v[42:45], v73 offset:64
	s_waitcnt lgkmcnt(0)
	v_mfma_f32_16x16x32_bf16 v[18:21], v[22:25], v[42:45], v[18:21]
	ds_read_b128 v[22:25], v80 offset:64
	ds_read_b128 v[46:49], v72 offset:27712
	s_waitcnt lgkmcnt(0)
	v_mfma_f32_16x16x32_bf16 v[30:33], v[22:25], v[46:49], v[18:21]
	ds_read_b128 v[22:25], v108
	s_nop 2
	ds_read_b128 v[18:21], v109
	s_waitcnt lgkmcnt(0)
	v_mfma_f32_16x16x32_bf16 v[18:21], v[18:21], v[34:37], 0
	s_nop 0
	v_mul_f32_e32 v0, v31, v31
	v_fmac_f32_e32 v0, v30, v30
	v_mfma_f32_16x16x32_bf16 v[18:21], v[22:25], v[38:41], v[18:21]
	ds_read_b128 v[22:25], v109 offset:64
	s_waitcnt lgkmcnt(0)
	v_mfma_f32_16x16x32_bf16 v[18:21], v[22:25], v[42:45], v[18:21]
	ds_read_b128 v[22:25], v108 offset:64
	s_waitcnt lgkmcnt(0)
	v_mfma_f32_16x16x32_bf16 v[26:29], v[22:25], v[46:49], v[18:21]
	s_nop 4
	ds_read_b128 v[18:21], v111
	ds_read_b128 v[22:25], v110
	s_waitcnt lgkmcnt(1)
	v_mfma_f32_16x16x32_bf16 v[18:21], v[18:21], v[34:37], 0
	s_waitcnt lgkmcnt(0)
	v_mfma_f32_16x16x32_bf16 v[18:21], v[22:25], v[38:41], v[18:21]
	ds_read_b128 v[22:25], v111 offset:64
	s_waitcnt lgkmcnt(0)
	v_mfma_f32_16x16x32_bf16 v[18:21], v[22:25], v[42:45], v[18:21]
	ds_read_b128 v[22:25], v110 offset:64
	s_waitcnt lgkmcnt(0)
	v_mfma_f32_16x16x32_bf16 v[22:25], v[22:25], v[46:49], v[18:21]
	s_nop 4
	ds_read_b128 v[18:21], v113
	s_waitcnt lgkmcnt(0)
	v_mfma_f32_16x16x32_bf16 v[18:21], v[18:21], v[34:37], 0
	ds_read_b128 v[34:37], v112
	s_waitcnt lgkmcnt(0)
	v_mfma_f32_16x16x32_bf16 v[18:21], v[34:37], v[38:41], v[18:21]
	ds_read_b128 v[34:37], v113 offset:64
	s_waitcnt lgkmcnt(0)
	v_mfma_f32_16x16x32_bf16 v[18:21], v[34:37], v[42:45], v[18:21]
	ds_read_b128 v[34:37], v112 offset:64
	s_waitcnt lgkmcnt(0)
	v_mfma_f32_16x16x32_bf16 v[18:21], v[34:37], v[46:49], v[18:21]
	v_mul_f32_e32 v34, v33, v33
	v_fmac_f32_e32 v34, v32, v32
	v_add_f32_e32 v0, v0, v34
	v_mul_f32_e32 v34, v27, v27
	v_mul_f32_e32 v35, v29, v29
	v_fmac_f32_e32 v34, v26, v26
	v_fmac_f32_e32 v35, v28, v28
	v_add_f32_e32 v34, v34, v35
	v_add_f32_e32 v0, v0, v34
	v_mul_f32_e32 v34, v23, v23
	v_mul_f32_e32 v35, v25, v25
	v_fmac_f32_e32 v34, v22, v22
	v_fmac_f32_e32 v35, v24, v24
	v_add_f32_e32 v34, v34, v35
	v_add_f32_e32 v0, v0, v34
	v_mul_f32_e32 v34, v19, v19
	v_mul_f32_e32 v35, v21, v21
	v_fmac_f32_e32 v34, v18, v18
	v_fmac_f32_e32 v35, v20, v20
	v_add_f32_e32 v34, v34, v35
	v_add_f32_e32 v0, v0, v34
	v_mov_b32_e32 v34, v0
	s_nop 1
	v_permlane16_swap_b32_e32 v34, v0
	s_waitcnt lgkmcnt(0)
	v_add_f32_e32 v0, v0, v34
	v_mov_b32_e32 v34, v0
	s_nop 1
	v_permlane32_swap_b32_e32 v34, v0
	s_and_saveexec_b64 s[0:1], s[54:55]
	s_cbranch_execz .LBB0_356
	s_and_b32 s14, s77, 0xffffff00
	s_add_i32 s14, s14, 0
	s_lshl_b32 s15, s79, 2
	s_add_i32 s14, s14, s15
	s_waitcnt lgkmcnt(0)
	v_add_f32_e32 v0, v0, v34
	v_lshl_add_u32 v34, v102, 2, s14
	ds_write_b32 v34, v0 offset:27136

.LBB0_394:
	s_add_i32 s24, s24, -1
	s_add_i32 s41, s41, 64
	v_subrev_u32_e32 v227, 64, v227
	v_add_u32_e32 v228, 64, v228
	v_add_u32_e32 v229, 64, v229
	v_add_u32_e32 v230, 64, v230
	s_cmp_lt_u32 s25, 9
	v_add_u32_e32 v231, 64, v231
	s_waitcnt lgkmcnt(0)
	s_cbranch_scc0 .Lband_exit
	v_mov_b32_e32 v233, v197
	v_mov_b32_e32 v232, v178
	s_cmp_lg_u32 s25, 8
	s_cselect_b64 s[18:19], -1, 0
	s_cbranch_scc0 .Lband_noload
	s_add_i32 s36, s23, s41
	s_ashr_i32 s37, s36, 31
	s_waitcnt vmcnt(1)
	v_lshl_add_u64 v[130:131], s[36:37], 1, v[202:203]
	v_add_u32_e32 v86, s23, v231
	v_add_u32_e32 v94, s23, v230
	v_mov_b32_e32 v197, v1
	v_add_u32_e32 v118, s23, v229
	v_mov_b32_e32 v199, v1
	v_add_u32_e32 v132, s23, v228
	v_mov_b32_e32 v201, v1
	v_mad_i64_i32 v[86:87], s[36:37], v86, s59, v[194:195]
	v_lshl_add_u64 v[90:91], v[130:131], 0, v[0:1]
	v_mad_i64_i32 v[94:95], s[36:37], v94, s59, v[194:195]
	v_lshl_add_u64 v[98:99], v[130:131], 0, v[196:197]
	v_mad_i64_i32 v[118:119], s[36:37], v118, s59, v[194:195]
	v_lshl_add_u64 v[122:123], v[130:131], 0, v[198:199]
	v_mad_i64_i32 v[132:133], s[36:37], v132, s59, v[194:195]
	s_waitcnt vmcnt(0)
	v_lshl_add_u64 v[134:135], v[130:131], 0, v[200:201]
	global_load_dwordx4 v[86:89], v[86:87], off offset:2048
	s_nop 0
	global_load_dwordx4 v[90:93], v[90:91], off
	s_nop 0
	global_load_dwordx4 v[94:97], v[94:95], off offset:2048
	s_nop 0
	global_load_dwordx4 v[98:101], v[98:99], off
	s_nop 0
	global_load_dwordx4 v[118:121], v[118:119], off offset:2048
	s_nop 0
	global_load_dwordx4 v[122:125], v[122:123], off
	s_nop 0
	global_load_dwordx4 v[130:133], v[132:133], off offset:2048
	s_nop 0
	global_load_dwordx4 v[134:137], v[134:135], off
.Lband_noload:
	s_barrier
	s_branch .LBB0_382

.LBB0_402:
	v_sub_f32_e32 v17, v17, v15
	v_sub_f32_e32 v16, v16, v15
	v_exp_f32_e32 v68, v17
	v_exp_f32_e32 v17, v16
	v_sub_f32_e32 v16, v27, v15
	v_exp_f32_e32 v153, v16
	v_sub_f32_e32 v16, v26, v15
	v_exp_f32_e32 v151, v16
	v_sub_f32_e32 v16, v25, v15
	v_exp_f32_e32 v149, v16
	v_sub_f32_e32 v16, v24, v15
	v_exp_f32_e32 v147, v16
	v_sub_f32_e32 v16, v23, v15
	v_exp_f32_e32 v145, v16
	v_sub_f32_e32 v16, v22, v15
	v_sub_f32_e32 v7, v7, v15
	v_exp_f32_e32 v143, v16
	v_exp_f32_e32 v155, v7
	v_sub_f32_e32 v7, v19, v15
	v_exp_f32_e32 v135, v7
	v_sub_f32_e32 v7, v18, v15
	v_exp_f32_e32 v133, v7
	v_sub_f32_e32 v7, v9, v15
	v_sub_f32_e32 v16, v21, v15
	v_exp_f32_e32 v131, v7
	v_sub_f32_e32 v7, v8, v15
	v_exp_f32_e32 v141, v16
	v_sub_f32_e32 v16, v20, v15
	v_exp_f32_e32 v129, v7
	v_cvt_pk_bf16_f32 v34, v143, v145
	v_cvt_pk_bf16_f32 v35, v147, v149
	v_cvt_pk_bf16_f32 v36, v151, v153
	v_cvt_pk_bf16_f32 v37, v17, v68
	v_mov_b32_e32 v7, v1
	v_exp_f32_e32 v139, v16
	v_sub_f32_e32 v6, v6, v15
	v_add_u32_e32 v16, v93, v7
	v_add_u32_e32 v69, 0xd000, v16
	ds_read2_b64 v[18:21], v69 offset1:4
	v_exp_f32_e32 v137, v6
	ds_read2_b64 v[6:9], v69 offset0:8 offset1:12
	v_cvt_pk_bf16_f32 v62, v129, v131
	v_cvt_pk_bf16_f32 v63, v133, v135
	v_cvt_pk_bf16_f32 v64, v137, v155
	v_cvt_pk_bf16_f32 v65, v139, v141
	v_add_u32_e32 v15, 0xd800, v16
	v_add_f32_e32 v0, 0, v0
	s_waitcnt lgkmcnt(1)
	v_mfma_f32_16x16x32_bf16 v[2:5], v[18:21], v[62:65], v[2:5]
	ds_read2_b64 v[18:21], v15 offset0:32 offset1:36
	v_add_f32_e32 v0, v156, v0
	s_add_u32 s18, s40, s47
	s_waitcnt lgkmcnt(1)
	v_mfma_f32_16x16x32_bf16 v[30:33], v[6:9], v[34:37], v[2:5]
	v_mad_i64_i32 v[66:67], s[14:15], v90, s59, 0
	s_addc_u32 s19, s41, 0
	s_nop 0
	ds_read2_b64 v[2:5], v15 offset0:40 offset1:44
	v_add_u32_e32 v15, 0xe000, v16
	s_waitcnt lgkmcnt(1)
	v_mfma_f32_16x16x32_bf16 v[6:9], v[18:21], v[62:65], v[58:61]
	ds_read2_b64 v[18:21], v15 offset0:64 offset1:68
	v_mov_b32_e32 v93, v1
	v_readlane_b32 s6, v236, 9
	s_waitcnt lgkmcnt(1)
	v_mfma_f32_16x16x32_bf16 v[26:29], v[2:5], v[34:37], v[6:9]
	ds_read2_b64 v[2:5], v15 offset0:72 offset1:76
	v_add_u32_e32 v15, 0xe800, v16
	v_readlane_b32 s7, v236, 10
	s_waitcnt lgkmcnt(1)
	v_mfma_f32_16x16x32_bf16 v[6:9], v[18:21], v[62:65], v[54:57]
	ds_read2_b64 v[18:21], v15 offset0:96 offset1:100
	s_waitcnt lgkmcnt(1)
	v_mfma_f32_16x16x32_bf16 v[22:25], v[2:5], v[34:37], v[6:9]
	ds_read2_b64 v[2:5], v15 offset0:104 offset1:108
	v_add_u32_e32 v15, 0xf000, v16
	s_waitcnt lgkmcnt(1)
	v_mfma_f32_16x16x32_bf16 v[6:9], v[18:21], v[62:65], v[50:53]
	s_nop 2
	ds_read2_b64 v[50:53], v15 offset0:128 offset1:132
	s_waitcnt lgkmcnt(1)
	v_mfma_f32_16x16x32_bf16 v[18:21], v[2:5], v[34:37], v[6:9]
	ds_read2_b64 v[2:5], v15 offset0:136 offset1:140
	v_add_u32_e32 v15, 0xf800, v16
	s_waitcnt lgkmcnt(1)
	v_mfma_f32_16x16x32_bf16 v[6:9], v[50:53], v[62:65], v[46:49]
	s_nop 2
	ds_read2_b64 v[46:49], v15 offset0:160 offset1:164
	ds_read2_b64 v[50:53], v15 offset0:168 offset1:172
	v_add_u32_e32 v15, 0x3000, v69
	s_waitcnt lgkmcnt(2)
	v_mfma_f32_16x16x32_bf16 v[6:9], v[2:5], v[34:37], v[6:9]
	s_waitcnt lgkmcnt(1)
	v_mfma_f32_16x16x32_bf16 v[2:5], v[46:49], v[62:65], v[42:45]
	ds_read2_b64 v[46:49], v15 offset0:192 offset1:196
	ds_read2_b64 v[54:57], v15 offset0:200 offset1:204
	v_add_u32_e32 v15, 0x3800, v69
	v_lshl_add_u64 v[42:43], s[18:19], 0, v[66:67]
	s_waitcnt lgkmcnt(1)
	v_mfma_f32_16x16x32_bf16 v[38:41], v[46:49], v[62:65], v[38:41]
	v_add_f32_e64 v46, v110, v0
	v_add_f32_e64 v47, v111, v1
	v_lshl_add_u64 v[42:43], v[42:43], 0, v[92:93]
	v_pk_add_f32 v[46:47], v[112:113], v[46:47]
	v_mfma_f32_16x16x32_bf16 v[2:5], v[50:53], v[34:37], v[2:5]
	v_add_f32_e64 v46, v114, v46
	v_add_f32_e64 v47, v115, v47
	ds_read2_b64 v[50:53], v15 offset0:224 offset1:228
	ds_read2_b64 v[58:61], v15 offset0:232 offset1:236
	v_pk_add_f32 v[46:47], v[116:117], v[46:47]
	global_load_dwordx2 v[44:45], v[42:43], off nt
	s_waitcnt lgkmcnt(0)
	s_barrier
	v_pk_add_f32 v[46:47], v[118:119], v[46:47]
	v_mfma_f32_16x16x32_bf16 v[10:13], v[50:53], v[62:65], v[10:13]
	v_add_f32_e64 v46, v122, v46
	v_add_f32_e64 v47, v123, v47
	s_add_u32 s18, s42, s47
	v_pk_add_f32 v[46:47], v[94:95], v[46:47]
	v_mfma_f32_16x16x32_bf16 v[10:13], v[58:61], v[34:37], v[10:13]
	v_add_f32_e64 v46, v96, v46
	v_add_f32_e64 v47, v97, v47
	s_addc_u32 s19, s43, 0
	v_pk_add_f32 v[46:47], v[98:99], v[46:47]
	s_add_i32 s46, s46, s6
	v_pk_add_f32 v[46:47], v[100:101], v[46:47]
	s_add_i32 s45, s45, s35
	v_pk_add_f32 v[46:47], v[102:103], v[46:47]
	s_add_i32 s44, s44, s30
	v_pk_add_f32 v[46:47], v[104:105], v[46:47]
	s_cmpk_gt_i32 s46, 0xff
	v_pk_add_f32 v[46:47], v[106:107], v[46:47]
	s_waitcnt vmcnt(0)
	v_lshlrev_b32_e32 v49, 16, v44
	v_pk_add_f32 v[46:47], v[108:109], v[46:47]
	v_and_b32_e32 v44, 0xffff0000, v44
	v_pk_add_f32 v[46:47], v[120:121], v[46:47]
	s_nop 0
	v_add_f32_e32 v0, v47, v157
	v_fmac_f32_e32 v0, v46, v124
	v_mul_f32_e32 v16, v0, v126
	v_add_f32_e32 v0, 0, v127
	v_add_f32_e32 v0, v158, v0
	v_pk_add_f32 v[46:47], v[128:129], v[0:1]
	s_nop 0
	v_pk_add_f32 v[46:47], v[130:131], v[46:47]
	s_nop 0
	v_pk_add_f32 v[46:47], v[132:133], v[46:47]
	s_nop 0
	v_pk_add_f32 v[46:47], v[134:135], v[46:47]
	s_nop 0
	v_pk_add_f32 v[46:47], v[136:137], v[46:47]
	s_nop 0
	v_pk_add_f32 v[46:47], v[154:155], v[46:47]
	s_nop 0
	v_pk_add_f32 v[46:47], v[138:139], v[46:47]
	s_nop 0
	v_pk_add_f32 v[46:47], v[140:141], v[46:47]
	s_nop 0
	v_pk_add_f32 v[46:47], v[142:143], v[46:47]
	s_nop 0
	v_pk_add_f32 v[46:47], v[144:145], v[46:47]
	s_nop 0
	v_pk_add_f32 v[46:47], v[146:147], v[46:47]
	s_nop 0
	v_pk_add_f32 v[46:47], v[148:149], v[46:47]
	s_nop 0
	v_pk_add_f32 v[46:47], v[150:151], v[46:47]
	s_nop 0
	v_pk_add_f32 v[46:47], v[152:153], v[46:47]
	s_nop 0
	v_pk_add_f32 v[16:17], v[16:17], v[46:47]
	s_nop 0
	v_add_f32_e32 v0, v17, v68
	v_fmac_f32_e32 v0, v16, v14
	v_mov_b32_e32 v46, v0
	s_nop 1
	v_permlane16_swap_b32_e32 v46, v0
	v_mfma_f32_16x16x32_bf16 v[14:17], v[54:57], v[34:37], v[38:41]
	v_and_b32_e32 v54, 0xffff0000, v45
	v_ashrrev_i32_e32 v91, 31, v90
	s_waitcnt lgkmcnt(0)
	v_add_f32_e32 v0, v0, v46
	v_mov_b32_e32 v38, v0
	s_nop 1
	v_permlane32_swap_b32_e32 v38, v0
	v_mul_f32_e32 v40, 0xbfb8aa3b, v49
	v_mul_f32_e32 v41, 0xbfb8aa3b, v44
	v_exp_f32_e32 v40, v40
	v_exp_f32_e32 v41, v41
	s_waitcnt lgkmcnt(0)
	v_add_f32_e32 v0, v0, v38
	v_div_scale_f32 v38, s[14:15], v0, v0, 1.0
	v_rcp_f32_e32 v46, v38
	v_pk_add_f32 v[40:41], v[40:41], 1.0 op_sel_hi:[1,0]
	v_fma_f32 v34, -v38, v46, 1.0
	v_fmac_f32_e32 v46, v34, v46
	v_div_scale_f32 v34, vcc, 1.0, v0, 1.0
	v_mul_f32_e32 v47, v34, v46
	v_fma_f32 v35, -v38, v47, v34
	v_fmac_f32_e32 v47, v35, v46
	v_fma_f32 v48, -v38, v47, v34
	global_load_dwordx2 v[36:37], v[42:43], off offset:32 nt
	global_load_dwordx2 v[38:39], v[42:43], off offset:64 nt
	global_load_dwordx2 v[34:35], v[42:43], off offset:96 nt
	v_div_fmas_f32 v46, v48, v46, v47
	v_div_scale_f32 v48, s[14:15], v41, v41, v44
	v_rcp_f32_e32 v50, v48
	v_div_fixup_f32 v0, v46, v0, 1.0
	v_pk_mul_f32 v[30:31], v[30:31], v[0:1] op_sel_hi:[1,0]
	v_pk_mul_f32 v[32:33], v[32:33], v[0:1] op_sel_hi:[1,0]
	v_fma_f32 v51, -v48, v50, 1.0
	v_fmac_f32_e32 v50, v51, v50
	v_div_scale_f32 v51, vcc, v44, v41, v44
	v_mul_f32_e32 v52, v51, v50
	v_fma_f32 v53, -v48, v52, v51
	v_fmac_f32_e32 v52, v53, v50
	v_fma_f32 v48, -v48, v52, v51
	v_div_fmas_f32 v48, v48, v50, v52
	v_div_fixup_f32 v41, v48, v41, v44
	v_lshlrev_b32_e32 v52, 16, v45
	v_mul_f32_e32 v44, 0xbfb8aa3b, v52
	v_mul_f32_e32 v45, 0xbfb8aa3b, v54
	v_exp_f32_e32 v44, v44
	v_exp_f32_e32 v45, v45
	v_rcp_f32_e32 v48, v40
	s_nop 0
	v_mul_f32_e32 v40, v49, v48
	v_pk_add_f32 v[44:45], v[44:45], 1.0 op_sel_hi:[1,0]
	v_pk_mul_f32 v[30:31], v[30:31], v[40:41]
	v_lshlrev_b64 v[46:47], 12, v[90:91]
	v_lshl_add_u64 v[46:47], s[18:19], 0, v[46:47]
	v_pk_mul_f32 v[26:27], v[26:27], v[0:1] op_sel_hi:[1,0]
	v_rcp_f32_e32 v40, v45
	s_nop 0
	v_mul_f32_e32 v41, v54, v40
	v_rcp_f32_e32 v40, v44
	s_nop 0
	v_mul_f32_e32 v40, v52, v40
	v_pk_mul_f32 v[32:33], v[32:33], v[40:41]
	v_cvt_pk_bf16_f32 v40, v30, v31
	v_cvt_pk_bf16_f32 v41, v32, v33
	v_lshl_add_u64 v[30:31], v[46:47], 0, v[92:93]
	global_store_dwordx2 v[30:31], v[40:41], off
	v_pk_mul_f32 v[28:29], v[28:29], v[0:1] op_sel_hi:[1,0]
	v_pk_mul_f32 v[22:23], v[22:23], v[0:1] op_sel_hi:[1,0]
	v_pk_mul_f32 v[24:25], v[24:25], v[0:1] op_sel_hi:[1,0]
	v_pk_mul_f32 v[20:21], v[20:21], v[0:1] op_sel_hi:[1,0]
	v_pk_mul_f32 v[6:7], v[6:7], v[0:1] op_sel_hi:[1,0]
	v_pk_mul_f32 v[8:9], v[8:9], v[0:1] op_sel_hi:[1,0]
	s_waitcnt vmcnt(3)
	v_lshlrev_b32_e32 v48, 16, v36
	v_and_b32_e32 v36, 0xffff0000, v36
	v_mul_f32_e32 v44, 0xbfb8aa3b, v48
	v_mul_f32_e32 v45, 0xbfb8aa3b, v36
	v_exp_f32_e32 v44, v44
	v_exp_f32_e32 v45, v45
	v_and_b32_e32 v47, 0xffff0000, v37
	v_pk_mul_f32 v[2:3], v[2:3], v[0:1] op_sel_hi:[1,0]
	v_pk_mul_f32 v[4:5], v[4:5], v[0:1] op_sel_hi:[1,0]
	v_pk_add_f32 v[32:33], v[44:45], 1.0 op_sel_hi:[1,0]
	s_nop 0
	s_nop 0
	v_rcp_f32_e32 v40, v33
	s_nop 0
	v_mul_f32_e32 v33, v36, v40
	v_lshlrev_b32_e32 v45, 16, v37
	v_mul_f32_e32 v36, 0xbfb8aa3b, v45
	v_mul_f32_e32 v37, 0xbfb8aa3b, v47
	v_exp_f32_e32 v36, v36
	v_exp_f32_e32 v37, v37
	v_rcp_f32_e32 v40, v32
	s_nop 0
	v_mul_f32_e32 v32, v48, v40
	v_pk_add_f32 v[36:37], v[36:37], 1.0 op_sel_hi:[1,0]
	v_pk_mul_f32 v[26:27], v[26:27], v[32:33]
	v_cvt_pk_bf16_f32 v26, v26, v27
	v_rcp_f32_e32 v32, v37
	s_nop 0
	v_mul_f32_e32 v33, v47, v32
	s_waitcnt vmcnt(2)
	v_lshlrev_b32_e32 v37, 16, v38
	v_and_b32_e32 v38, 0xffff0000, v38
	v_mul_f32_e32 v40, 0xbfb8aa3b, v37
	v_mul_f32_e32 v41, 0xbfb8aa3b, v38
	v_exp_f32_e32 v40, v40
	v_exp_f32_e32 v41, v41
	v_rcp_f32_e32 v32, v36
	s_nop 0
	v_mul_f32_e32 v32, v45, v32
	v_pk_mul_f32 v[28:29], v[28:29], v[32:33]
	v_pk_add_f32 v[32:33], v[40:41], 1.0 op_sel_hi:[1,0]
	s_nop 0
	v_cvt_pk_bf16_f32 v27, v28, v29
	global_store_dwordx2 v[30:31], v[26:27], off offset:32
	v_rcp_f32_e32 v26, v33
	s_nop 0
	v_mul_f32_e32 v27, v38, v26
	v_lshlrev_b32_e32 v38, 16, v39
	v_and_b32_e32 v39, 0xffff0000, v39
	v_mul_f32_e32 v28, 0xbfb8aa3b, v38
	v_mul_f32_e32 v29, 0xbfb8aa3b, v39
	v_exp_f32_e32 v28, v28
	v_exp_f32_e32 v29, v29
	v_rcp_f32_e32 v26, v32
	s_nop 0
	v_mul_f32_e32 v26, v37, v26
	v_pk_add_f32 v[28:29], v[28:29], 1.0 op_sel_hi:[1,0]
	v_pk_mul_f32 v[26:27], v[22:23], v[26:27]
	s_waitcnt vmcnt(2)
	v_lshlrev_b32_e32 v37, 16, v34
	v_and_b32_e32 v34, 0xffff0000, v34
	v_cvt_pk_bf16_f32 v26, v26, v27
	v_rcp_f32_e32 v22, v29
	s_nop 0
	v_mul_f32_e32 v29, v39, v22
	global_load_dwordx2 v[22:23], v[42:43], off offset:128 nt
	v_mul_f32_e32 v32, 0xbfb8aa3b, v37
	v_mul_f32_e32 v33, 0xbfb8aa3b, v34
	v_exp_f32_e32 v32, v32
	v_exp_f32_e32 v33, v33
	v_rcp_f32_e32 v36, v28
	s_nop 0
	v_mul_f32_e32 v28, v38, v36
	v_pk_mul_f32 v[24:25], v[24:25], v[28:29]
	v_lshlrev_b32_e32 v36, 16, v35
	v_pk_add_f32 v[28:29], v[32:33], 1.0 op_sel_hi:[1,0]
	v_cvt_pk_bf16_f32 v27, v24, v25
	v_pk_mul_f32 v[24:25], v[18:19], v[0:1] op_sel_hi:[1,0]
	global_store_dwordx2 v[30:31], v[26:27], off offset:64
	v_rcp_f32_e32 v18, v29
	s_nop 0
	v_mul_f32_e32 v27, v34, v18
	v_and_b32_e32 v34, 0xffff0000, v35
	v_mul_f32_e32 v18, 0xbfb8aa3b, v36
	v_mul_f32_e32 v19, 0xbfb8aa3b, v34
	v_exp_f32_e32 v18, v18
	v_exp_f32_e32 v19, v19
	v_rcp_f32_e32 v26, v28
	s_nop 0
	v_mul_f32_e32 v26, v37, v26
	v_pk_add_f32 v[18:19], v[18:19], 1.0 op_sel_hi:[1,0]
	v_pk_mul_f32 v[24:25], v[24:25], v[26:27]
	s_waitcnt vmcnt(1)
	v_lshlrev_b32_e32 v38, 16, v22
	v_rcp_f32_e32 v26, v19
	s_nop 0
	v_mul_f32_e32 v19, v34, v26
	v_and_b32_e32 v22, 0xffff0000, v22
	global_load_dwordx2 v[26:27], v[42:43], off offset:160 nt
	global_load_dwordx2 v[28:29], v[42:43], off offset:192 nt
	global_load_dwordx2 v[32:33], v[42:43], off offset:224 nt
	v_mul_f32_e32 v34, 0xbfb8aa3b, v38
	v_mul_f32_e32 v35, 0xbfb8aa3b, v22
	v_exp_f32_e32 v34, v34
	v_exp_f32_e32 v35, v35
	v_rcp_f32_e32 v37, v18
	s_nop 0
	v_mul_f32_e32 v18, v36, v37
	v_pk_mul_f32 v[18:19], v[20:21], v[18:19]
	v_cvt_pk_bf16_f32 v20, v24, v25
	v_pk_add_f32 v[24:25], v[34:35], 1.0 op_sel_hi:[1,0]
	v_cvt_pk_bf16_f32 v21, v18, v19
	global_store_dwordx2 v[30:31], v[20:21], off offset:96
	v_rcp_f32_e32 v18, v25
	s_nop 0
	v_mul_f32_e32 v19, v22, v18
	v_lshlrev_b32_e32 v25, 16, v23
	v_and_b32_e32 v23, 0xffff0000, v23
	v_mul_f32_e32 v20, 0xbfb8aa3b, v25
	v_mul_f32_e32 v21, 0xbfb8aa3b, v23
	v_exp_f32_e32 v20, v20
	v_exp_f32_e32 v21, v21
	v_rcp_f32_e32 v18, v24
	s_nop 0
	v_mul_f32_e32 v18, v38, v18
	v_pk_add_f32 v[20:21], v[20:21], 1.0 op_sel_hi:[1,0]
	v_pk_mul_f32 v[6:7], v[6:7], v[18:19]
	v_cvt_pk_bf16_f32 v6, v6, v7
	v_rcp_f32_e32 v18, v21
	s_nop 0
	v_mul_f32_e32 v19, v23, v18
	v_rcp_f32_e32 v18, v20
	s_nop 0
	v_mul_f32_e32 v18, v25, v18
	v_pk_mul_f32 v[8:9], v[8:9], v[18:19]
	s_waitcnt vmcnt(3)
	v_lshlrev_b32_e32 v21, 16, v26
	v_and_b32_e32 v24, 0xffff0000, v26
	v_mul_f32_e32 v22, 0xbfb8aa3b, v21
	v_mul_f32_e32 v23, 0xbfb8aa3b, v24
	v_exp_f32_e32 v22, v22
	v_exp_f32_e32 v23, v23
	v_cvt_pk_bf16_f32 v7, v8, v9
	global_store_dwordx2 v[30:31], v[6:7], off offset:128
	v_pk_add_f32 v[18:19], v[22:23], 1.0 op_sel_hi:[1,0]
	s_nop 0
	s_nop 0
	v_rcp_f32_e32 v6, v19
	s_nop 0
	v_mul_f32_e32 v7, v24, v6
	v_lshlrev_b32_e32 v22, 16, v27
	v_and_b32_e32 v24, 0xffff0000, v27
	v_mul_f32_e32 v8, 0xbfb8aa3b, v22
	v_mul_f32_e32 v9, 0xbfb8aa3b, v24
	v_exp_f32_e32 v8, v8
	v_exp_f32_e32 v9, v9
	v_rcp_f32_e32 v6, v18
	s_nop 0
	v_mul_f32_e32 v6, v21, v6
	v_pk_add_f32 v[8:9], v[8:9], 1.0 op_sel_hi:[1,0]
	v_pk_mul_f32 v[2:3], v[2:3], v[6:7]
	v_cvt_pk_bf16_f32 v2, v2, v3
	v_rcp_f32_e32 v6, v9
	s_nop 0
	v_mul_f32_e32 v7, v24, v6
	s_waitcnt vmcnt(3)
	v_lshlrev_b32_e32 v20, 16, v28
	v_and_b32_e32 v9, 0xffff0000, v28
	v_mul_f32_e32 v18, 0xbfb8aa3b, v20
	v_mul_f32_e32 v19, 0xbfb8aa3b, v9
	v_exp_f32_e32 v18, v18
	v_exp_f32_e32 v19, v19
	v_rcp_f32_e32 v6, v8
	s_nop 0
	v_mul_f32_e32 v6, v22, v6
	v_pk_mul_f32 v[4:5], v[4:5], v[6:7]
	v_pk_add_f32 v[6:7], v[18:19], 1.0 op_sel_hi:[1,0]
	s_nop 0
	v_cvt_pk_bf16_f32 v3, v4, v5
	global_store_dwordx2 v[30:31], v[2:3], off offset:160
	v_pk_mul_f32 v[2:3], v[14:15], v[0:1] op_sel_hi:[1,0]
	v_rcp_f32_e32 v4, v7
	s_nop 0
	v_mul_f32_e32 v5, v9, v4
	v_lshlrev_b32_e32 v18, 16, v29
	v_and_b32_e32 v19, 0xffff0000, v29
	v_mul_f32_e32 v8, 0xbfb8aa3b, v18
	v_mul_f32_e32 v9, 0xbfb8aa3b, v19
	v_exp_f32_e32 v8, v8
	v_exp_f32_e32 v9, v9
	v_rcp_f32_e32 v4, v6
	s_nop 0
	v_mul_f32_e32 v4, v20, v4
	v_pk_add_f32 v[8:9], v[8:9], 1.0 op_sel_hi:[1,0]
	v_pk_mul_f32 v[2:3], v[2:3], v[4:5]
	v_pk_mul_f32 v[4:5], v[16:17], v[0:1] op_sel_hi:[1,0]
	v_cvt_pk_bf16_f32 v2, v2, v3
	v_rcp_f32_e32 v6, v9
	s_nop 0
	v_mul_f32_e32 v7, v19, v6
	s_waitcnt vmcnt(3)
	v_lshlrev_b32_e32 v16, 16, v32
	v_and_b32_e32 v9, 0xffff0000, v32
	v_mul_f32_e32 v14, 0xbfb8aa3b, v16
	v_mul_f32_e32 v15, 0xbfb8aa3b, v9
	v_exp_f32_e32 v14, v14
	v_exp_f32_e32 v15, v15
	v_rcp_f32_e32 v6, v8
	s_nop 0
	v_mul_f32_e32 v6, v18, v6
	v_pk_mul_f32 v[4:5], v[4:5], v[6:7]
	v_pk_add_f32 v[6:7], v[14:15], 1.0 op_sel_hi:[1,0]
	s_nop 0
	v_cvt_pk_bf16_f32 v3, v4, v5
	global_store_dwordx2 v[30:31], v[2:3], off offset:192
	v_pk_mul_f32 v[2:3], v[10:11], v[0:1] op_sel_hi:[1,0]
	v_rcp_f32_e32 v4, v7
	s_nop 0
	v_mul_f32_e32 v5, v9, v4
	v_lshlrev_b32_e32 v14, 16, v33
	v_and_b32_e32 v15, 0xffff0000, v33
	v_mul_f32_e32 v8, 0xbfb8aa3b, v14
	v_mul_f32_e32 v9, 0xbfb8aa3b, v15
	v_exp_f32_e32 v8, v8
	v_exp_f32_e32 v9, v9
	v_rcp_f32_e32 v4, v6
	s_nop 0
	v_mul_f32_e32 v4, v16, v4
	v_pk_add_f32 v[8:9], v[8:9], 1.0 op_sel_hi:[1,0]
	v_pk_mul_f32 v[2:3], v[2:3], v[4:5]
	v_pk_mul_f32 v[4:5], v[12:13], v[0:1] op_sel_hi:[1,0]
	v_cvt_pk_bf16_f32 v2, v2, v3
	v_rcp_f32_e32 v0, v9
	s_nop 0
	v_mul_f32_e32 v7, v15, v0
	v_rcp_f32_e32 v0, v8
	s_nop 0
	v_mul_f32_e32 v6, v14, v0
	v_pk_mul_f32 v[4:5], v[4:5], v[6:7]
	s_nop 0
	v_cvt_pk_bf16_f32 v3, v4, v5
	global_store_dwordx2 v[30:31], v[2:3], off offset:224
	s_cbranch_scc1 .LBB0_409
.LBB0_403:
	s_and_b32 s18, s44, 0x180
	s_and_b32 s24, s45, 0xffffff80
	s_lshl_b32 s47, s18, 1
	s_add_u32 s14, s2, s47
	s_addc_u32 s15, s36, 0
	s_add_u32 s22, s1, s47
	s_addc_u32 s23, s37, 0
	s_or_b32 s18, s18, s0
	s_ashr_i32 s19, s18, 31
	s_lshl_b64 s[18:19], s[18:19], 9
	v_mov_b32_e32 v0, v204
	s_add_u32 s18, s38, s18
	s_addc_u32 s19, s39, s19
	v_lshlrev_b32_e32 v4, 4, v0
	v_ashrrev_i32_e32 v12, 4, v0
	v_ashrrev_i32_e32 v14, 3, v0
	v_and_b32_e32 v10, 0xf0, v4
	v_mov_b32_e32 v11, v1
	v_and_b32_e32 v18, 0x70, v4
	v_mov_b32_e32 v19, v1
	v_ashrrev_i32_e32 v13, 31, v12
	v_ashrrev_i32_e32 v15, 31, v14
	v_add_u32_e32 v8, 0x200, v0
	v_lshl_add_u64 v[2:3], s[22:23], 0, v[10:11]
	v_lshl_add_u64 v[4:5], s[18:19], 0, v[18:19]
	v_lshlrev_b64 v[6:7], 12, v[12:13]
	v_lshlrev_b64 v[20:21], 9, v[14:15]
	v_ashrrev_i32_e32 v16, 4, v8
	v_lshl_add_u64 v[54:55], v[2:3], 0, v[6:7]
	v_lshl_add_u64 v[6:7], v[4:5], 0, v[20:21]
	v_ashrrev_i32_e32 v17, 31, v16
	v_ashrrev_i32_e32 v22, 3, v8
	global_load_dwordx4 v[34:37], v[54:55], off
	global_load_dwordx4 v[38:41], v[6:7], off
	v_lshlrev_b64 v[6:7], 12, v[16:17]
	v_ashrrev_i32_e32 v23, 31, v22
	v_lshl_add_u64 v[56:57], v[2:3], 0, v[6:7]
	v_lshlrev_b64 v[24:25], 9, v[22:23]
	v_readfirstlane_b32 s22, v0
	v_lshl_add_u64 v[2:3], v[4:5], 0, v[24:25]
	global_load_dwordx4 v[42:45], v[56:57], off
	global_load_dwordx4 v[46:49], v[2:3], off
	v_and_b32_e32 v66, 15, v0
	s_ashr_i32 s22, s22, 2
	v_bfe_u32 v67, v0, 4, 2
	s_and_b32 s22, s22, -16
	v_or_b32_e32 v0, s24, v66
	v_add_u32_e32 v90, s22, v0
	v_mov_b64_e32 v[2:3], s[14:15]
	v_mad_i64_i32 v[2:3], s[14:15], v90, s59, v[2:3]
	v_lshlrev_b32_e32 v0, 4, v67
	v_lshl_add_u64 v[26:27], v[2:3], 0, v[0:1]
	global_load_dwordx4 v[6:9], v[26:27], off nt
	global_load_dwordx4 v[2:5], v[26:27], off offset:64 nt
	s_movk_i32 s7, 0x110
	v_mul_lo_u32 v15, v12, s7
	v_add_u32_e32 v23, 0, v10
	global_load_dwordx4 v[10:13], v[26:27], off offset:128 nt
	s_movk_i32 s6, 0x90
	v_mul_lo_u32 v14, v14, s6
	v_mad_u32_u24 v17, v66, s7, 0
	v_add_u32_e32 v28, 0, v18
	v_mul_lo_u32 v16, v16, s7
	v_add_u32_e32 v143, v17, v0
	v_add_u32_e32 v145, v23, v15
	v_add_u32_e32 v147, v28, v14
	v_add_u32_e32 v149, v23, v16
	global_load_dwordx4 v[14:17], v[26:27], off offset:192 nt
	v_mul_lo_u32 v22, v22, s6
	s_mov_b32 s6, 0x40000
	v_add_u32_e32 v151, v28, v22
	v_add_co_u32_e32 v22, vcc, s6, v54
	v_lshl_add_u64 v[20:21], s[18:19], 0, v[20:21]
	s_nop 0
	v_addc_co_u32_e32 v23, vcc, 0, v55, vcc
	v_add_co_u32_e32 v26, vcc, s6, v56
	v_lshl_add_u64 v[24:25], s[18:19], 0, v[24:25]
	s_nop 0
	v_addc_co_u32_e32 v27, vcc, 0, v57, vcc
	v_lshl_add_u64 v[70:71], v[20:21], 0, v[18:19]
	v_lshl_add_u64 v[72:73], v[24:25], 0, v[18:19]
	global_load_dwordx4 v[18:21], v[22:23], off
	s_nop 0
	global_load_dwordx4 v[22:25], v[70:71], off offset:128
	s_nop 0
	global_load_dwordx4 v[26:29], v[26:27], off
	s_nop 0
	global_load_dwordx4 v[30:33], v[72:73], off offset:128
	v_xor_b32_e32 v0, 16, v209
	v_lshlrev_b32_e32 v92, 3, v67
	s_mov_b32 s14, 0xf149f2ca
	s_mov_b32 s6, 0x80000
	s_waitcnt vmcnt(11)
	ds_write_b128 v145, v[34:37]
	s_waitcnt vmcnt(10)
	ds_write_b128 v147, v[38:41] offset:34816
	s_waitcnt vmcnt(9)
	ds_write_b128 v149, v[42:45]
	s_waitcnt vmcnt(8)
	ds_write_b128 v151, v[46:49] offset:34816
	s_waitcnt lgkmcnt(0)
	s_barrier
	ds_read_b128 v[34:37], v143
	ds_read_b128 v[38:41], v143 offset:64
	ds_read_b128 v[42:45], v143 offset:4352
	ds_read_b128 v[46:49], v143 offset:4416
	s_waitcnt vmcnt(7) lgkmcnt(3)
	v_mfma_f32_16x16x32_bf16 v[34:37], v[34:37], v[6:9], 0
	ds_read_b128 v[50:53], v143 offset:8704
	ds_read_b128 v[58:61], v143 offset:8768
	s_waitcnt lgkmcnt(3)
	v_mfma_f32_16x16x32_bf16 v[42:45], v[42:45], v[6:9], 0
	s_waitcnt vmcnt(6)
	v_mfma_f32_16x16x32_bf16 v[34:37], v[38:41], v[2:5], v[34:37]
	s_waitcnt lgkmcnt(2)
	v_mfma_f32_16x16x32_bf16 v[38:41], v[46:49], v[2:5], v[42:45]
	s_nop 3
	ds_read_b128 v[42:45], v143 offset:128
	ds_read_b128 v[46:49], v143 offset:192
	s_waitcnt vmcnt(5) lgkmcnt(1)
	v_mfma_f32_16x16x32_bf16 v[34:37], v[42:45], v[10:13], v[34:37]
	ds_read_b128 v[42:45], v143 offset:4480
	ds_read_b128 v[62:65], v143 offset:4544
	v_mfma_f32_16x16x32_bf16 v[50:53], v[50:53], v[6:9], 0
	s_waitcnt lgkmcnt(1)
	v_mfma_f32_16x16x32_bf16 v[38:41], v[42:45], v[10:13], v[38:41]
	ds_read_b128 v[42:45], v143 offset:8832
	s_waitcnt vmcnt(4)
	v_mfma_f32_16x16x32_bf16 v[34:37], v[46:49], v[14:17], v[34:37]
	ds_read_b128 v[46:49], v143 offset:8896
	v_mfma_f32_16x16x32_bf16 v[50:53], v[58:61], v[2:5], v[50:53]
	v_and_b32_e32 v58, 64, v209
	s_waitcnt lgkmcnt(2)
	v_mfma_f32_16x16x32_bf16 v[38:41], v[62:65], v[14:17], v[38:41]
	v_add_u32_e32 v62, 64, v58
	ds_read_b128 v[58:61], v143 offset:13056
	v_cmp_lt_i32_e32 vcc, v0, v62
	s_waitcnt lgkmcnt(2)
	v_mfma_f32_16x16x32_bf16 v[42:45], v[42:45], v[10:13], v[50:53]
	v_cndmask_b32_e32 v0, v209, v0, vcc
	v_lshlrev_b32_e32 v91, 2, v0
	s_nop 0
	ds_read_b128 v[50:53], v143 offset:13120
	s_waitcnt lgkmcnt(2)
	v_mfma_f32_16x16x32_bf16 v[42:45], v[46:49], v[14:17], v[42:45]
	ds_read_b128 v[46:49], v143 offset:13184
	v_xor_b32_e32 v0, 32, v209
	v_cmp_lt_i32_e32 vcc, v0, v62
	s_waitcnt lgkmcnt(2)
	v_mfma_f32_16x16x32_bf16 v[58:61], v[58:61], v[6:9], 0
	ds_read_b128 v[62:65], v143 offset:13248
	v_cndmask_b32_e32 v0, v209, v0, vcc
	v_lshlrev_b32_e32 v125, 2, v0
	s_waitcnt lgkmcnt(2)
	v_mfma_f32_16x16x32_bf16 v[50:53], v[50:53], v[2:5], v[58:61]
	v_mul_u32_u24_e32 v0, 0x90, v66
	v_add3_u32 v93, 0, v92, v0
	s_waitcnt lgkmcnt(1)
	v_mfma_f32_16x16x32_bf16 v[46:49], v[46:49], v[10:13], v[50:53]
	v_mul_f32_e64 v58, v40, s34
	v_mul_f32_e64 v59, v41, s34
	v_pk_mul_f32 v[60:61], v[38:39], s[34:35] op_sel_hi:[1,0]
	v_max_f32_e32 v39, v58, v59
	s_waitcnt lgkmcnt(0)
	v_mfma_f32_16x16x32_bf16 v[46:49], v[62:65], v[14:17], v[46:49]
	v_mul_f32_e64 v62, v36, s34
	v_mul_f32_e64 v63, v37, s34
	v_pk_mul_f32 v[64:65], v[34:35], s[34:35] op_sel_hi:[1,0]
	v_pk_mul_f32 v[34:35], v[44:45], s[34:35] op_sel_hi:[1,0]
	v_max_f32_e32 v0, v64, v65
	v_max_f32_e32 v38, v62, v63
	s_nop 1
	v_pk_mul_f32 v[66:67], v[48:49], s[34:35] op_sel_hi:[1,0]
	v_max3_f32 v39, v60, v61, v39
	v_pk_mul_f32 v[36:37], v[42:43], s[34:35] op_sel_hi:[1,0]
	v_pk_mul_f32 v[68:69], v[46:47], s[34:35] op_sel_hi:[1,0]
	v_max3_f32 v0, v0, v38, v39
	v_max_f32_e32 v38, v34, v35
	v_max_f32_e32 v39, v66, v67
	v_max3_f32 v38, v36, v37, v38
	v_max3_f32 v39, v68, v69, v39
	v_max3_f32 v0, v0, v38, v39
	v_mov_b32_e32 v40, v0
	s_nop 1
	v_permlane16_swap_b32_e32 v40, v0
	v_add_co_u32_e32 v50, vcc, s6, v54
	s_waitcnt lgkmcnt(0)
	v_max_f32_e32 v40, v40, v40
	v_max_f32_e32 v0, v0, v40
	v_mov_b32_e32 v74, v0
	s_nop 1
	v_permlane32_swap_b32_e32 v74, v0
	v_addc_co_u32_e32 v51, vcc, 0, v55, vcc
	v_add_co_u32_e32 v38, vcc, s6, v56
	s_waitcnt lgkmcnt(0)
	v_max3_f32 v95, v0, v74, s14
	v_sub_f32_e32 v0, v36, v95
	v_exp_f32_e32 v94, v0
	v_sub_f32_e32 v0, v37, v95
	v_exp_f32_e32 v96, v0
	v_sub_f32_e32 v0, v34, v95
	v_exp_f32_e32 v98, v0
	v_sub_f32_e32 v0, v35, v95
	v_exp_f32_e32 v100, v0
	v_sub_f32_e32 v0, v68, v95
	v_exp_f32_e32 v102, v0
	v_sub_f32_e32 v0, v69, v95
	v_exp_f32_e32 v104, v0
	v_sub_f32_e32 v0, v66, v95
	v_exp_f32_e32 v106, v0
	v_sub_f32_e32 v0, v67, v95
	v_exp_f32_e32 v108, v0
	v_addc_co_u32_e32 v39, vcc, 0, v57, vcc
	v_cvt_pk_bf16_f32 v34, v94, v96
	v_cvt_pk_bf16_f32 v35, v98, v100
	v_cvt_pk_bf16_f32 v36, v102, v104
	v_cvt_pk_bf16_f32 v37, v106, v108
	v_mov_b32_e32 v0, v1
	global_load_dwordx4 v[42:45], v[50:51], off
	s_nop 0
	global_load_dwordx4 v[38:41], v[38:39], off
	s_nop 0
	global_load_dwordx4 v[50:53], v[70:71], off offset:256
	global_load_dwordx4 v[46:49], v[72:73], off offset:256
	s_mov_b32 s6, 0xc0000
	v_add_u32_e32 v0, v93, v0
	v_add_u32_e32 v66, 0x8800, v0
	v_add_u32_e32 v74, 0x9000, v0
	v_add_u32_e32 v97, 0x9800, v0
	ds_read2_b64 v[82:85], v66 offset1:4
	ds_read2_b64 v[86:89], v66 offset0:8 offset1:12
	ds_read2_b64 v[66:69], v74 offset0:32 offset1:36
	ds_read2_b64 v[74:77], v74 offset0:40 offset1:44
	ds_read2_b64 v[78:81], v97 offset0:64 offset1:68
	ds_read2_b64 v[126:129], v97 offset0:72 offset1:76
	v_add_u32_e32 v97, 0xa000, v0
	ds_read2_b64 v[130:133], v97 offset0:96 offset1:100
	ds_read2_b64 v[134:137], v97 offset0:104 offset1:108
	v_add_u32_e32 v97, 0xa800, v0
	ds_read2_b64 v[138:141], v97 offset0:128 offset1:132
	ds_read2_b64 v[152:155], v97 offset0:136 offset1:140
	v_add_u32_e32 v97, 0xb000, v0
	ds_read2_b64 v[158:161], v97 offset0:160 offset1:164
	ds_read2_b64 v[162:165], v97 offset0:168 offset1:172
	v_add_u32_e32 v97, 0xb800, v0
	v_add_u32_e32 v0, 0xc000, v0
	ds_read2_b64 v[166:169], v97 offset0:192 offset1:196
	ds_read2_b64 v[170:173], v97 offset0:200 offset1:204
	ds_read2_b64 v[174:177], v0 offset0:224 offset1:228
	ds_read2_b64 v[178:181], v0 offset0:232 offset1:236
	s_waitcnt vmcnt(7)
	ds_write_b128 v145, v[18:21] offset:17408
	s_waitcnt vmcnt(6)
	ds_write_b128 v147, v[22:25] offset:53248
	s_waitcnt vmcnt(5)
	ds_write_b128 v149, v[26:29] offset:17408
	s_waitcnt vmcnt(4)
	ds_write_b128 v151, v[30:33] offset:53248
	s_waitcnt lgkmcnt(0)
	s_barrier
	ds_read_b128 v[18:21], v143 offset:17408
	ds_read_b128 v[22:25], v143 offset:17472
	ds_read_b128 v[26:29], v143 offset:17536
	s_waitcnt lgkmcnt(2)
	v_mfma_f32_16x16x32_bf16 v[18:21], v[18:21], v[6:9], 0
	ds_read_b128 v[30:33], v143 offset:21824
	v_sub_f32_e32 v97, 0xf149f2ca, v95
	v_sub_f32_e32 v0, v64, v95
	s_waitcnt lgkmcnt(2)
	v_mfma_f32_16x16x32_bf16 v[18:21], v[22:25], v[2:5], v[18:21]
	ds_read_b128 v[22:25], v143 offset:17600
	v_exp_f32_e32 v0, v0
	s_waitcnt lgkmcnt(2)
	v_mfma_f32_16x16x32_bf16 v[18:21], v[26:29], v[10:13], v[18:21]
	ds_read_b128 v[26:29], v143 offset:21760
	s_waitcnt lgkmcnt(1)
	v_mfma_f32_16x16x32_bf16 v[182:185], v[22:25], v[14:17], v[18:21]
	s_nop 4
	ds_read_b128 v[18:21], v143 offset:21888
	s_waitcnt lgkmcnt(1)
	v_mfma_f32_16x16x32_bf16 v[22:25], v[26:29], v[6:9], 0
	v_sub_f32_e32 v26, v65, v95
	v_exp_f32_e32 v156, v26
	ds_read_b128 v[26:29], v143 offset:21952
	v_mfma_f32_16x16x32_bf16 v[22:25], v[30:33], v[2:5], v[22:25]
	v_sub_f32_e32 v30, v62, v95
	v_exp_f32_e32 v110, v30
	ds_read_b128 v[30:33], v143 offset:26112
	s_waitcnt lgkmcnt(2)
	v_mfma_f32_16x16x32_bf16 v[18:21], v[18:21], v[10:13], v[22:25]
	v_cvt_pk_bf16_f32 v216, v0, v156
	s_nop 1
	v_sub_f32_e32 v22, v63, v95
	v_exp_f32_e32 v112, v22
	ds_read_b128 v[22:25], v143 offset:26176
	s_waitcnt lgkmcnt(2)
	v_mfma_f32_16x16x32_bf16 v[190:193], v[26:29], v[14:17], v[18:21]
	v_cvt_pk_bf16_f32 v217, v110, v112
	s_nop 1
	v_sub_f32_e32 v18, v60, v95
	v_exp_f32_e32 v114, v18
	ds_read_b128 v[18:21], v143 offset:26240
	s_waitcnt lgkmcnt(2)
	v_mfma_f32_16x16x32_bf16 v[26:29], v[30:33], v[6:9], 0
	v_sub_f32_e32 v30, v61, v95
	v_exp_f32_e32 v116, v30
	ds_read_b128 v[30:33], v143 offset:26304
	s_waitcnt lgkmcnt(2)
	v_mfma_f32_16x16x32_bf16 v[22:25], v[22:25], v[2:5], v[26:29]
	v_cvt_pk_bf16_f32 v218, v114, v116
	s_nop 1
	v_sub_f32_e32 v26, v58, v95
	v_exp_f32_e32 v118, v26
	ds_read_b128 v[26:29], v143 offset:30464
	s_waitcnt lgkmcnt(2)
	v_mfma_f32_16x16x32_bf16 v[18:21], v[18:21], v[10:13], v[22:25]
	v_sub_f32_e32 v58, v59, v95
	v_exp_f32_e32 v59, v97
	v_exp_f32_e32 v122, v58
	ds_read_b128 v[22:25], v143 offset:30528
	s_waitcnt lgkmcnt(2)
	v_mfma_f32_16x16x32_bf16 v[194:197], v[30:33], v[14:17], v[18:21]
	ds_read_b128 v[30:33], v143 offset:30656
	v_cmp_neq_f32_e32 vcc, 1.0, v59
	s_cmp_lg_u64 vcc, 0
	ds_read_b128 v[18:21], v143 offset:30592
	s_waitcnt lgkmcnt(3)
	v_mfma_f32_16x16x32_bf16 v[26:29], v[26:29], v[6:9], 0
	v_mul_f32_e32 v120, 0, v59
	s_cselect_b64 vcc, -1, 0
	v_cndmask_b32_e32 v198, 0, v120, vcc
	s_waitcnt lgkmcnt(2)
	v_mfma_f32_16x16x32_bf16 v[22:25], v[22:25], v[2:5], v[26:29]
	v_mov_b32_e32 v199, v198
	v_mov_b32_e32 v200, v198
	v_mov_b32_e32 v201, v198
	s_waitcnt lgkmcnt(0)
	v_mfma_f32_16x16x32_bf16 v[18:21], v[18:21], v[10:13], v[22:25]
	v_cvt_pk_bf16_f32 v219, v118, v122
	v_mfma_f32_16x16x32_bf16 v[220:223], v[30:33], v[14:17], v[18:21]
	s_nop 0
	v_mfma_f32_16x16x32_bf16 v[18:21], v[66:69], v[216:219], v[198:201]
	v_mfma_f32_16x16x32_bf16 v[58:61], v[74:77], v[34:37], v[18:21]
	v_mfma_f32_16x16x32_bf16 v[18:21], v[78:81], v[216:219], v[198:201]
	v_mfma_f32_16x16x32_bf16 v[62:65], v[126:129], v[34:37], v[18:21]
	v_mul_f32_e64 v126, v192, s34
	v_mul_f32_e64 v127, v193, s34
	s_nop 0
	v_pk_mul_f32 v[128:129], v[222:223], s[34:35] op_sel_hi:[1,0]
	s_nop 2
	v_add_co_u32_e32 v18, vcc, s6, v54
	v_mfma_f32_16x16x32_bf16 v[26:29], v[130:133], v[216:219], v[198:201]
	s_nop 0
	v_addc_co_u32_e32 v19, vcc, 0, v55, vcc
	v_add_co_u32_e32 v20, vcc, s6, v56
	v_mfma_f32_16x16x32_bf16 v[66:69], v[134:137], v[34:37], v[26:29]
	s_nop 0
	v_addc_co_u32_e32 v21, vcc, 0, v57, vcc
	global_load_dwordx4 v[22:25], v[18:19], off
	s_nop 0
	global_load_dwordx4 v[18:21], v[20:21], off
	s_nop 0
	global_load_dwordx4 v[30:33], v[70:71], off offset:384
	global_load_dwordx4 v[26:29], v[72:73], off offset:384
	v_mfma_f32_16x16x32_bf16 v[54:57], v[138:141], v[216:219], v[198:201]
	v_mul_f32_e64 v136, v190, s34
	v_mul_f32_e64 v137, v191, s34
	v_pk_mul_f32 v[138:139], v[184:185], s[34:35] op_sel_hi:[1,0]
	v_pk_mul_f32 v[140:141], v[182:183], s[34:35] op_sel_hi:[1,0]
	v_mfma_f32_16x16x32_bf16 v[70:73], v[152:155], v[34:37], v[54:57]
	v_mul_f32_e64 v130, v196, s34
	v_mul_f32_e64 v131, v197, s34
	v_max_f32_e32 v78, v140, v141
	v_max_f32_e32 v79, v138, v139
	v_mfma_f32_16x16x32_bf16 v[54:57], v[158:161], v[216:219], v[198:201]
	v_mul_f32_e64 v134, v194, s34
	v_mul_f32_e64 v135, v195, s34
	v_pk_mul_f32 v[132:133], v[220:221], s[34:35] op_sel_hi:[1,0]
	v_mfma_f32_16x16x32_bf16 v[74:77], v[162:165], v[34:37], v[54:57]
	v_mfma_f32_16x16x32_bf16 v[82:85], v[82:85], v[216:219], v[198:201]
	s_nop 2
	v_max_f32_e32 v54, v126, v127
	v_max3_f32 v80, v136, v137, v54
	v_max3_f32 v97, v78, v79, v80
	v_mfma_f32_16x16x32_bf16 v[54:57], v[166:169], v[216:219], v[198:201]
	v_max_f32_e32 v78, v130, v131
	v_max3_f32 v99, v134, v135, v78
	v_mfma_f32_16x16x32_bf16 v[78:81], v[170:173], v[34:37], v[54:57]
	s_nop 4
	v_max_f32_e32 v54, v128, v129
	v_max3_f32 v54, v132, v133, v54
	v_max3_f32 v97, v97, v99, v54
	v_mov_b32_e32 v99, v97
	s_nop 1
	v_permlane16_swap_b32_e32 v99, v97
	v_mfma_f32_16x16x32_bf16 v[54:57], v[174:177], v[216:219], v[198:201]
	s_waitcnt lgkmcnt(0)
	v_max_f32_e32 v99, v99, v99
	v_max_f32_e32 v97, v97, v99
	v_mov_b32_e32 v99, v97
	s_nop 1
	v_permlane32_swap_b32_e32 v99, v97
	v_mfma_f32_16x16x32_bf16 v[54:57], v[178:181], v[34:37], v[54:57]
	s_waitcnt lgkmcnt(0)
	v_max3_f32 v142, v95, v97, v99
	v_sub_f32_e32 v95, v95, v142
	v_exp_f32_e32 v124, v95
	v_mfma_f32_16x16x32_bf16 v[34:37], v[86:89], v[34:37], v[82:85]
	v_cmp_neq_f32_e32 vcc, 1.0, v124
	s_cbranch_vccz .LBB0_405
	s_nop 5
	v_pk_mul_f32 v[36:37], v[36:37], v[124:125] op_sel_hi:[1,0]
	v_pk_mul_f32 v[34:35], v[34:35], v[124:125] op_sel_hi:[1,0]
	v_pk_mul_f32 v[60:61], v[60:61], v[124:125] op_sel_hi:[1,0]
	v_pk_mul_f32 v[58:59], v[58:59], v[124:125] op_sel_hi:[1,0]
	v_pk_mul_f32 v[64:65], v[64:65], v[124:125] op_sel_hi:[1,0]
	v_pk_mul_f32 v[62:63], v[62:63], v[124:125] op_sel_hi:[1,0]
	v_pk_mul_f32 v[68:69], v[68:69], v[124:125] op_sel_hi:[1,0]
	v_pk_mul_f32 v[66:67], v[66:67], v[124:125] op_sel_hi:[1,0]
	v_pk_mul_f32 v[72:73], v[72:73], v[124:125] op_sel_hi:[1,0]
	v_pk_mul_f32 v[70:71], v[70:71], v[124:125] op_sel_hi:[1,0]
	v_pk_mul_f32 v[76:77], v[76:77], v[124:125] op_sel_hi:[1,0]
	v_pk_mul_f32 v[74:75], v[74:75], v[124:125] op_sel_hi:[1,0]
	v_pk_mul_f32 v[80:81], v[80:81], v[124:125] op_sel_hi:[1,0]
	v_pk_mul_f32 v[78:79], v[78:79], v[124:125] op_sel_hi:[1,0]
	v_pk_mul_f32 v[56:57], v[56:57], v[124:125] op_sel_hi:[1,0]
	v_pk_mul_f32 v[54:55], v[54:55], v[124:125] op_sel_hi:[1,0]
.LBB0_405:
	s_nop 0
	v_sub_f32_e32 v82, v140, v142
	v_exp_f32_e32 v111, v82
	v_sub_f32_e32 v82, v141, v142
	v_exp_f32_e32 v113, v82
	v_sub_f32_e32 v82, v138, v142
	v_exp_f32_e32 v115, v82
	v_sub_f32_e32 v82, v139, v142
	v_exp_f32_e32 v117, v82
	v_sub_f32_e32 v82, v136, v142
	v_exp_f32_e32 v119, v82
	v_sub_f32_e32 v82, v137, v142
	v_exp_f32_e32 v123, v82
	v_sub_f32_e32 v82, v126, v142
	v_exp_f32_e32 v95, v82
	v_sub_f32_e32 v82, v134, v142
	v_exp_f32_e32 v99, v82
	v_sub_f32_e32 v82, v135, v142
	v_exp_f32_e32 v101, v82
	v_sub_f32_e32 v82, v130, v142
	v_exp_f32_e32 v103, v82
	v_sub_f32_e32 v82, v131, v142
	v_exp_f32_e32 v105, v82
	v_sub_f32_e32 v82, v132, v142
	v_exp_f32_e32 v107, v82
	v_sub_f32_e32 v82, v133, v142
	v_exp_f32_e32 v109, v82
	v_sub_f32_e32 v82, v128, v142
	v_exp_f32_e32 v121, v82
	v_sub_f32_e32 v82, v129, v142
	v_exp_f32_e32 v157, v82
	v_cvt_pk_bf16_f32 v82, v99, v101
	v_cvt_pk_bf16_f32 v83, v103, v105
	v_cvt_pk_bf16_f32 v84, v107, v109
	v_cvt_pk_bf16_f32 v85, v121, v157
	v_mov_b32_e32 v86, v1
	v_cvt_pk_bf16_f32 v87, v115, v117
	v_add_u32_e32 v136, v93, v86
	v_add_u32_e32 v138, 0xd000, v136
	ds_read2_b64 v[128:131], v138 offset1:4
	v_sub_f32_e32 v86, v127, v142
	v_exp_f32_e32 v97, v86
	ds_read2_b64 v[132:135], v138 offset0:8 offset1:12
	v_cvt_pk_bf16_f32 v86, v111, v113
	v_cvt_pk_bf16_f32 v88, v119, v123
	v_cvt_pk_bf16_f32 v89, v95, v97
	v_add_u32_e32 v137, 0xd800, v136
	s_waitcnt lgkmcnt(1)
	v_mfma_f32_16x16x32_bf16 v[34:37], v[128:131], v[86:89], v[34:37]
	ds_read2_b64 v[126:129], v137 offset0:32 offset1:36
	s_waitcnt lgkmcnt(1)
	v_mfma_f32_16x16x32_bf16 v[34:37], v[132:135], v[82:85], v[34:37]
	ds_read2_b64 v[130:133], v137 offset0:40 offset1:44
	v_add_u32_e32 v134, 0xe000, v136
	s_waitcnt lgkmcnt(1)
	v_mfma_f32_16x16x32_bf16 v[58:61], v[126:129], v[86:89], v[58:61]
	ds_read2_b64 v[126:129], v134 offset0:64 offset1:68
	s_waitcnt lgkmcnt(1)
	v_mfma_f32_16x16x32_bf16 v[58:61], v[130:133], v[82:85], v[58:61]
	ds_read2_b64 v[130:133], v134 offset0:72 offset1:76
	v_add_u32_e32 v134, 0xe800, v136
	s_waitcnt lgkmcnt(1)
	v_mfma_f32_16x16x32_bf16 v[62:65], v[126:129], v[86:89], v[62:65]
	ds_read2_b64 v[126:129], v134 offset0:96 offset1:100
	s_waitcnt lgkmcnt(1)
	v_mfma_f32_16x16x32_bf16 v[62:65], v[130:133], v[82:85], v[62:65]
	ds_read2_b64 v[130:133], v134 offset0:104 offset1:108
	v_add_u32_e32 v134, 0xf000, v136
	s_waitcnt lgkmcnt(1)
	v_mfma_f32_16x16x32_bf16 v[66:69], v[126:129], v[86:89], v[66:69]
	ds_read2_b64 v[126:129], v134 offset0:128 offset1:132
	s_waitcnt lgkmcnt(1)
	v_mfma_f32_16x16x32_bf16 v[66:69], v[130:133], v[82:85], v[66:69]
	ds_read2_b64 v[130:133], v134 offset0:136 offset1:140
	v_add_u32_e32 v134, 0xf800, v136
	s_waitcnt lgkmcnt(1)
	v_mfma_f32_16x16x32_bf16 v[70:73], v[126:129], v[86:89], v[70:73]
	ds_read2_b64 v[126:129], v134 offset0:160 offset1:164
	s_waitcnt lgkmcnt(1)
	v_mfma_f32_16x16x32_bf16 v[70:73], v[130:133], v[82:85], v[70:73]
	ds_read2_b64 v[130:133], v134 offset0:168 offset1:172
	v_add_u32_e32 v134, 0x3000, v138
	s_waitcnt lgkmcnt(1)
	v_mfma_f32_16x16x32_bf16 v[74:77], v[126:129], v[86:89], v[74:77]
	ds_read2_b64 v[126:129], v134 offset0:192 offset1:196
	ds_read2_b64 v[134:137], v134 offset0:200 offset1:204
	s_waitcnt lgkmcnt(2)
	v_mfma_f32_16x16x32_bf16 v[74:77], v[130:133], v[82:85], v[74:77]
	v_add_u32_e32 v130, 0x3800, v138
	ds_read2_b64 v[138:141], v130 offset0:224 offset1:228
	ds_read2_b64 v[152:155], v130 offset0:232 offset1:236
	s_waitcnt vmcnt(7)
	ds_write_b128 v145, v[42:45]
	s_waitcnt vmcnt(5)
	ds_write_b128 v147, v[50:53] offset:34816
	ds_write_b128 v149, v[38:41]
	s_waitcnt vmcnt(4)
	ds_write_b128 v151, v[46:49] offset:34816
	s_waitcnt lgkmcnt(0)
	s_barrier
	ds_read_b128 v[38:41], v143
	ds_read_b128 v[42:45], v143 offset:64
	s_waitcnt lgkmcnt(1)
	v_mfma_f32_16x16x32_bf16 v[38:41], v[38:41], v[6:9], 0
	ds_read_b128 v[46:49], v143 offset:4416
	ds_read_b128 v[130:133], v143 offset:13120
	s_waitcnt lgkmcnt(2)
	v_mfma_f32_16x16x32_bf16 v[38:41], v[42:45], v[2:5], v[38:41]
	ds_read_b128 v[42:45], v143 offset:128
	s_waitcnt lgkmcnt(0)
	v_mfma_f32_16x16x32_bf16 v[38:41], v[42:45], v[10:13], v[38:41]
	ds_read_b128 v[42:45], v143 offset:192
	v_mfma_f32_16x16x32_bf16 v[78:81], v[126:129], v[86:89], v[78:81]
	ds_read_b128 v[126:129], v143 offset:8768
	s_waitcnt lgkmcnt(1)
	v_mfma_f32_16x16x32_bf16 v[38:41], v[42:45], v[14:17], v[38:41]
	ds_read_b128 v[42:45], v143 offset:4352
	s_waitcnt lgkmcnt(0)
	v_mfma_f32_16x16x32_bf16 v[42:45], v[42:45], v[6:9], 0
	s_nop 4
	v_mul_f32_e64 v52, v40, s34
	v_mul_f32_e64 v53, v41, s34
	v_mfma_f32_16x16x32_bf16 v[42:45], v[46:49], v[2:5], v[42:45]
	ds_read_b128 v[46:49], v143 offset:4480
	s_waitcnt lgkmcnt(0)
	v_mfma_f32_16x16x32_bf16 v[42:45], v[46:49], v[10:13], v[42:45]
	ds_read_b128 v[46:49], v143 offset:4544
	s_waitcnt lgkmcnt(0)
	v_mfma_f32_16x16x32_bf16 v[44:47], v[46:49], v[14:17], v[42:45]
	ds_read_b128 v[48:51], v143 offset:8704
	s_nop 6
	v_pk_mul_f32 v[42:43], v[46:47], s[34:35] op_sel_hi:[1,0]
	s_waitcnt lgkmcnt(0)
	v_mfma_f32_16x16x32_bf16 v[48:51], v[48:51], v[6:9], 0
	v_max_f32_e32 v40, v42, v43
	v_mfma_f32_16x16x32_bf16 v[48:51], v[126:129], v[2:5], v[48:51]
	ds_read_b128 v[126:129], v143 offset:8832
	s_waitcnt lgkmcnt(0)
	v_mfma_f32_16x16x32_bf16 v[48:51], v[126:129], v[10:13], v[48:51]
	ds_read_b128 v[126:129], v143 offset:8896
	s_waitcnt lgkmcnt(0)
	v_mfma_f32_16x16x32_bf16 v[48:51], v[126:129], v[14:17], v[48:51]
	ds_read_b128 v[126:129], v143 offset:13056
	s_nop 6
	v_pk_mul_f32 v[46:47], v[50:51], s[34:35] op_sel_hi:[1,0]
	s_waitcnt lgkmcnt(0)
	v_mfma_f32_16x16x32_bf16 v[126:129], v[126:129], v[6:9], 0
	v_mul_f32_e64 v50, v48, s34
	v_mul_f32_e64 v51, v49, s34
	v_mfma_f32_16x16x32_bf16 v[126:129], v[130:133], v[2:5], v[126:129]
	ds_read_b128 v[130:133], v143 offset:13184
	s_waitcnt lgkmcnt(0)
	v_mfma_f32_16x16x32_bf16 v[126:129], v[130:133], v[10:13], v[126:129]
	ds_read_b128 v[130:133], v143 offset:13248
	s_waitcnt lgkmcnt(0)
	v_mfma_f32_16x16x32_bf16 v[158:161], v[130:133], v[14:17], v[126:129]
	s_nop 4
	v_mul_f32_e64 v128, v38, s34
	v_mul_f32_e64 v129, v39, s34
	v_pk_mul_f32 v[132:133], v[44:45], s[34:35] op_sel_hi:[1,0]
	v_max_f32_e32 v38, v128, v129
	v_pk_mul_f32 v[44:45], v[160:161], s[34:35] op_sel_hi:[1,0]
	v_max_f32_e32 v39, v52, v53
	v_max3_f32 v40, v132, v133, v40
	v_pk_mul_f32 v[48:49], v[158:159], s[34:35] op_sel_hi:[1,0]
	v_max3_f32 v38, v38, v39, v40
	v_max_f32_e32 v39, v46, v47
	v_max_f32_e32 v40, v44, v45
	v_max3_f32 v39, v50, v51, v39
	v_max3_f32 v40, v48, v49, v40
	v_max3_f32 v126, v38, v39, v40
	ds_bpermute_b32 v127, v91, v126
	v_mfma_f32_16x16x32_bf16 v[38:41], v[134:137], v[82:85], v[78:81]
	s_waitcnt lgkmcnt(0)
	s_nop 1
	v_max_f32_e32 v78, v127, v127
	v_max_f32_e32 v78, v126, v78
	v_mov_b32_e32 v79, v78
	s_nop 1
	v_permlane32_swap_b32_e32 v79, v78
	v_mfma_f32_16x16x32_bf16 v[54:57], v[138:141], v[86:89], v[54:57]
	s_waitcnt lgkmcnt(0)
	v_max3_f32 v131, v142, v78, v79
	v_sub_f32_e32 v78, v142, v131
	v_exp_f32_e32 v126, v78
	v_mfma_f32_16x16x32_bf16 v[78:81], v[152:155], v[82:85], v[54:57]
	v_cmp_neq_f32_e32 vcc, 1.0, v126
	s_cbranch_vccz .LBB0_407
	v_pk_mul_f32 v[36:37], v[36:37], v[126:127] op_sel_hi:[1,0]
	v_pk_mul_f32 v[34:35], v[34:35], v[126:127] op_sel_hi:[1,0]
	v_pk_mul_f32 v[60:61], v[60:61], v[126:127] op_sel_hi:[1,0]
	v_pk_mul_f32 v[58:59], v[58:59], v[126:127] op_sel_hi:[1,0]
	v_pk_mul_f32 v[64:65], v[64:65], v[126:127] op_sel_hi:[1,0]
	v_pk_mul_f32 v[62:63], v[62:63], v[126:127] op_sel_hi:[1,0]
	v_pk_mul_f32 v[68:69], v[68:69], v[126:127] op_sel_hi:[1,0]
	v_pk_mul_f32 v[66:67], v[66:67], v[126:127] op_sel_hi:[1,0]
	v_pk_mul_f32 v[72:73], v[72:73], v[126:127] op_sel_hi:[1,0]
	v_pk_mul_f32 v[70:71], v[70:71], v[126:127] op_sel_hi:[1,0]
	v_pk_mul_f32 v[76:77], v[76:77], v[126:127] op_sel_hi:[1,0]
	v_pk_mul_f32 v[74:75], v[74:75], v[126:127] op_sel_hi:[1,0]
	v_pk_mul_f32 v[40:41], v[40:41], v[126:127] op_sel_hi:[1,0]
	v_pk_mul_f32 v[38:39], v[38:39], v[126:127] op_sel_hi:[1,0]
	v_pk_mul_f32 v[80:81], v[80:81], v[126:127] op_sel_hi:[1,0]
	v_pk_mul_f32 v[78:79], v[78:79], v[126:127] op_sel_hi:[1,0]
.LBB0_407:
	v_sub_f32_e32 v42, v42, v131
	v_exp_f32_e32 v136, v42
	v_sub_f32_e32 v42, v50, v131
	v_exp_f32_e32 v138, v42
	v_sub_f32_e32 v42, v51, v131
	v_exp_f32_e32 v140, v42
	v_sub_f32_e32 v42, v46, v131
	v_exp_f32_e32 v142, v42
	v_sub_f32_e32 v42, v47, v131
	v_exp_f32_e32 v144, v42
	v_sub_f32_e32 v42, v48, v131
	v_exp_f32_e32 v146, v42
	v_sub_f32_e32 v42, v49, v131
	v_exp_f32_e32 v148, v42
	v_sub_f32_e32 v42, v44, v131
	v_exp_f32_e32 v150, v42
	v_sub_f32_e32 v42, v45, v131
	v_exp_f32_e32 v152, v42
	v_sub_f32_e32 v54, v128, v131
	v_cvt_pk_bf16_f32 v82, v138, v140
	v_cvt_pk_bf16_f32 v83, v142, v144
	v_cvt_pk_bf16_f32 v84, v146, v148
	v_cvt_pk_bf16_f32 v85, v150, v152
	v_mov_b32_e32 v42, v1
	v_exp_f32_e32 v127, v54
	v_sub_f32_e32 v54, v129, v131
	v_sub_f32_e32 v52, v52, v131
	v_add_u32_e32 v129, v93, v42
	v_add_u32_e32 v42, 0x9000, v129
	ds_read2_b64 v[44:47], v42 offset0:32 offset1:36
	v_exp_f32_e32 v128, v52
	v_sub_f32_e32 v52, v53, v131
	v_exp_f32_e32 v130, v52
	v_sub_f32_e32 v52, v132, v131
	v_exp_f32_e32 v132, v52
	v_sub_f32_e32 v52, v133, v131
	v_sub_f32_e32 v43, v43, v131
	v_exp_f32_e32 v158, v54
	v_exp_f32_e32 v134, v52
	v_exp_f32_e32 v154, v43
	ds_read2_b64 v[48:51], v42 offset0:40 offset1:44
	v_cvt_pk_bf16_f32 v86, v127, v158
	v_cvt_pk_bf16_f32 v87, v128, v130
	v_cvt_pk_bf16_f32 v88, v132, v134
	v_cvt_pk_bf16_f32 v89, v136, v154
	v_add_u32_e32 v56, 0x9800, v129
	ds_read2_b64 v[52:55], v56 offset0:64 offset1:68
	s_waitcnt lgkmcnt(2)
	v_mfma_f32_16x16x32_bf16 v[42:45], v[44:47], v[86:89], v[58:61]
	v_add_u32_e32 v133, 0xa000, v129
	s_waitcnt lgkmcnt(1)
	v_mfma_f32_16x16x32_bf16 v[58:61], v[48:51], v[82:85], v[42:45]
	s_waitcnt lgkmcnt(0)
	v_mfma_f32_16x16x32_bf16 v[46:49], v[52:55], v[86:89], v[62:65]
	s_nop 2
	ds_read2_b64 v[42:45], v56 offset0:72 offset1:76
	ds_read2_b64 v[50:53], v133 offset0:96 offset1:100
	s_waitcnt lgkmcnt(1)
	v_mfma_f32_16x16x32_bf16 v[54:57], v[42:45], v[82:85], v[46:49]
	ds_read2_b64 v[42:45], v133 offset0:104 offset1:108
	v_add_u32_e32 v133, 0xa800, v129
	ds_read2_b64 v[62:65], v133 offset0:128 offset1:132
	s_waitcnt lgkmcnt(2)
	v_mfma_f32_16x16x32_bf16 v[46:49], v[50:53], v[86:89], v[66:69]
	s_waitcnt lgkmcnt(1)
	v_mfma_f32_16x16x32_bf16 v[50:53], v[42:45], v[82:85], v[46:49]
	ds_read2_b64 v[42:45], v133 offset0:136 offset1:140
	v_add_u32_e32 v66, 0xb000, v129
	s_waitcnt lgkmcnt(1)
	v_mfma_f32_16x16x32_bf16 v[46:49], v[62:65], v[86:89], v[70:73]
	ds_read2_b64 v[62:65], v66 offset0:160 offset1:164
	s_waitcnt lgkmcnt(1)
	v_mfma_f32_16x16x32_bf16 v[46:49], v[42:45], v[82:85], v[46:49]
	ds_read2_b64 v[42:45], v66 offset0:168 offset1:172
	v_add_u32_e32 v70, 0xb800, v129
	ds_read2_b64 v[66:69], v70 offset0:192 offset1:196
	ds_read2_b64 v[70:73], v70 offset0:200 offset1:204
	s_waitcnt lgkmcnt(3)
	v_mfma_f32_16x16x32_bf16 v[62:65], v[62:65], v[86:89], v[74:77]
	s_nop 2
	v_add_u32_e32 v74, 0x8800, v129
	v_add_u32_e32 v129, 0xc000, v129
	s_waitcnt lgkmcnt(2)
	v_mfma_f32_16x16x32_bf16 v[42:45], v[42:45], v[82:85], v[62:65]
	s_nop 2
	ds_read2_b64 v[62:65], v74 offset1:4
	ds_read2_b64 v[74:77], v74 offset0:8 offset1:12
	s_waitcnt lgkmcnt(3)
	v_mfma_f32_16x16x32_bf16 v[38:41], v[66:69], v[86:89], v[38:41]
	ds_read2_b64 v[66:69], v129 offset0:224 offset1:228
	ds_read2_b64 v[160:163], v129 offset0:232 offset1:236
	s_waitcnt vmcnt(3)
	ds_write_b128 v145, v[22:25] offset:17408
	s_waitcnt vmcnt(1)
	ds_write_b128 v147, v[30:33] offset:53248
	ds_write_b128 v149, v[18:21] offset:17408
	s_waitcnt vmcnt(0)
	ds_write_b128 v151, v[26:29] offset:53248
	s_waitcnt lgkmcnt(0)
	s_barrier
	ds_read_b128 v[18:21], v143 offset:17408
	ds_read_b128 v[22:25], v143 offset:17472
	v_mfma_f32_16x16x32_bf16 v[28:31], v[66:69], v[86:89], v[78:81]
	ds_read_b128 v[66:69], v143 offset:17536
	s_waitcnt lgkmcnt(2)
	v_mfma_f32_16x16x32_bf16 v[18:21], v[18:21], v[6:9], 0
	ds_read_b128 v[78:81], v143 offset:26240
	s_waitcnt lgkmcnt(2)
	v_mfma_f32_16x16x32_bf16 v[18:21], v[22:25], v[2:5], v[18:21]
	ds_read_b128 v[22:25], v143 offset:17600
	s_waitcnt lgkmcnt(2)
	v_mfma_f32_16x16x32_bf16 v[18:21], v[66:69], v[10:13], v[18:21]
	ds_read_b128 v[66:69], v143 offset:21760
	s_waitcnt lgkmcnt(1)
	v_mfma_f32_16x16x32_bf16 v[20:23], v[22:25], v[14:17], v[18:21]
	ds_read_b128 v[24:27], v143 offset:21824
	v_mfma_f32_16x16x32_bf16 v[38:41], v[70:73], v[82:85], v[38:41]
	ds_read_b128 v[70:73], v143 offset:21888
	s_nop 4
	v_pk_mul_f32 v[18:19], v[22:23], s[34:35] op_sel_hi:[1,0]
	s_waitcnt lgkmcnt(2)
	v_mfma_f32_16x16x32_bf16 v[66:69], v[66:69], v[6:9], 0
	s_waitcnt lgkmcnt(1)
	v_mfma_f32_16x16x32_bf16 v[24:27], v[24:27], v[2:5], v[66:69]
	s_nop 5
	ds_read_b128 v[66:69], v143 offset:21952
	s_waitcnt lgkmcnt(1)
	v_mfma_f32_16x16x32_bf16 v[24:27], v[70:73], v[10:13], v[24:27]
	ds_read_b128 v[70:73], v143 offset:26112
	s_waitcnt lgkmcnt(1)
	v_mfma_f32_16x16x32_bf16 v[24:27], v[66:69], v[14:17], v[24:27]
	ds_read_b128 v[66:69], v143 offset:26176
	s_waitcnt lgkmcnt(1)
	v_mfma_f32_16x16x32_bf16 v[70:73], v[70:73], v[6:9], 0
	s_waitcnt lgkmcnt(0)
	v_mfma_f32_16x16x32_bf16 v[66:69], v[66:69], v[2:5], v[70:73]
	s_nop 5
	ds_read_b128 v[70:73], v143 offset:26304
	v_mfma_f32_16x16x32_bf16 v[66:69], v[78:81], v[10:13], v[66:69]
	ds_read_b128 v[78:81], v143 offset:30464
	s_waitcnt lgkmcnt(1)
	v_mfma_f32_16x16x32_bf16 v[66:69], v[70:73], v[14:17], v[66:69]
	ds_read_b128 v[70:73], v143 offset:30528
	s_nop 6
	v_pk_mul_f32 v[22:23], v[66:67], s[34:35] op_sel_hi:[1,0]
	s_waitcnt lgkmcnt(1)
	v_mfma_f32_16x16x32_bf16 v[6:9], v[78:81], v[6:9], 0
	ds_read_b128 v[78:81], v143 offset:30592
	s_waitcnt lgkmcnt(1)
	v_mfma_f32_16x16x32_bf16 v[2:5], v[70:73], v[2:5], v[6:9]
	s_nop 4
	ds_read_b128 v[6:9], v143 offset:30656
	s_waitcnt lgkmcnt(1)
	v_mfma_f32_16x16x32_bf16 v[2:5], v[78:81], v[10:13], v[2:5]
	s_waitcnt lgkmcnt(0)
	v_mfma_f32_16x16x32_bf16 v[2:5], v[6:9], v[14:17], v[2:5]
	v_mul_f32_e64 v8, v20, s34
	v_mul_f32_e64 v9, v21, s34
	v_pk_mul_f32 v[20:21], v[26:27], s[34:35] op_sel_hi:[1,0]
	v_pk_mul_f32 v[6:7], v[24:25], s[34:35] op_sel_hi:[1,0]
	s_nop 3
	v_pk_mul_f32 v[16:17], v[4:5], s[34:35] op_sel_hi:[1,0]
	v_max_f32_e32 v4, v20, v21
	v_pk_mul_f32 v[24:25], v[68:69], s[34:35] op_sel_hi:[1,0]
	v_pk_mul_f32 v[26:27], v[2:3], s[34:35] op_sel_hi:[1,0]
	v_max_f32_e32 v2, v8, v9
	v_max_f32_e32 v3, v18, v19
	v_max3_f32 v4, v6, v7, v4
	v_max3_f32 v2, v2, v3, v4
	v_max_f32_e32 v3, v24, v25
	v_max_f32_e32 v4, v16, v17
	v_max3_f32 v3, v22, v23, v3
	v_max3_f32 v4, v26, v27, v4
	v_max3_f32 v2, v2, v3, v4
	v_mov_b32_e32 v3, v2
	s_nop 1
	v_permlane16_swap_b32_e32 v3, v2
	v_mfma_f32_16x16x32_bf16 v[10:13], v[160:163], v[82:85], v[28:31]
	s_waitcnt lgkmcnt(0)
	v_max_f32_e32 v3, v3, v3
	v_max_f32_e32 v14, v2, v3
	v_mov_b32_e32 v15, v14
	s_nop 1
	v_permlane32_swap_b32_e32 v15, v14
	v_mfma_f32_16x16x32_bf16 v[2:5], v[62:65], v[86:89], v[34:37]
	s_waitcnt lgkmcnt(0)
	v_max3_f32 v15, v131, v14, v15
	v_sub_f32_e32 v14, v131, v15
	v_exp_f32_e32 v14, v14
	v_mfma_f32_16x16x32_bf16 v[2:5], v[74:77], v[82:85], v[2:5]
	v_cmp_neq_f32_e32 vcc, 1.0, v14
	s_cbranch_vccz .LBB0_402
	s_nop 5
	v_pk_mul_f32 v[4:5], v[4:5], v[14:15] op_sel_hi:[1,0]
	v_pk_mul_f32 v[2:3], v[2:3], v[14:15] op_sel_hi:[1,0]
	v_pk_mul_f32 v[60:61], v[60:61], v[14:15] op_sel_hi:[1,0]
	v_pk_mul_f32 v[58:59], v[58:59], v[14:15] op_sel_hi:[1,0]
	v_pk_mul_f32 v[56:57], v[56:57], v[14:15] op_sel_hi:[1,0]
	v_pk_mul_f32 v[54:55], v[54:55], v[14:15] op_sel_hi:[1,0]
	v_pk_mul_f32 v[52:53], v[52:53], v[14:15] op_sel_hi:[1,0]
	v_pk_mul_f32 v[50:51], v[50:51], v[14:15] op_sel_hi:[1,0]
	v_pk_mul_f32 v[48:49], v[48:49], v[14:15] op_sel_hi:[1,0]
	v_pk_mul_f32 v[46:47], v[46:47], v[14:15] op_sel_hi:[1,0]
	v_pk_mul_f32 v[44:45], v[44:45], v[14:15] op_sel_hi:[1,0]
	v_pk_mul_f32 v[42:43], v[42:43], v[14:15] op_sel_hi:[1,0]
	v_pk_mul_f32 v[40:41], v[40:41], v[14:15] op_sel_hi:[1,0]
	v_pk_mul_f32 v[38:39], v[38:39], v[14:15] op_sel_hi:[1,0]
	v_pk_mul_f32 v[12:13], v[12:13], v[14:15] op_sel_hi:[1,0]
	v_pk_mul_f32 v[10:11], v[10:11], v[14:15] op_sel_hi:[1,0]
	s_branch .LBB0_402

	.amdhsa_kernel _Z4mega6Params
		.amdhsa_group_segment_fixed_size 0
		.amdhsa_private_segment_fixed_size 0
		.amdhsa_kernarg_size 368
		.amdhsa_user_sgpr_count 2
		.amdhsa_user_sgpr_dispatch_ptr 0
		.amdhsa_user_sgpr_queue_ptr 0
		.amdhsa_user_sgpr_kernarg_segment_ptr 1
		.amdhsa_user_sgpr_dispatch_id 0
		.amdhsa_user_sgpr_kernarg_preload_length 0
		.amdhsa_user_sgpr_kernarg_preload_offset 0
		.amdhsa_user_sgpr_private_segment_size 0
		.amdhsa_uses_dynamic_stack 0
		.amdhsa_enable_private_segment 0
		.amdhsa_system_sgpr_workgroup_id_x 1
		.amdhsa_system_sgpr_workgroup_id_y 0
		.amdhsa_system_sgpr_workgroup_id_z 0
		.amdhsa_system_sgpr_workgroup_info 0
		.amdhsa_system_vgpr_workitem_id 2
		.amdhsa_next_free_vgpr 256
		.amdhsa_next_free_sgpr 100
		.amdhsa_accum_offset 256
		.amdhsa_reserve_vcc 1
		.amdhsa_float_round_mode_32 0
		.amdhsa_float_round_mode_16_64 0
		.amdhsa_float_denorm_mode_32 3
		.amdhsa_float_denorm_mode_16_64 3
		.amdhsa_dx10_clamp 1
		.amdhsa_ieee_mode 1
		.amdhsa_fp16_overflow 0
		.amdhsa_tg_split 0
		.amdhsa_exception_fp_ieee_invalid_op 0
		.amdhsa_exception_fp_denorm_src 0
		.amdhsa_exception_fp_ieee_div_zero 0
		.amdhsa_exception_fp_ieee_overflow 0
		.amdhsa_exception_fp_ieee_underflow 0
		.amdhsa_exception_fp_ieee_inexact 0
		.amdhsa_exception_int_div_zero 0
	.end_amdhsa_kernel

amdhsa.kernels:
  - .agpr_count:     0
    .args:
      - .offset:         0
        .size:           112
        .value_kind:     by_value
      - .offset:         112
        .size:           4
        .value_kind:     hidden_block_count_x
      - .offset:         116
        .size:           4
        .value_kind:     hidden_block_count_y
      - .offset:         120
        .size:           4
        .value_kind:     hidden_block_count_z
      - .offset:         124
        .size:           2
        .value_kind:     hidden_group_size_x
      - .offset:         126
        .size:           2
        .value_kind:     hidden_group_size_y
      - .offset:         128
        .size:           2
        .value_kind:     hidden_group_size_z
      - .offset:         130
        .size:           2
        .value_kind:     hidden_remainder_x
      - .offset:         132
        .size:           2
        .value_kind:     hidden_remainder_y
      - .offset:         134
        .size:           2
        .value_kind:     hidden_remainder_z
      - .offset:         152
        .size:           8
        .value_kind:     hidden_global_offset_x
      - .offset:         160
        .size:           8
        .value_kind:     hidden_global_offset_y
      - .offset:         168
        .size:           8
        .value_kind:     hidden_global_offset_z
      - .offset:         176
        .size:           2
        .value_kind:     hidden_grid_dims
      - .offset:         200
        .size:           8
        .value_kind:     hidden_multigrid_sync_arg
      - .offset:         232
        .size:           4
        .value_kind:     hidden_dynamic_lds_size
    .group_segment_fixed_size: 0
    .kernarg_segment_align: 8
    .kernarg_segment_size: 368
    .language:       OpenCL C
    .language_version:
      - 2
      - 0
    .max_flat_workgroup_size: 512
    .name:           _Z4mega6Params
    .private_segment_fixed_size: 0
    .sgpr_count:     106
    .sgpr_spill_count: 176
    .symbol:         _Z4mega6Params.kd
    .uniform_work_group_size: 1
    .uses_dynamic_stack: false
    .vgpr_count:     256
    .vgpr_spill_count: 0
    .wavefront_size: 64
